# in-proj and FF1 epilogue stores marked nt (outputs far larger than L2; keeps weights and A tiles resident)
# speedup vs baseline: 1.0024x; 1.0024x over previous
;   template <int CAT>
;   __device__ __forceinline__ void slot(const f32x4 (&acc)[2][2][4][2], int bj, int r00, int p0, bool sunit, int fq, int c0, bf16_t* bdst, int bstride, float* fdst,
;                                        float scale) const {
;     ...
;         } else if (CAT == 4) {
;           if (fq == 0) *(f32x4*)((float*)(ws + W_WI) + (size_t)r * 4) = (f32x4){v[0] * 0.5f, v[1] * 0.5f, v[2] * 0.5f, v[3] * 0.5f};
;   __device__ __forceinline__ void operator()(const f32x4 (&acc)[2][2][4][2], const Unit& u, int wr, int wc, int fr, int fq) const {
;     ...
;       slot_info(u.pn * 8 + bj * 4 + wc, grp, off);
;       if (grp == G_PAD) continue;
;       const int c0 = off + 8 * fq;
;       const bool dorope = (grp == G_Q || grp == G_K || grp == G_QI) && ((off & 63) == 0);
;       const float scale = grp == G_Q ? 0.125f * 1.44269504089f : (grp == G_QI ? 0.125f : 1.0f);
;       bf16_t* bdst;
;       int bstride;
;       float* fdst = nullptr;
;       switch (grp) {
;         case G_Q: bdst = (bf16_t*)(ws + W_Q); bstride = 512; break;
;         case G_QI: bdst = (bf16_t*)(ws + W_QI); bstride = 256; break;
;         case G_K: bdst = (bf16_t*)(ws + (sunit ? W_KS : W_KP)); bstride = 128; fdst = out + (sunit ? O_SK : O_PK); break;
;         case G_V: bdst = (bf16_t*)(ws + (sunit ? W_VS : W_VP)); bstride = 128; fdst = out + (sunit ? O_SV : O_PV); break;
;         case G_U: bdst = (bf16_t*)(ws + W_U); bstride = 512; break;
;         case G_VG: bdst = (bf16_t*)(ws + W_VG); bstride = 512; break;
;         case G_GA: bdst = (bf16_t*)(ws + W_GA); bstride = 1024; break;
;         case G_GB: bdst = (bf16_t*)(ws + W_GB); bstride = 1024; break;
;         default: bdst = nullptr; bstride = 0; break;
;       }
;       if (dorope) slot<0>(acc, bj, r00, p0, sunit, fq, c0, bdst, bstride, fdst, scale);
;       else if (grp == G_GA || grp == G_GB) slot<2>(acc, bj, r00, p0, sunit, fq, c0, bdst, bstride, fdst, scale);
;       else if (grp == G_KI) slot<3>(acc, bj, r00, p0, sunit, fq, c0, bdst, bstride, fdst, scale);
;       else if (grp == G_WI) slot<4>(acc, bj, r00, p0, sunit, fq, c0, bdst, bstride, fdst, scale);
.LBB0_2442:
	s_cmp_eq_u32 s59, 3
	s_cselect_b64 vcc, -1, 0
	v_mov_b32_e32 v130, 0x3e000000
	s_cmp_lg_u32 s59, 0
	v_cndmask_b32_e32 v130, 1.0, v130, vcc
	s_cselect_b64 vcc, -1, 0
	v_mov_b32_e32 v131, 0x3e38aa3b
	v_cndmask_b32_e32 v194, v131, v130, vcc
	v_add_u32_e32 v234, s56, v236
	s_mov_b64 s[2:3], -1
	s_and_b64 vcc, exec, s[0:1]
	s_cbranch_vccz .LBB0_2492
	s_and_b32 s0, s59, 14
	s_cmp_lg_u32 s0, 8
	s_mov_b64 s[0:1], -1
	s_cbranch_scc0 .LBB0_2489
	s_mov_b64 s[56:57], -1
	s_mov_b64 s[0:1], 0
	s_cmp_lt_i32 s59, 5
	s_mov_b64 s[2:3], 0
	s_cbranch_scc1 .LBB0_2484
	s_cmp_eq_u32 s59, 5
	s_mov_b64 s[2:3], -1
	s_cbranch_scc0 .LBB0_2449
	s_and_saveexec_b64 s[2:3], s[8:9]
	s_cbranch_execz .LBB0_2448
	v_pk_mul_f32 v[132:133], v[128:129], 0.5 op_sel_hi:[1,0]
	v_pk_mul_f32 v[130:131], v[126:127], 0.5 op_sel_hi:[1,0]
	v_lshl_add_u64 v[134:135], s[40:41], 0, v[218:219]
	global_store_dwordx4 v[134:135], v[130:133], off nt
	v_lshl_add_u64 v[134:135], s[40:41], 0, v[226:227]
	s_nop 0
	v_pk_mul_f32 v[132:133], v[120:121], 0.5 op_sel_hi:[1,0]
	v_pk_mul_f32 v[130:131], v[118:119], 0.5 op_sel_hi:[1,0]
	global_store_dwordx4 v[134:135], v[130:133], off nt
	v_lshl_add_u64 v[134:135], s[40:41], 0, v[250:251]
	s_nop 0
	v_pk_mul_f32 v[132:133], v[112:113], 0.5 op_sel_hi:[1,0]
	v_pk_mul_f32 v[130:131], v[110:111], 0.5 op_sel_hi:[1,0]
	global_store_dwordx4 v[134:135], v[130:133], off nt
	v_lshl_add_u64 v[134:135], s[40:41], 0, v[136:137]
	s_nop 0
	v_pk_mul_f32 v[132:133], v[104:105], 0.5 op_sel_hi:[1,0]
	v_pk_mul_f32 v[130:131], v[102:103], 0.5 op_sel_hi:[1,0]
	global_store_dwordx4 v[134:135], v[130:133], off nt
	v_lshl_add_u64 v[134:135], s[40:41], 0, v[142:143]
	s_nop 0
	v_pk_mul_f32 v[132:133], v[96:97], 0.5 op_sel_hi:[1,0]
	v_pk_mul_f32 v[130:131], v[94:95], 0.5 op_sel_hi:[1,0]
	global_store_dwordx4 v[134:135], v[130:133], off nt
	v_lshl_add_u64 v[134:135], s[40:41], 0, v[232:233]
	s_nop 0
	v_pk_mul_f32 v[132:133], v[88:89], 0.5 op_sel_hi:[1,0]
	v_pk_mul_f32 v[130:131], v[86:87], 0.5 op_sel_hi:[1,0]
	global_store_dwordx4 v[134:135], v[130:133], off nt
	v_lshl_add_u64 v[134:135], s[40:41], 0, v[230:231]
	s_nop 0
	v_pk_mul_f32 v[132:133], v[80:81], 0.5 op_sel_hi:[1,0]
	v_pk_mul_f32 v[130:131], v[78:79], 0.5 op_sel_hi:[1,0]
	global_store_dwordx4 v[134:135], v[130:133], off nt
	v_lshl_add_u64 v[134:135], s[40:41], 0, v[220:221]
	s_nop 0
	v_pk_mul_f32 v[132:133], v[72:73], 0.5 op_sel_hi:[1,0]
	v_pk_mul_f32 v[130:131], v[70:71], 0.5 op_sel_hi:[1,0]
	global_store_dwordx4 v[134:135], v[130:133], off nt

;   template <int CAT>
;   __device__ __forceinline__ void slot(const f32x4 (&acc)[2][2][4][2], int bj, int r00, int p0, bool sunit, int fq, int c0, bf16_t* bdst, int bstride, float* fdst,
;                                        float scale) const {
;     ...
;           u32x4 w;
; #pragma unroll
;           for (int e = 0; e < 4; ++e) w[e] = cvt_pk_bf16(v[2 * e] * scale, v[2 * e + 1] * scale);
;           size_t brow = (size_t)r;
;           if (fdst && sunit) brow = (size_t)(l * 16 + (sr >> 5)) * 2080 + 2048 + (sr & 31);
;           *(u32x4*)(bdst + brow * bstride + c0) = w;
;           if (fdst) {
;             float* fp = fdst + ((size_t)(sunit ? l * MS + sr : l * MP + r)) * 128 + c0;
;             *(f32x4*)fp = (f32x4){v[0], v[1], v[2], v[3]};
;             *(f32x4*)(fp + 4) = (f32x4){v[4], v[5], v[6], v[7]};
;           }
.LBB0_2453:
	v_ashrrev_i32_e32 v235, 31, v234
	v_mul_lo_u32 v140, v139, s52
	v_mul_lo_u32 v141, v138, s53
	v_mad_u64_u32 v[138:139], s[2:3], v138, s52, 0
	v_lshl_add_u64 v[136:137], v[234:235], 1, s[4:5]
	v_add3_u32 v139, v139, v141, v140
	v_cndmask_b32_e64 v140, 0, 1, s[56:57]
	v_lshl_add_u64 v[134:135], v[234:235], 2, s[54:55]
	v_lshl_add_u64 v[138:139], v[138:139], 1, v[136:137]
	v_cmp_ne_u32_e64 s[2:3], 1, v140
	s_andn2_b64 vcc, exec, s[56:57]
	global_store_dwordx4 v[138:139], v[130:133], off nt
	s_cbranch_vccnz .LBB0_2455
	v_readlane_b32 s56, v255, 22
	s_lshl_b32 s56, s56, s47
	v_readlane_b32 s57, v255, 23
	v_add_u32_e32 v130, s56, v247
	v_ashrrev_i32_e32 v131, 31, v130
	v_lshlrev_b64 v[130:131], 9, v[130:131]
	v_lshl_add_u64 v[130:131], v[134:135], 0, v[130:131]
	global_store_dwordx4 v[130:131], v[126:129], off nt
	global_store_dwordx4 v[130:131], v[122:125], off offset:16 nt

;   template <int CAT>
;   __device__ __forceinline__ void slot(const f32x4 (&acc)[2][2][4][2], int bj, int r00, int p0, bool sunit, int fq, int c0, bf16_t* bdst, int bstride, float* fdst,
;                                        float scale) const {
;     ...
;           u32x4 w;
; #pragma unroll
;           for (int e = 0; e < 4; ++e) w[e] = cvt_pk_bf16(v[2 * e] * scale, v[2 * e + 1] * scale);
;           size_t brow = (size_t)r;
;           if (fdst && sunit) brow = (size_t)(l * 16 + (sr >> 5)) * 2080 + 2048 + (sr & 31);
;           *(u32x4*)(bdst + brow * bstride + c0) = w;
;           if (fdst) {
;             float* fp = fdst + ((size_t)(sunit ? l * MS + sr : l * MP + r)) * 128 + c0;
;             *(f32x4*)fp = (f32x4){v[0], v[1], v[2], v[3]};
;             *(f32x4*)(fp + 4) = (f32x4){v[4], v[5], v[6], v[7]};
;           }
.LBB0_2457:
	v_mul_lo_u32 v140, v139, s52
	v_mul_lo_u32 v141, v138, s53
	v_mad_u64_u32 v[138:139], s[56:57], v138, s52, 0
	v_add3_u32 v139, v139, v141, v140
	v_lshl_add_u64 v[138:139], v[138:139], 1, v[136:137]
	s_and_b64 vcc, exec, s[2:3]
	global_store_dwordx4 v[138:139], v[130:133], off nt
	s_cbranch_vccnz .LBB0_2459
	v_readlane_b32 s56, v255, 22
	s_lshl_b32 s56, s56, s47
	v_readlane_b32 s57, v255, 23
	v_add_u32_e32 v130, s56, v187
	v_ashrrev_i32_e32 v131, 31, v130
	v_lshlrev_b64 v[130:131], 9, v[130:131]
	v_lshl_add_u64 v[130:131], v[134:135], 0, v[130:131]
	global_store_dwordx4 v[130:131], v[118:121], off nt
	global_store_dwordx4 v[130:131], v[114:117], off offset:16 nt

;   template <int CAT>
;   __device__ __forceinline__ void slot(const f32x4 (&acc)[2][2][4][2], int bj, int r00, int p0, bool sunit, int fq, int c0, bf16_t* bdst, int bstride, float* fdst,
;                                        float scale) const {
;     ...
;           u32x4 w;
; #pragma unroll
;           for (int e = 0; e < 4; ++e) w[e] = cvt_pk_bf16(v[2 * e] * scale, v[2 * e + 1] * scale);
;           size_t brow = (size_t)r;
;           if (fdst && sunit) brow = (size_t)(l * 16 + (sr >> 5)) * 2080 + 2048 + (sr & 31);
;           *(u32x4*)(bdst + brow * bstride + c0) = w;
;           if (fdst) {
;             float* fp = fdst + ((size_t)(sunit ? l * MS + sr : l * MP + r)) * 128 + c0;
;             *(f32x4*)fp = (f32x4){v[0], v[1], v[2], v[3]};
;             *(f32x4*)(fp + 4) = (f32x4){v[4], v[5], v[6], v[7]};
;           }
.LBB0_2461:
	v_mul_lo_u32 v140, v139, s52
	v_mul_lo_u32 v141, v138, s53
	v_mad_u64_u32 v[138:139], s[56:57], v138, s52, 0
	v_add3_u32 v139, v139, v141, v140
	v_lshl_add_u64 v[138:139], v[138:139], 1, v[136:137]
	s_and_b64 vcc, exec, s[2:3]
	global_store_dwordx4 v[138:139], v[130:133], off nt
	s_cbranch_vccnz .LBB0_2463
	v_readlane_b32 s56, v255, 22
	s_lshl_b32 s56, s56, s47
	v_readlane_b32 s57, v255, 23
	v_add_u32_e32 v130, s56, v197
	v_ashrrev_i32_e32 v131, 31, v130
	v_lshlrev_b64 v[130:131], 9, v[130:131]
	v_lshl_add_u64 v[130:131], v[134:135], 0, v[130:131]
	global_store_dwordx4 v[130:131], v[110:113], off nt
	global_store_dwordx4 v[130:131], v[106:109], off offset:16 nt

;   template <int CAT>
;   __device__ __forceinline__ void slot(const f32x4 (&acc)[2][2][4][2], int bj, int r00, int p0, bool sunit, int fq, int c0, bf16_t* bdst, int bstride, float* fdst,
;                                        float scale) const {
;     ...
;           u32x4 w;
; #pragma unroll
;           for (int e = 0; e < 4; ++e) w[e] = cvt_pk_bf16(v[2 * e] * scale, v[2 * e + 1] * scale);
;           size_t brow = (size_t)r;
;           if (fdst && sunit) brow = (size_t)(l * 16 + (sr >> 5)) * 2080 + 2048 + (sr & 31);
;           *(u32x4*)(bdst + brow * bstride + c0) = w;
;           if (fdst) {
;             float* fp = fdst + ((size_t)(sunit ? l * MS + sr : l * MP + r)) * 128 + c0;
;             *(f32x4*)fp = (f32x4){v[0], v[1], v[2], v[3]};
;             *(f32x4*)(fp + 4) = (f32x4){v[4], v[5], v[6], v[7]};
;           }
.LBB0_2465:
	v_mul_lo_u32 v140, v139, s52
	v_mul_lo_u32 v141, v138, s53
	v_mad_u64_u32 v[138:139], s[56:57], v138, s52, 0
	v_add3_u32 v139, v139, v141, v140
	v_lshl_add_u64 v[138:139], v[138:139], 1, v[136:137]
	s_and_b64 vcc, exec, s[2:3]
	global_store_dwordx4 v[138:139], v[130:133], off nt
	s_cbranch_vccnz .LBB0_2467
	v_readlane_b32 s56, v255, 22
	s_lshl_b32 s56, s56, s47
	v_readlane_b32 s57, v255, 23
	v_add_u32_e32 v130, s56, v245
	v_ashrrev_i32_e32 v131, 31, v130
	v_lshlrev_b64 v[130:131], 9, v[130:131]
	v_lshl_add_u64 v[130:131], v[134:135], 0, v[130:131]
	global_store_dwordx4 v[130:131], v[102:105], off nt
	global_store_dwordx4 v[130:131], v[98:101], off offset:16 nt

;   template <int CAT>
;   __device__ __forceinline__ void slot(const f32x4 (&acc)[2][2][4][2], int bj, int r00, int p0, bool sunit, int fq, int c0, bf16_t* bdst, int bstride, float* fdst,
;                                        float scale) const {
;     ...
;           u32x4 w;
; #pragma unroll
;           for (int e = 0; e < 4; ++e) w[e] = cvt_pk_bf16(v[2 * e] * scale, v[2 * e + 1] * scale);
;           size_t brow = (size_t)r;
;           if (fdst && sunit) brow = (size_t)(l * 16 + (sr >> 5)) * 2080 + 2048 + (sr & 31);
;           *(u32x4*)(bdst + brow * bstride + c0) = w;
;           if (fdst) {
;             float* fp = fdst + ((size_t)(sunit ? l * MS + sr : l * MP + r)) * 128 + c0;
;             *(f32x4*)fp = (f32x4){v[0], v[1], v[2], v[3]};
;             *(f32x4*)(fp + 4) = (f32x4){v[4], v[5], v[6], v[7]};
;           }
.LBB0_2469:
	v_mul_lo_u32 v140, v139, s52
	v_mul_lo_u32 v141, v138, s53
	v_mad_u64_u32 v[138:139], s[56:57], v138, s52, 0
	v_add3_u32 v139, v139, v141, v140
	v_lshl_add_u64 v[138:139], v[138:139], 1, v[136:137]
	s_and_b64 vcc, exec, s[2:3]
	global_store_dwordx4 v[138:139], v[130:133], off nt
	s_cbranch_vccnz .LBB0_2471
	v_readlane_b32 s56, v255, 22
	s_lshl_b32 s56, s56, s47
	v_readlane_b32 s57, v255, 23
	v_add_u32_e32 v130, s56, v185
	v_ashrrev_i32_e32 v131, 31, v130
	v_lshlrev_b64 v[130:131], 9, v[130:131]
	v_lshl_add_u64 v[130:131], v[134:135], 0, v[130:131]
	global_store_dwordx4 v[130:131], v[94:97], off nt
	global_store_dwordx4 v[130:131], v[90:93], off offset:16 nt

;   template <int CAT>
;   __device__ __forceinline__ void slot(const f32x4 (&acc)[2][2][4][2], int bj, int r00, int p0, bool sunit, int fq, int c0, bf16_t* bdst, int bstride, float* fdst,
;                                        float scale) const {
;     ...
;           u32x4 w;
; #pragma unroll
;           for (int e = 0; e < 4; ++e) w[e] = cvt_pk_bf16(v[2 * e] * scale, v[2 * e + 1] * scale);
;           size_t brow = (size_t)r;
;           if (fdst && sunit) brow = (size_t)(l * 16 + (sr >> 5)) * 2080 + 2048 + (sr & 31);
;           *(u32x4*)(bdst + brow * bstride + c0) = w;
;           if (fdst) {
;             float* fp = fdst + ((size_t)(sunit ? l * MS + sr : l * MP + r)) * 128 + c0;
;             *(f32x4*)fp = (f32x4){v[0], v[1], v[2], v[3]};
;             *(f32x4*)(fp + 4) = (f32x4){v[4], v[5], v[6], v[7]};
;           }
.LBB0_2473:
	v_mul_lo_u32 v140, v139, s52
	v_mul_lo_u32 v141, v138, s53
	v_mad_u64_u32 v[138:139], s[56:57], v138, s52, 0
	v_add3_u32 v139, v139, v141, v140
	v_lshl_add_u64 v[138:139], v[138:139], 1, v[136:137]
	s_and_b64 vcc, exec, s[2:3]
	global_store_dwordx4 v[138:139], v[130:133], off nt
	s_cbranch_vccnz .LBB0_2475
	v_readlane_b32 s56, v255, 22
	s_lshl_b32 s56, s56, s47
	v_readlane_b32 s57, v255, 23
	v_add_u32_e32 v130, s56, v188
	v_ashrrev_i32_e32 v131, 31, v130
	v_lshlrev_b64 v[130:131], 9, v[130:131]
	v_lshl_add_u64 v[130:131], v[134:135], 0, v[130:131]
	global_store_dwordx4 v[130:131], v[86:89], off nt
	global_store_dwordx4 v[130:131], v[82:85], off offset:16 nt

;   template <int CAT>
;   __device__ __forceinline__ void slot(const f32x4 (&acc)[2][2][4][2], int bj, int r00, int p0, bool sunit, int fq, int c0, bf16_t* bdst, int bstride, float* fdst,
;                                        float scale) const {
;     ...
;           u32x4 w;
; #pragma unroll
;           for (int e = 0; e < 4; ++e) w[e] = cvt_pk_bf16(v[2 * e] * scale, v[2 * e + 1] * scale);
;           size_t brow = (size_t)r;
;           if (fdst && sunit) brow = (size_t)(l * 16 + (sr >> 5)) * 2080 + 2048 + (sr & 31);
;           *(u32x4*)(bdst + brow * bstride + c0) = w;
;           if (fdst) {
;             float* fp = fdst + ((size_t)(sunit ? l * MS + sr : l * MP + r)) * 128 + c0;
;             *(f32x4*)fp = (f32x4){v[0], v[1], v[2], v[3]};
;             *(f32x4*)(fp + 4) = (f32x4){v[4], v[5], v[6], v[7]};
;           }
.LBB0_2477:
	v_mul_lo_u32 v140, v139, s52
	v_mul_lo_u32 v141, v138, s53
	v_mad_u64_u32 v[138:139], s[56:57], v138, s52, 0
	v_add3_u32 v139, v139, v141, v140
	v_lshl_add_u64 v[138:139], v[138:139], 1, v[136:137]
	s_and_b64 vcc, exec, s[2:3]
	global_store_dwordx4 v[138:139], v[130:133], off nt
	s_cbranch_vccnz .LBB0_2479
	v_readlane_b32 s56, v255, 22
	s_lshl_b32 s56, s56, s47
	v_readlane_b32 s57, v255, 23
	v_add_u32_e32 v130, s56, v186
	v_ashrrev_i32_e32 v131, 31, v130
	v_lshlrev_b64 v[130:131], 9, v[130:131]
	v_lshl_add_u64 v[130:131], v[134:135], 0, v[130:131]
	global_store_dwordx4 v[130:131], v[78:81], off nt
	global_store_dwordx4 v[130:131], v[74:77], off offset:16 nt

;   template <int CAT>
;   __device__ __forceinline__ void slot(const f32x4 (&acc)[2][2][4][2], int bj, int r00, int p0, bool sunit, int fq, int c0, bf16_t* bdst, int bstride, float* fdst,
;                                        float scale) const {
;     ...
;           u32x4 w;
; #pragma unroll
;           for (int e = 0; e < 4; ++e) w[e] = cvt_pk_bf16(v[2 * e] * scale, v[2 * e + 1] * scale);
;           size_t brow = (size_t)r;
;           if (fdst && sunit) brow = (size_t)(l * 16 + (sr >> 5)) * 2080 + 2048 + (sr & 31);
;           *(u32x4*)(bdst + brow * bstride + c0) = w;
;           if (fdst) {
;             float* fp = fdst + ((size_t)(sunit ? l * MS + sr : l * MP + r)) * 128 + c0;
;             *(f32x4*)fp = (f32x4){v[0], v[1], v[2], v[3]};
;             *(f32x4*)(fp + 4) = (f32x4){v[4], v[5], v[6], v[7]};
;           }
.LBB0_2481:
	v_mul_lo_u32 v140, v139, s52
	v_mul_lo_u32 v141, v138, s53
	v_mad_u64_u32 v[138:139], s[0:1], v138, s52, 0
	v_add3_u32 v139, v139, v141, v140
	v_lshl_add_u64 v[136:137], v[138:139], 1, v[136:137]
	s_and_b64 vcc, exec, s[2:3]
	global_store_dwordx4 v[136:137], v[130:133], off nt
	s_cbranch_vccnz .LBB0_2483
	v_readlane_b32 s0, v255, 22
	s_lshl_b32 s0, s0, s47
	v_readlane_b32 s1, v255, 23
	v_add_u32_e32 v130, s0, v184
	v_ashrrev_i32_e32 v131, 31, v130
	v_lshlrev_b64 v[130:131], 9, v[130:131]
	v_lshl_add_u64 v[130:131], v[134:135], 0, v[130:131]
	global_store_dwordx4 v[130:131], v[70:73], off nt
	global_store_dwordx4 v[130:131], v[66:69], off offset:16 nt

;   template <int CAT>
;   __device__ __forceinline__ void slot(const f32x4 (&acc)[2][2][4][2], int bj, int r00, int p0, bool sunit, int fq, int c0, bf16_t* bdst, int bstride, float* fdst,
;                                        float scale) const {
;     ...
;         if (CAT == 3) {
;           float* d = (float*)(ws + W_KIRAW) + (size_t)r * 64 + c0;
;           *(f32x4*)d = (f32x4){v[0], v[1], v[2], v[3]};
;           *(f32x4*)(d + 4) = (f32x4){v[4], v[5], v[6], v[7]};
.LBB0_2486:
	s_and_b64 vcc, exec, s[0:1]
	s_cbranch_vccz .LBB0_2488
	v_ashrrev_i32_e32 v235, 31, v234
	v_lshl_add_u64 v[130:131], s[42:43], 0, v[216:217]
	v_lshlrev_b64 v[132:133], 2, v[234:235]
	v_lshl_add_u64 v[130:131], v[130:131], 0, v[132:133]
	global_store_dwordx4 v[130:131], v[126:129], off nt
	global_store_dwordx4 v[130:131], v[122:125], off offset:16 nt
	v_lshl_add_u64 v[130:131], s[42:43], 0, v[214:215]
	v_lshl_add_u64 v[130:131], v[130:131], 0, v[132:133]
	global_store_dwordx4 v[130:131], v[118:121], off nt
	global_store_dwordx4 v[130:131], v[114:117], off offset:16 nt
	v_lshl_add_u64 v[130:131], s[42:43], 0, v[212:213]
	v_lshl_add_u64 v[130:131], v[130:131], 0, v[132:133]
	global_store_dwordx4 v[130:131], v[110:113], off nt
	global_store_dwordx4 v[130:131], v[106:109], off offset:16 nt
	v_lshl_add_u64 v[130:131], s[42:43], 0, v[210:211]
	v_lshl_add_u64 v[130:131], v[130:131], 0, v[132:133]
	global_store_dwordx4 v[130:131], v[102:105], off nt
	global_store_dwordx4 v[130:131], v[98:101], off offset:16 nt
	v_lshl_add_u64 v[130:131], s[42:43], 0, v[208:209]
	v_lshl_add_u64 v[130:131], v[130:131], 0, v[132:133]
	global_store_dwordx4 v[130:131], v[94:97], off nt
	global_store_dwordx4 v[130:131], v[90:93], off offset:16 nt
	v_lshl_add_u64 v[130:131], s[42:43], 0, v[206:207]
	v_lshl_add_u64 v[130:131], v[130:131], 0, v[132:133]
	global_store_dwordx4 v[130:131], v[86:89], off nt
	global_store_dwordx4 v[130:131], v[82:85], off offset:16 nt
	v_lshl_add_u64 v[130:131], s[42:43], 0, v[204:205]
	v_lshl_add_u64 v[130:131], v[130:131], 0, v[132:133]
	global_store_dwordx4 v[130:131], v[78:81], off nt
	global_store_dwordx4 v[130:131], v[74:77], off offset:16 nt
	v_lshl_add_u64 v[130:131], s[42:43], 0, v[202:203]
	v_lshl_add_u64 v[130:131], v[130:131], 0, v[132:133]
	global_store_dwordx4 v[130:131], v[70:73], off nt
	global_store_dwordx4 v[130:131], v[66:69], off offset:16 nt

;   template <int CAT>
;   __device__ __forceinline__ void slot(const f32x4 (&acc)[2][2][4][2], int bj, int r00, int p0, bool sunit, int fq, int c0, bf16_t* bdst, int bstride, float* fdst,
;                                        float scale) const {
;     ...
;         if (CAT == 2) {
;           unsigned q[8];
; #pragma unroll
;           for (int e = 0; e < 8; ++e) q[e] = (unsigned)(__frcp_rn(1.f + __expf(-v[e])) * 255.f + 0.5f);
;           u32x2 w8;
;           w8[0] = q[0] | (q[1] << 8) | (q[2] << 16) | (q[3] << 24);
;           w8[1] = q[4] | (q[5] << 8) | (q[6] << 16) | (q[7] << 24);
;           *(u32x2*)((unsigned char*)bdst + (size_t)r * 1024 + c0) = w8;
;           continue;
.LBB0_2489:
	s_and_b64 vcc, exec, s[0:1]
	s_cbranch_vccz .LBB0_2491
	v_mul_f32_e32 v132, 0xbfb8aa3b, v126
	v_mul_f32_e32 v133, 0xbfb8aa3b, v122
	v_exp_f32_e32 v134, v132
	v_exp_f32_e32 v135, v133
	v_mul_f32_e32 v132, 0xbfb8aa3b, v127
	v_mul_f32_e32 v133, 0xbfb8aa3b, v123
	v_exp_f32_e32 v136, v132
	v_pk_add_f32 v[134:135], v[134:135], 1.0 op_sel_hi:[1,0]
	v_exp_f32_e32 v137, v133
	v_rcp_f32_e32 v141, v135
	s_mov_b32 s2, 0x437f0000
	v_mul_f32_e32 v132, 0xbfb8aa3b, v128
	v_mul_f32_e32 v133, 0xbfb8aa3b, v124
	v_fma_f32 v142, -v135, v141, 1.0
	v_fma_f32 v135, v142, v141, v141
	v_rcp_f32_e32 v141, v134
	v_exp_f32_e32 v138, v132
	v_exp_f32_e32 v139, v133
	v_mul_f32_e32 v132, 0xbfb8aa3b, v129
	v_fma_f32 v142, -v134, v141, 1.0
	v_fma_f32 v134, v142, v141, v141
	v_pk_fma_f32 v[134:135], v[134:135], s[2:3], 0.5 op_sel_hi:[1,0,0]
	v_mul_f32_e32 v133, 0xbfb8aa3b, v125
	v_cvt_u32_f32_e32 v140, v135
	v_cvt_u32_f32_e32 v141, v134
	v_pk_add_f32 v[134:135], v[136:137], 1.0 op_sel_hi:[1,0]
	v_exp_f32_e32 v132, v132
	v_rcp_f32_e32 v137, v135
	v_exp_f32_e32 v133, v133
	v_ashrrev_i32_e32 v235, 31, v234
	v_lshl_add_u64 v[130:131], s[4:5], 0, v[234:235]
	v_fma_f32 v142, -v135, v137, 1.0
	v_fma_f32 v135, v142, v137, v137
	v_rcp_f32_e32 v137, v134
	v_pk_add_f32 v[132:133], v[132:133], 1.0 op_sel_hi:[1,0]
	v_fma_f32 v142, -v134, v137, 1.0
	v_fma_f32 v134, v142, v137, v137
	v_pk_fma_f32 v[134:135], v[134:135], s[2:3], 0.5 op_sel_hi:[1,0,0]
	s_nop 0
	v_cvt_u32_f32_e32 v136, v134
	v_cvt_u32_f32_e32 v137, v135
	v_pk_add_f32 v[134:135], v[138:139], 1.0 op_sel_hi:[1,0]
	v_lshlrev_b32_e32 v136, 8, v136
	v_rcp_f32_e32 v139, v135
	v_lshlrev_b32_e32 v137, 8, v137
	v_or_b32_e32 v137, v137, v140
	v_or_b32_e32 v136, v136, v141
	v_fma_f32 v142, -v135, v139, 1.0
	v_fma_f32 v135, v142, v139, v139
	v_rcp_f32_e32 v139, v134
	s_nop 0
	v_fma_f32 v142, -v134, v139, 1.0
	v_fma_f32 v134, v142, v139, v139
	v_rcp_f32_e32 v139, v133
	v_pk_fma_f32 v[134:135], v[134:135], s[2:3], 0.5 op_sel_hi:[1,0,0]
	v_fma_f32 v142, -v133, v139, 1.0
	v_fma_f32 v133, v142, v139, v139
	v_rcp_f32_e32 v139, v132
	v_cvt_u32_f32_sdwa v134, v134 dst_sel:WORD_1 dst_unused:UNUSED_PAD src0_sel:DWORD
	v_cvt_u32_f32_sdwa v135, v135 dst_sel:WORD_1 dst_unused:UNUSED_PAD src0_sel:DWORD
	v_fma_f32 v142, -v132, v139, 1.0
	v_fma_f32 v132, v142, v139, v139
	v_pk_fma_f32 v[132:133], v[132:133], s[2:3], 0.5 op_sel_hi:[1,0,0]
	v_or_b32_e32 v135, v137, v135
	v_cvt_u32_f32_sdwa v132, v132 dst_sel:BYTE_3 dst_unused:UNUSED_PAD src0_sel:DWORD
	v_cvt_u32_f32_sdwa v133, v133 dst_sel:BYTE_3 dst_unused:UNUSED_PAD src0_sel:DWORD
	v_or_b32_e32 v134, v136, v134
	v_or_b32_e32 v132, v134, v132
	v_or_b32_e32 v133, v135, v133
	v_lshl_add_u64 v[134:135], v[130:131], 0, v[200:201]
	global_store_dwordx2 v[134:135], v[132:133], off nt
	v_mul_f32_e32 v132, 0xbfb8aa3b, v118
	v_mul_f32_e32 v133, 0xbfb8aa3b, v114
	v_exp_f32_e32 v134, v132
	v_exp_f32_e32 v135, v133
	v_mul_f32_e32 v132, 0xbfb8aa3b, v119
	v_mul_f32_e32 v133, 0xbfb8aa3b, v115
	v_exp_f32_e32 v136, v132
	v_pk_add_f32 v[134:135], v[134:135], 1.0 op_sel_hi:[1,0]
	v_exp_f32_e32 v137, v133
	v_rcp_f32_e32 v141, v135
	v_mul_f32_e32 v132, 0xbfb8aa3b, v120
	v_mul_f32_e32 v133, 0xbfb8aa3b, v116
	v_exp_f32_e32 v138, v132
	v_fma_f32 v142, -v135, v141, 1.0
	v_fma_f32 v135, v142, v141, v141
	v_rcp_f32_e32 v141, v134
	v_exp_f32_e32 v139, v133
	v_mul_f32_e32 v132, 0xbfb8aa3b, v121
	v_mul_f32_e32 v133, 0xbfb8aa3b, v117
	v_fma_f32 v142, -v134, v141, 1.0
	v_fma_f32 v134, v142, v141, v141
	v_pk_fma_f32 v[134:135], v[134:135], s[2:3], 0.5 op_sel_hi:[1,0,0]
	v_exp_f32_e32 v132, v132
	v_cvt_u32_f32_e32 v140, v135
	v_cvt_u32_f32_e32 v141, v134
	v_pk_add_f32 v[134:135], v[136:137], 1.0 op_sel_hi:[1,0]
	v_exp_f32_e32 v133, v133
	v_rcp_f32_e32 v137, v135
	v_pk_add_f32 v[132:133], v[132:133], 1.0 op_sel_hi:[1,0]
	v_fma_f32 v142, -v135, v137, 1.0
	v_fma_f32 v135, v142, v137, v137
	v_rcp_f32_e32 v137, v134
	s_nop 0
	v_fma_f32 v142, -v134, v137, 1.0
	v_fma_f32 v134, v142, v137, v137
	v_pk_fma_f32 v[134:135], v[134:135], s[2:3], 0.5 op_sel_hi:[1,0,0]
	s_nop 0
	v_cvt_u32_f32_e32 v136, v134
	v_cvt_u32_f32_e32 v137, v135
	v_pk_add_f32 v[134:135], v[138:139], 1.0 op_sel_hi:[1,0]
	v_lshlrev_b32_e32 v136, 8, v136
	v_rcp_f32_e32 v139, v135
	v_lshlrev_b32_e32 v137, 8, v137
	v_or_b32_e32 v137, v137, v140
	v_or_b32_e32 v136, v136, v141
	v_fma_f32 v142, -v135, v139, 1.0
	v_fma_f32 v135, v142, v139, v139
	v_rcp_f32_e32 v139, v134
	s_nop 0
	v_fma_f32 v142, -v134, v139, 1.0
	v_fma_f32 v134, v142, v139, v139
	v_rcp_f32_e32 v139, v133
	v_pk_fma_f32 v[134:135], v[134:135], s[2:3], 0.5 op_sel_hi:[1,0,0]
	v_fma_f32 v142, -v133, v139, 1.0
	v_fma_f32 v133, v142, v139, v139
	v_rcp_f32_e32 v139, v132
	v_cvt_u32_f32_sdwa v134, v134 dst_sel:WORD_1 dst_unused:UNUSED_PAD src0_sel:DWORD
	v_cvt_u32_f32_sdwa v135, v135 dst_sel:WORD_1 dst_unused:UNUSED_PAD src0_sel:DWORD
	v_fma_f32 v142, -v132, v139, 1.0
	v_fma_f32 v132, v142, v139, v139
	v_pk_fma_f32 v[132:133], v[132:133], s[2:3], 0.5 op_sel_hi:[1,0,0]
	v_or_b32_e32 v135, v137, v135
	v_cvt_u32_f32_sdwa v132, v132 dst_sel:BYTE_3 dst_unused:UNUSED_PAD src0_sel:DWORD
	v_cvt_u32_f32_sdwa v133, v133 dst_sel:BYTE_3 dst_unused:UNUSED_PAD src0_sel:DWORD
	v_or_b32_e32 v134, v136, v134
	v_or_b32_e32 v132, v134, v132
	v_or_b32_e32 v133, v135, v133
	v_lshl_add_u64 v[134:135], v[130:131], 0, v[198:199]
	global_store_dwordx2 v[134:135], v[132:133], off nt
	v_mul_f32_e32 v132, 0xbfb8aa3b, v110
	v_mul_f32_e32 v133, 0xbfb8aa3b, v106
	v_exp_f32_e32 v134, v132
	v_exp_f32_e32 v135, v133
	v_mul_f32_e32 v132, 0xbfb8aa3b, v111
	v_mul_f32_e32 v133, 0xbfb8aa3b, v107
	v_exp_f32_e32 v136, v132
;   template <int CAT>
;   __device__ __forceinline__ void slot(const f32x4 (&acc)[2][2][4][2], int bj, int r00, int p0, bool sunit, int fq, int c0, bf16_t* bdst, int bstride, float* fdst,
;                                        float scale) const {
;     ...
;         if (CAT == 2) {
;           unsigned q[8];
; #pragma unroll
;           for (int e = 0; e < 8; ++e) q[e] = (unsigned)(__frcp_rn(1.f + __expf(-v[e])) * 255.f + 0.5f);
;           u32x2 w8;
;           w8[0] = q[0] | (q[1] << 8) | (q[2] << 16) | (q[3] << 24);
;           w8[1] = q[4] | (q[5] << 8) | (q[6] << 16) | (q[7] << 24);
;           *(u32x2*)((unsigned char*)bdst + (size_t)r * 1024 + c0) = w8;
;           continue;
	v_pk_add_f32 v[134:135], v[134:135], 1.0 op_sel_hi:[1,0]
	v_exp_f32_e32 v137, v133
	v_rcp_f32_e32 v141, v135
	v_mul_f32_e32 v132, 0xbfb8aa3b, v112
	v_mul_f32_e32 v133, 0xbfb8aa3b, v108
	v_exp_f32_e32 v138, v132
	v_fma_f32 v142, -v135, v141, 1.0
	v_fma_f32 v135, v142, v141, v141
	v_rcp_f32_e32 v141, v134
	v_exp_f32_e32 v139, v133
	v_mul_f32_e32 v132, 0xbfb8aa3b, v113
	v_mul_f32_e32 v133, 0xbfb8aa3b, v109
	v_fma_f32 v142, -v134, v141, 1.0
	v_fma_f32 v134, v142, v141, v141
	v_pk_fma_f32 v[134:135], v[134:135], s[2:3], 0.5 op_sel_hi:[1,0,0]
	v_exp_f32_e32 v132, v132
	v_cvt_u32_f32_e32 v140, v135
	v_cvt_u32_f32_e32 v141, v134
	v_pk_add_f32 v[134:135], v[136:137], 1.0 op_sel_hi:[1,0]
	v_exp_f32_e32 v133, v133
	v_rcp_f32_e32 v137, v135
	v_pk_add_f32 v[132:133], v[132:133], 1.0 op_sel_hi:[1,0]
	v_fma_f32 v142, -v135, v137, 1.0
	v_fma_f32 v135, v142, v137, v137
	v_rcp_f32_e32 v137, v134
	s_nop 0
	v_fma_f32 v142, -v134, v137, 1.0
	v_fma_f32 v134, v142, v137, v137
	v_pk_fma_f32 v[134:135], v[134:135], s[2:3], 0.5 op_sel_hi:[1,0,0]
	s_nop 0
	v_cvt_u32_f32_e32 v136, v134
	v_cvt_u32_f32_e32 v137, v135
	v_pk_add_f32 v[134:135], v[138:139], 1.0 op_sel_hi:[1,0]
	v_lshlrev_b32_e32 v136, 8, v136
	v_rcp_f32_e32 v139, v135
	v_lshlrev_b32_e32 v137, 8, v137
	v_or_b32_e32 v137, v137, v140
	v_or_b32_e32 v136, v136, v141
	v_fma_f32 v142, -v135, v139, 1.0
	v_fma_f32 v135, v142, v139, v139
	v_rcp_f32_e32 v139, v134
	s_nop 0
	v_fma_f32 v142, -v134, v139, 1.0
	v_fma_f32 v134, v142, v139, v139
	v_rcp_f32_e32 v139, v133
	v_pk_fma_f32 v[134:135], v[134:135], s[2:3], 0.5 op_sel_hi:[1,0,0]
	v_fma_f32 v142, -v133, v139, 1.0
	v_fma_f32 v133, v142, v139, v139
	v_rcp_f32_e32 v139, v132
	v_cvt_u32_f32_sdwa v134, v134 dst_sel:WORD_1 dst_unused:UNUSED_PAD src0_sel:DWORD
	v_cvt_u32_f32_sdwa v135, v135 dst_sel:WORD_1 dst_unused:UNUSED_PAD src0_sel:DWORD
	v_fma_f32 v142, -v132, v139, 1.0
	v_fma_f32 v132, v142, v139, v139
	v_pk_fma_f32 v[132:133], v[132:133], s[2:3], 0.5 op_sel_hi:[1,0,0]
	v_or_b32_e32 v135, v137, v135
	v_cvt_u32_f32_sdwa v132, v132 dst_sel:BYTE_3 dst_unused:UNUSED_PAD src0_sel:DWORD
	v_cvt_u32_f32_sdwa v133, v133 dst_sel:BYTE_3 dst_unused:UNUSED_PAD src0_sel:DWORD
	v_or_b32_e32 v134, v136, v134
	v_or_b32_e32 v132, v134, v132
	v_or_b32_e32 v133, v135, v133
	v_lshl_add_u64 v[134:135], v[130:131], 0, v[228:229]
	global_store_dwordx2 v[134:135], v[132:133], off nt
	v_mul_f32_e32 v132, 0xbfb8aa3b, v102
	v_mul_f32_e32 v133, 0xbfb8aa3b, v98
	v_exp_f32_e32 v134, v132
	v_exp_f32_e32 v135, v133
	v_mul_f32_e32 v132, 0xbfb8aa3b, v103
	v_mul_f32_e32 v133, 0xbfb8aa3b, v99
	v_exp_f32_e32 v136, v132
	v_pk_add_f32 v[134:135], v[134:135], 1.0 op_sel_hi:[1,0]
	v_exp_f32_e32 v137, v133
	v_rcp_f32_e32 v141, v135
	v_mul_f32_e32 v132, 0xbfb8aa3b, v104
	v_mul_f32_e32 v133, 0xbfb8aa3b, v100
	v_exp_f32_e32 v138, v132
	v_fma_f32 v142, -v135, v141, 1.0
	v_fma_f32 v135, v142, v141, v141
	v_rcp_f32_e32 v141, v134
	v_exp_f32_e32 v139, v133
	v_mul_f32_e32 v132, 0xbfb8aa3b, v105
	v_mul_f32_e32 v133, 0xbfb8aa3b, v101
	v_fma_f32 v142, -v134, v141, 1.0
	v_fma_f32 v134, v142, v141, v141
	v_pk_fma_f32 v[134:135], v[134:135], s[2:3], 0.5 op_sel_hi:[1,0,0]
	v_exp_f32_e32 v132, v132
	v_cvt_u32_f32_e32 v140, v135
	v_cvt_u32_f32_e32 v141, v134
	v_pk_add_f32 v[134:135], v[136:137], 1.0 op_sel_hi:[1,0]
	v_exp_f32_e32 v133, v133
	v_rcp_f32_e32 v137, v135
	v_pk_add_f32 v[132:133], v[132:133], 1.0 op_sel_hi:[1,0]
	v_fma_f32 v142, -v135, v137, 1.0
	v_fma_f32 v135, v142, v137, v137
	v_rcp_f32_e32 v137, v134
	s_nop 0
	v_fma_f32 v142, -v134, v137, 1.0
	v_fma_f32 v134, v142, v137, v137
	v_pk_fma_f32 v[134:135], v[134:135], s[2:3], 0.5 op_sel_hi:[1,0,0]
	s_nop 0
	v_cvt_u32_f32_e32 v136, v134
	v_cvt_u32_f32_e32 v137, v135
	v_pk_add_f32 v[134:135], v[138:139], 1.0 op_sel_hi:[1,0]
	v_lshlrev_b32_e32 v136, 8, v136
	v_rcp_f32_e32 v139, v135
	v_lshlrev_b32_e32 v137, 8, v137
	v_or_b32_e32 v137, v137, v140
	v_or_b32_e32 v136, v136, v141
	v_fma_f32 v142, -v135, v139, 1.0
	v_fma_f32 v135, v142, v139, v139
	v_rcp_f32_e32 v139, v134
	s_nop 0
	v_fma_f32 v142, -v134, v139, 1.0
	v_fma_f32 v134, v142, v139, v139
	v_rcp_f32_e32 v139, v133
	v_pk_fma_f32 v[134:135], v[134:135], s[2:3], 0.5 op_sel_hi:[1,0,0]
	v_fma_f32 v142, -v133, v139, 1.0
	v_fma_f32 v133, v142, v139, v139
	v_rcp_f32_e32 v139, v132
	v_cvt_u32_f32_sdwa v134, v134 dst_sel:WORD_1 dst_unused:UNUSED_PAD src0_sel:DWORD
	v_cvt_u32_f32_sdwa v135, v135 dst_sel:WORD_1 dst_unused:UNUSED_PAD src0_sel:DWORD
	v_fma_f32 v142, -v132, v139, 1.0
	v_fma_f32 v132, v142, v139, v139
	v_pk_fma_f32 v[132:133], v[132:133], s[2:3], 0.5 op_sel_hi:[1,0,0]
	v_or_b32_e32 v135, v137, v135
	v_cvt_u32_f32_sdwa v132, v132 dst_sel:BYTE_3 dst_unused:UNUSED_PAD src0_sel:DWORD
	v_cvt_u32_f32_sdwa v133, v133 dst_sel:BYTE_3 dst_unused:UNUSED_PAD src0_sel:DWORD
	v_or_b32_e32 v134, v136, v134
	v_or_b32_e32 v132, v134, v132
	v_or_b32_e32 v133, v135, v133
	v_lshl_add_u64 v[134:135], v[130:131], 0, v[242:243]
	global_store_dwordx2 v[134:135], v[132:133], off nt
	v_mul_f32_e32 v132, 0xbfb8aa3b, v94
	v_mul_f32_e32 v133, 0xbfb8aa3b, v90
	v_exp_f32_e32 v134, v132
	v_exp_f32_e32 v135, v133
	v_mul_f32_e32 v132, 0xbfb8aa3b, v95
	v_mul_f32_e32 v133, 0xbfb8aa3b, v91
	v_exp_f32_e32 v136, v132
	v_pk_add_f32 v[134:135], v[134:135], 1.0 op_sel_hi:[1,0]
	v_exp_f32_e32 v137, v133
	v_rcp_f32_e32 v141, v135
	v_mul_f32_e32 v132, 0xbfb8aa3b, v96
	v_mul_f32_e32 v133, 0xbfb8aa3b, v92
	v_exp_f32_e32 v138, v132
	v_fma_f32 v142, -v135, v141, 1.0
	v_fma_f32 v135, v142, v141, v141
	v_rcp_f32_e32 v141, v134
	v_exp_f32_e32 v139, v133
	v_mul_f32_e32 v132, 0xbfb8aa3b, v97
	v_mul_f32_e32 v133, 0xbfb8aa3b, v93
	v_fma_f32 v142, -v134, v141, 1.0
;   template <int CAT>
;   __device__ __forceinline__ void slot(const f32x4 (&acc)[2][2][4][2], int bj, int r00, int p0, bool sunit, int fq, int c0, bf16_t* bdst, int bstride, float* fdst,
;                                        float scale) const {
;     ...
;         if (CAT == 2) {
;           unsigned q[8];
; #pragma unroll
;           for (int e = 0; e < 8; ++e) q[e] = (unsigned)(__frcp_rn(1.f + __expf(-v[e])) * 255.f + 0.5f);
;           u32x2 w8;
;           w8[0] = q[0] | (q[1] << 8) | (q[2] << 16) | (q[3] << 24);
;           w8[1] = q[4] | (q[5] << 8) | (q[6] << 16) | (q[7] << 24);
;           *(u32x2*)((unsigned char*)bdst + (size_t)r * 1024 + c0) = w8;
;           continue;
	v_fma_f32 v134, v142, v141, v141
	v_pk_fma_f32 v[134:135], v[134:135], s[2:3], 0.5 op_sel_hi:[1,0,0]
	v_exp_f32_e32 v132, v132
	v_cvt_u32_f32_e32 v140, v135
	v_cvt_u32_f32_e32 v141, v134
	v_pk_add_f32 v[134:135], v[136:137], 1.0 op_sel_hi:[1,0]
	v_exp_f32_e32 v133, v133
	v_rcp_f32_e32 v137, v135
	v_pk_add_f32 v[132:133], v[132:133], 1.0 op_sel_hi:[1,0]
	v_fma_f32 v142, -v135, v137, 1.0
	v_fma_f32 v135, v142, v137, v137
	v_rcp_f32_e32 v137, v134
	s_nop 0
	v_fma_f32 v142, -v134, v137, 1.0
	v_fma_f32 v134, v142, v137, v137
	v_pk_fma_f32 v[134:135], v[134:135], s[2:3], 0.5 op_sel_hi:[1,0,0]
	s_nop 0
	v_cvt_u32_f32_e32 v136, v134
	v_cvt_u32_f32_e32 v137, v135
	v_pk_add_f32 v[134:135], v[138:139], 1.0 op_sel_hi:[1,0]
	v_lshlrev_b32_e32 v136, 8, v136
	v_rcp_f32_e32 v139, v135
	v_lshlrev_b32_e32 v137, 8, v137
	v_or_b32_e32 v137, v137, v140
	v_or_b32_e32 v136, v136, v141
	v_fma_f32 v142, -v135, v139, 1.0
	v_fma_f32 v135, v142, v139, v139
	v_rcp_f32_e32 v139, v134
	s_nop 0
	v_fma_f32 v142, -v134, v139, 1.0
	v_fma_f32 v134, v142, v139, v139
	v_rcp_f32_e32 v139, v133
	v_pk_fma_f32 v[134:135], v[134:135], s[2:3], 0.5 op_sel_hi:[1,0,0]
	v_fma_f32 v142, -v133, v139, 1.0
	v_fma_f32 v133, v142, v139, v139
	v_rcp_f32_e32 v139, v132
	v_cvt_u32_f32_sdwa v134, v134 dst_sel:WORD_1 dst_unused:UNUSED_PAD src0_sel:DWORD
	v_cvt_u32_f32_sdwa v135, v135 dst_sel:WORD_1 dst_unused:UNUSED_PAD src0_sel:DWORD
	v_fma_f32 v142, -v132, v139, 1.0
	v_fma_f32 v132, v142, v139, v139
	v_pk_fma_f32 v[132:133], v[132:133], s[2:3], 0.5 op_sel_hi:[1,0,0]
	v_or_b32_e32 v135, v137, v135
	v_cvt_u32_f32_sdwa v132, v132 dst_sel:BYTE_3 dst_unused:UNUSED_PAD src0_sel:DWORD
	v_cvt_u32_f32_sdwa v133, v133 dst_sel:BYTE_3 dst_unused:UNUSED_PAD src0_sel:DWORD
	v_or_b32_e32 v134, v136, v134
	v_or_b32_e32 v132, v134, v132
	v_or_b32_e32 v133, v135, v133
	v_lshl_add_u64 v[134:135], v[130:131], 0, v[224:225]
	global_store_dwordx2 v[134:135], v[132:133], off nt
	v_mul_f32_e32 v132, 0xbfb8aa3b, v86
	v_mul_f32_e32 v133, 0xbfb8aa3b, v82
	v_exp_f32_e32 v134, v132
	v_exp_f32_e32 v135, v133
	v_mul_f32_e32 v132, 0xbfb8aa3b, v87
	v_mul_f32_e32 v133, 0xbfb8aa3b, v83
	v_exp_f32_e32 v136, v132
	v_pk_add_f32 v[134:135], v[134:135], 1.0 op_sel_hi:[1,0]
	v_exp_f32_e32 v137, v133
	v_rcp_f32_e32 v141, v135
	v_mul_f32_e32 v132, 0xbfb8aa3b, v88
	v_mul_f32_e32 v133, 0xbfb8aa3b, v84
	v_exp_f32_e32 v138, v132
	v_fma_f32 v142, -v135, v141, 1.0
	v_fma_f32 v135, v142, v141, v141
	v_rcp_f32_e32 v141, v134
	v_exp_f32_e32 v139, v133
	v_mul_f32_e32 v132, 0xbfb8aa3b, v89
	v_mul_f32_e32 v133, 0xbfb8aa3b, v85
	v_fma_f32 v142, -v134, v141, 1.0
	v_fma_f32 v134, v142, v141, v141
	v_pk_fma_f32 v[134:135], v[134:135], s[2:3], 0.5 op_sel_hi:[1,0,0]
	v_exp_f32_e32 v132, v132
	v_cvt_u32_f32_e32 v140, v135
	v_cvt_u32_f32_e32 v141, v134
	v_pk_add_f32 v[134:135], v[136:137], 1.0 op_sel_hi:[1,0]
	v_exp_f32_e32 v133, v133
	v_rcp_f32_e32 v137, v135
	v_pk_add_f32 v[132:133], v[132:133], 1.0 op_sel_hi:[1,0]
	v_fma_f32 v142, -v135, v137, 1.0
	v_fma_f32 v135, v142, v137, v137
	v_rcp_f32_e32 v137, v134
	s_nop 0
	v_fma_f32 v142, -v134, v137, 1.0
	v_fma_f32 v134, v142, v137, v137
	v_pk_fma_f32 v[134:135], v[134:135], s[2:3], 0.5 op_sel_hi:[1,0,0]
	s_nop 0
	v_cvt_u32_f32_e32 v136, v134
	v_cvt_u32_f32_e32 v137, v135
	v_pk_add_f32 v[134:135], v[138:139], 1.0 op_sel_hi:[1,0]
	v_lshlrev_b32_e32 v136, 8, v136
	v_rcp_f32_e32 v139, v135
	v_lshlrev_b32_e32 v137, 8, v137
	v_or_b32_e32 v137, v137, v140
	v_or_b32_e32 v136, v136, v141
	v_fma_f32 v142, -v135, v139, 1.0
	v_fma_f32 v135, v142, v139, v139
	v_rcp_f32_e32 v139, v134
	s_nop 0
	v_fma_f32 v142, -v134, v139, 1.0
	v_fma_f32 v134, v142, v139, v139
	v_rcp_f32_e32 v139, v133
	v_pk_fma_f32 v[134:135], v[134:135], s[2:3], 0.5 op_sel_hi:[1,0,0]
	v_fma_f32 v142, -v133, v139, 1.0
	v_fma_f32 v133, v142, v139, v139
	v_rcp_f32_e32 v139, v132
	v_cvt_u32_f32_sdwa v134, v134 dst_sel:WORD_1 dst_unused:UNUSED_PAD src0_sel:DWORD
	v_cvt_u32_f32_sdwa v135, v135 dst_sel:WORD_1 dst_unused:UNUSED_PAD src0_sel:DWORD
	v_fma_f32 v142, -v132, v139, 1.0
	v_fma_f32 v132, v142, v139, v139
	v_pk_fma_f32 v[132:133], v[132:133], s[2:3], 0.5 op_sel_hi:[1,0,0]
	v_or_b32_e32 v135, v137, v135
	v_cvt_u32_f32_sdwa v132, v132 dst_sel:BYTE_3 dst_unused:UNUSED_PAD src0_sel:DWORD
	v_cvt_u32_f32_sdwa v133, v133 dst_sel:BYTE_3 dst_unused:UNUSED_PAD src0_sel:DWORD
	v_or_b32_e32 v134, v136, v134
	v_or_b32_e32 v132, v134, v132
	v_or_b32_e32 v133, v135, v133
	v_lshl_add_u64 v[134:135], v[130:131], 0, v[222:223]
	global_store_dwordx2 v[134:135], v[132:133], off nt
	v_mul_f32_e32 v132, 0xbfb8aa3b, v78
	v_mul_f32_e32 v133, 0xbfb8aa3b, v74
	v_exp_f32_e32 v134, v132
	v_exp_f32_e32 v135, v133
	v_mul_f32_e32 v132, 0xbfb8aa3b, v79
	v_mul_f32_e32 v133, 0xbfb8aa3b, v75
	v_exp_f32_e32 v136, v132
	v_pk_add_f32 v[134:135], v[134:135], 1.0 op_sel_hi:[1,0]
	v_exp_f32_e32 v137, v133
	v_rcp_f32_e32 v141, v135
	v_mul_f32_e32 v132, 0xbfb8aa3b, v80
;   template <int CAT>
;   __device__ __forceinline__ void slot(const f32x4 (&acc)[2][2][4][2], int bj, int r00, int p0, bool sunit, int fq, int c0, bf16_t* bdst, int bstride, float* fdst,
;                                        float scale) const {
;     ...
;         if (CAT == 2) {
;           unsigned q[8];
; #pragma unroll
;           for (int e = 0; e < 8; ++e) q[e] = (unsigned)(__frcp_rn(1.f + __expf(-v[e])) * 255.f + 0.5f);
;           u32x2 w8;
;           w8[0] = q[0] | (q[1] << 8) | (q[2] << 16) | (q[3] << 24);
;           w8[1] = q[4] | (q[5] << 8) | (q[6] << 16) | (q[7] << 24);
;           *(u32x2*)((unsigned char*)bdst + (size_t)r * 1024 + c0) = w8;
;           continue;
	v_mul_f32_e32 v133, 0xbfb8aa3b, v76
	v_exp_f32_e32 v138, v132
	v_fma_f32 v142, -v135, v141, 1.0
	v_fma_f32 v135, v142, v141, v141
	v_rcp_f32_e32 v141, v134
	v_exp_f32_e32 v139, v133
	v_mul_f32_e32 v132, 0xbfb8aa3b, v81
	v_mul_f32_e32 v133, 0xbfb8aa3b, v77
	v_fma_f32 v142, -v134, v141, 1.0
	v_fma_f32 v134, v142, v141, v141
	v_pk_fma_f32 v[134:135], v[134:135], s[2:3], 0.5 op_sel_hi:[1,0,0]
	v_exp_f32_e32 v132, v132
	v_cvt_u32_f32_e32 v140, v135
	v_cvt_u32_f32_e32 v141, v134
	v_pk_add_f32 v[134:135], v[136:137], 1.0 op_sel_hi:[1,0]
	v_exp_f32_e32 v133, v133
	v_rcp_f32_e32 v137, v135
	v_pk_add_f32 v[132:133], v[132:133], 1.0 op_sel_hi:[1,0]
	v_fma_f32 v142, -v135, v137, 1.0
	v_fma_f32 v135, v142, v137, v137
	v_rcp_f32_e32 v137, v134
	s_nop 0
	v_fma_f32 v142, -v134, v137, 1.0
	v_fma_f32 v134, v142, v137, v137
	v_pk_fma_f32 v[134:135], v[134:135], s[2:3], 0.5 op_sel_hi:[1,0,0]
	s_nop 0
	v_cvt_u32_f32_e32 v136, v134
	v_cvt_u32_f32_e32 v137, v135
	v_pk_add_f32 v[134:135], v[138:139], 1.0 op_sel_hi:[1,0]
	v_lshlrev_b32_e32 v136, 8, v136
	v_rcp_f32_e32 v139, v135
	v_lshlrev_b32_e32 v137, 8, v137
	v_or_b32_e32 v137, v137, v140
	v_or_b32_e32 v136, v136, v141
	v_fma_f32 v142, -v135, v139, 1.0
	v_fma_f32 v135, v142, v139, v139
	v_rcp_f32_e32 v139, v134
	s_nop 0
	v_fma_f32 v142, -v134, v139, 1.0
	v_fma_f32 v134, v142, v139, v139
	v_rcp_f32_e32 v139, v133
	v_pk_fma_f32 v[134:135], v[134:135], s[2:3], 0.5 op_sel_hi:[1,0,0]
	v_fma_f32 v142, -v133, v139, 1.0
	v_fma_f32 v133, v142, v139, v139
	v_rcp_f32_e32 v139, v132
	v_cvt_u32_f32_sdwa v134, v134 dst_sel:WORD_1 dst_unused:UNUSED_PAD src0_sel:DWORD
	v_cvt_u32_f32_sdwa v135, v135 dst_sel:WORD_1 dst_unused:UNUSED_PAD src0_sel:DWORD
	v_fma_f32 v142, -v132, v139, 1.0
	v_fma_f32 v132, v142, v139, v139
	v_pk_fma_f32 v[132:133], v[132:133], s[2:3], 0.5 op_sel_hi:[1,0,0]
	v_or_b32_e32 v135, v137, v135
	v_cvt_u32_f32_sdwa v132, v132 dst_sel:BYTE_3 dst_unused:UNUSED_PAD src0_sel:DWORD
	v_cvt_u32_f32_sdwa v133, v133 dst_sel:BYTE_3 dst_unused:UNUSED_PAD src0_sel:DWORD
	v_or_b32_e32 v134, v136, v134
	v_or_b32_e32 v132, v134, v132
	v_or_b32_e32 v133, v135, v133
	v_lshl_add_u64 v[134:135], v[130:131], 0, v[148:149]
	global_store_dwordx2 v[134:135], v[132:133], off nt
	v_mul_f32_e32 v132, 0xbfb8aa3b, v70
	v_mul_f32_e32 v133, 0xbfb8aa3b, v66
	v_exp_f32_e32 v134, v132
	v_exp_f32_e32 v135, v133
	v_mul_f32_e32 v132, 0xbfb8aa3b, v71
	v_mul_f32_e32 v133, 0xbfb8aa3b, v67
	v_exp_f32_e32 v136, v132
	v_pk_add_f32 v[134:135], v[134:135], 1.0 op_sel_hi:[1,0]
	v_exp_f32_e32 v137, v133
	v_rcp_f32_e32 v141, v135
	v_mul_f32_e32 v132, 0xbfb8aa3b, v72
	v_mul_f32_e32 v133, 0xbfb8aa3b, v68
	v_exp_f32_e32 v138, v132
	v_fma_f32 v142, -v135, v141, 1.0
	v_fma_f32 v135, v142, v141, v141
	v_rcp_f32_e32 v141, v134
	v_exp_f32_e32 v139, v133
	v_mul_f32_e32 v132, 0xbfb8aa3b, v73
	v_mul_f32_e32 v133, 0xbfb8aa3b, v69
	v_fma_f32 v142, -v134, v141, 1.0
	v_fma_f32 v134, v142, v141, v141
	v_pk_fma_f32 v[134:135], v[134:135], s[2:3], 0.5 op_sel_hi:[1,0,0]
	v_exp_f32_e32 v132, v132
	v_cvt_u32_f32_e32 v140, v135
	v_cvt_u32_f32_e32 v141, v134
	v_pk_add_f32 v[134:135], v[136:137], 1.0 op_sel_hi:[1,0]
	v_exp_f32_e32 v133, v133
	v_rcp_f32_e32 v137, v135
	v_pk_add_f32 v[132:133], v[132:133], 1.0 op_sel_hi:[1,0]
	v_lshl_add_u64 v[130:131], v[130:131], 0, v[146:147]
	v_fma_f32 v142, -v135, v137, 1.0
	v_fma_f32 v135, v142, v137, v137
	v_rcp_f32_e32 v137, v134
	s_nop 0
	v_fma_f32 v142, -v134, v137, 1.0
	v_fma_f32 v134, v142, v137, v137
	v_pk_fma_f32 v[134:135], v[134:135], s[2:3], 0.5 op_sel_hi:[1,0,0]
	s_nop 0
	v_cvt_u32_f32_e32 v136, v134
	v_cvt_u32_f32_e32 v137, v135
	v_pk_add_f32 v[134:135], v[138:139], 1.0 op_sel_hi:[1,0]
	v_lshlrev_b32_e32 v136, 8, v136
	v_rcp_f32_e32 v139, v135
	v_lshlrev_b32_e32 v137, 8, v137
	v_or_b32_e32 v137, v137, v140
	v_or_b32_e32 v136, v136, v141
	v_fma_f32 v142, -v135, v139, 1.0
	v_fma_f32 v135, v142, v139, v139
	v_rcp_f32_e32 v139, v134
	s_nop 0
	v_fma_f32 v142, -v134, v139, 1.0
	v_fma_f32 v134, v142, v139, v139
	v_rcp_f32_e32 v139, v133
	v_pk_fma_f32 v[134:135], v[134:135], s[2:3], 0.5 op_sel_hi:[1,0,0]
	v_fma_f32 v142, -v133, v139, 1.0
	v_fma_f32 v133, v142, v139, v139
	v_rcp_f32_e32 v139, v132
	v_cvt_u32_f32_sdwa v134, v134 dst_sel:WORD_1 dst_unused:UNUSED_PAD src0_sel:DWORD
	v_cvt_u32_f32_sdwa v135, v135 dst_sel:WORD_1 dst_unused:UNUSED_PAD src0_sel:DWORD
	v_fma_f32 v142, -v132, v139, 1.0
	v_fma_f32 v132, v142, v139, v139
	v_pk_fma_f32 v[132:133], v[132:133], s[2:3], 0.5 op_sel_hi:[1,0,0]
	v_or_b32_e32 v135, v137, v135
	v_cvt_u32_f32_sdwa v132, v132 dst_sel:BYTE_3 dst_unused:UNUSED_PAD src0_sel:DWORD
	v_cvt_u32_f32_sdwa v133, v133 dst_sel:BYTE_3 dst_unused:UNUSED_PAD src0_sel:DWORD
	v_or_b32_e32 v134, v136, v134
	v_lshlrev_b64 v[142:143], 4, v[172:173]
	v_lshlrev_b64 v[136:137], 4, v[174:175]
	v_or_b32_e32 v133, v135, v133
	v_or_b32_e32 v132, v134, v132
	global_store_dwordx2 v[130:131], v[132:133], off nt

;   template <int CAT>
;   __device__ __forceinline__ void slot(const f32x4 (&acc)[2][2][4][2], int bj, int r00, int p0, bool sunit, int fq, int c0, bf16_t* bdst, int bstride, float* fdst,
;                                        float scale) const {
;     ...
;           u32x4 w;
; #pragma unroll
;           for (int e = 0; e < 4; ++e) w[e] = cvt_pk_bf16(v[2 * e] * scale, v[2 * e + 1] * scale);
;           size_t brow = (size_t)r;
;           if (fdst && sunit) brow = (size_t)(l * 16 + (sr >> 5)) * 2080 + 2048 + (sr & 31);
;           *(u32x4*)(bdst + brow * bstride + c0) = w;
;           if (fdst) {
;             float* fp = fdst + ((size_t)(sunit ? l * MS + sr : l * MP + r)) * 128 + c0;
;             *(f32x4*)fp = (f32x4){v[0], v[1], v[2], v[3]};
;             *(f32x4*)(fp + 4) = (f32x4){v[4], v[5], v[6], v[7]};
;           }
.LBB0_2499:
	v_ashrrev_i32_e32 v235, 31, v234
	v_lshl_add_u64 v[138:139], v[234:235], 1, s[4:5]
	v_lshl_add_u64 v[134:135], v[234:235], 2, s[54:55]
	v_mul_lo_u32 v241, v241, s52
	v_mul_lo_u32 v242, v240, s53
	v_mad_u64_u32 v[234:235], s[2:3], v240, s52, 0
	v_add3_u32 v235, v235, v242, v241
	v_cndmask_b32_e64 v240, 0, 1, s[56:57]
	v_lshl_add_u64 v[234:235], v[234:235], 1, v[138:139]
	v_cmp_ne_u32_e64 s[2:3], 1, v240
	s_andn2_b64 vcc, exec, s[56:57]
	global_store_dwordx4 v[234:235], v[146:149], off nt
	s_cbranch_vccnz .LBB0_2501
	v_readlane_b32 s4, v255, 22
	s_lshl_b32 s4, s4, s47
	v_readlane_b32 s5, v255, 23
	v_add_u32_e32 v146, s4, v247
	v_ashrrev_i32_e32 v147, 31, v146
	v_lshlrev_b64 v[146:147], 9, v[146:147]
	v_lshl_add_u64 v[146:147], v[134:135], 0, v[146:147]
	global_store_dwordx4 v[146:147], v[126:129], off nt
	global_store_dwordx4 v[146:147], v[122:125], off offset:16 nt

;   template <int CAT>
;   __device__ __forceinline__ void slot(const f32x4 (&acc)[2][2][4][2], int bj, int r00, int p0, bool sunit, int fq, int c0, bf16_t* bdst, int bstride, float* fdst,
;                                        float scale) const {
;     ...
;           u32x4 w;
; #pragma unroll
;           for (int e = 0; e < 4; ++e) w[e] = cvt_pk_bf16(v[2 * e] * scale, v[2 * e + 1] * scale);
;           size_t brow = (size_t)r;
;           if (fdst && sunit) brow = (size_t)(l * 16 + (sr >> 5)) * 2080 + 2048 + (sr & 31);
;           *(u32x4*)(bdst + brow * bstride + c0) = w;
;           if (fdst) {
;             float* fp = fdst + ((size_t)(sunit ? l * MS + sr : l * MP + r)) * 128 + c0;
;             *(f32x4*)fp = (f32x4){v[0], v[1], v[2], v[3]};
;             *(f32x4*)(fp + 4) = (f32x4){v[4], v[5], v[6], v[7]};
;           }
.LBB0_2505:
	v_mul_lo_u32 v131, v127, s52
	v_mul_lo_u32 v136, v126, s53
	v_mad_u64_u32 v[126:127], s[4:5], v126, s52, 0
	v_add3_u32 v127, v127, v136, v131
	v_lshl_add_u64 v[126:127], v[126:127], 1, v[138:139]
	s_and_b64 vcc, exec, s[2:3]
	global_store_dwordx4 v[126:127], v[122:125], off nt
	s_cbranch_vccnz .LBB0_2507
	v_readlane_b32 s4, v255, 22
	s_lshl_b32 s4, s4, s47
	v_readlane_b32 s5, v255, 23
	v_add_u32_e32 v122, s4, v187
	v_ashrrev_i32_e32 v123, 31, v122
	v_lshlrev_b64 v[122:123], 9, v[122:123]
	v_lshl_add_u64 v[122:123], v[134:135], 0, v[122:123]
	global_store_dwordx4 v[122:123], v[118:121], off nt
	global_store_dwordx4 v[122:123], v[114:117], off offset:16 nt

;   template <int CAT>
;   __device__ __forceinline__ void slot(const f32x4 (&acc)[2][2][4][2], int bj, int r00, int p0, bool sunit, int fq, int c0, bf16_t* bdst, int bstride, float* fdst,
;                                        float scale) const {
;     ...
;           u32x4 w;
; #pragma unroll
;           for (int e = 0; e < 4; ++e) w[e] = cvt_pk_bf16(v[2 * e] * scale, v[2 * e + 1] * scale);
;           size_t brow = (size_t)r;
;           if (fdst && sunit) brow = (size_t)(l * 16 + (sr >> 5)) * 2080 + 2048 + (sr & 31);
;           *(u32x4*)(bdst + brow * bstride + c0) = w;
;           if (fdst) {
;             float* fp = fdst + ((size_t)(sunit ? l * MS + sr : l * MP + r)) * 128 + c0;
;             *(f32x4*)fp = (f32x4){v[0], v[1], v[2], v[3]};
;             *(f32x4*)(fp + 4) = (f32x4){v[4], v[5], v[6], v[7]};
;           }
.LBB0_2516:
	v_mul_lo_u32 v115, v237, s52
	v_mul_lo_u32 v117, v236, s53
	v_mad_u64_u32 v[236:237], s[54:55], v236, s52, 0
	v_add3_u32 v237, v237, v117, v115
	v_lshl_add_u64 v[236:237], v[236:237], 1, v[138:139]
	s_and_b64 vcc, exec, s[2:3]
	global_store_dwordx4 v[236:237], v[130:133], off nt
	s_cbranch_vccnz .LBB0_2518
	v_readlane_b32 s54, v255, 22
	s_lshl_b32 s54, s54, s47
	v_readlane_b32 s55, v255, 23
	v_add_u32_e32 v130, s54, v197
	v_ashrrev_i32_e32 v131, 31, v130
	v_lshlrev_b64 v[130:131], 9, v[130:131]
	v_lshl_add_u64 v[130:131], v[134:135], 0, v[130:131]
	global_store_dwordx4 v[130:131], v[110:113], off nt
	global_store_dwordx4 v[130:131], v[106:109], off offset:16 nt

;   template <int CAT>
;   __device__ __forceinline__ void slot(const f32x4 (&acc)[2][2][4][2], int bj, int r00, int p0, bool sunit, int fq, int c0, bf16_t* bdst, int bstride, float* fdst,
;                                        float scale) const {
;     ...
;           u32x4 w;
; #pragma unroll
;           for (int e = 0; e < 4; ++e) w[e] = cvt_pk_bf16(v[2 * e] * scale, v[2 * e + 1] * scale);
;           size_t brow = (size_t)r;
;           if (fdst && sunit) brow = (size_t)(l * 16 + (sr >> 5)) * 2080 + 2048 + (sr & 31);
;           *(u32x4*)(bdst + brow * bstride + c0) = w;
;           if (fdst) {
;             float* fp = fdst + ((size_t)(sunit ? l * MS + sr : l * MP + r)) * 128 + c0;
;             *(f32x4*)fp = (f32x4){v[0], v[1], v[2], v[3]};
;             *(f32x4*)(fp + 4) = (f32x4){v[4], v[5], v[6], v[7]};
;           }
.LBB0_2522:
	v_mul_lo_u32 v112, v111, s52
	v_mul_lo_u32 v113, v110, s53
	v_mad_u64_u32 v[110:111], s[54:55], v110, s52, 0
	v_add3_u32 v111, v111, v113, v112
	v_lshl_add_u64 v[110:111], v[110:111], 1, v[138:139]
	s_and_b64 vcc, exec, s[2:3]
	v_mov_b64_e32 v[146:147], v[224:225]
	v_mov_b64_e32 v[148:149], v[198:199]
	v_mov_b32_e32 v145, v196
	v_mov_b64_e32 v[142:143], v[200:201]
	global_store_dwordx4 v[110:111], v[106:109], off nt
	s_cbranch_vccnz .LBB0_2524
	v_readlane_b32 s54, v255, 22
	s_lshl_b32 s54, s54, s47
	v_readlane_b32 s55, v255, 23
	v_add_u32_e32 v106, s54, v245
	v_ashrrev_i32_e32 v107, 31, v106
	v_lshlrev_b64 v[106:107], 9, v[106:107]
	v_lshl_add_u64 v[106:107], v[134:135], 0, v[106:107]
	global_store_dwordx4 v[106:107], v[102:105], off nt
	global_store_dwordx4 v[106:107], v[98:101], off offset:16 nt

;   template <int CAT>
;   __device__ __forceinline__ void slot(const f32x4 (&acc)[2][2][4][2], int bj, int r00, int p0, bool sunit, int fq, int c0, bf16_t* bdst, int bstride, float* fdst,
;                                        float scale) const {
;     ...
;           u32x4 w;
; #pragma unroll
;           for (int e = 0; e < 4; ++e) w[e] = cvt_pk_bf16(v[2 * e] * scale, v[2 * e + 1] * scale);
;           size_t brow = (size_t)r;
;           if (fdst && sunit) brow = (size_t)(l * 16 + (sr >> 5)) * 2080 + 2048 + (sr & 31);
;           *(u32x4*)(bdst + brow * bstride + c0) = w;
;           if (fdst) {
;             float* fp = fdst + ((size_t)(sunit ? l * MS + sr : l * MP + r)) * 128 + c0;
;             *(f32x4*)fp = (f32x4){v[0], v[1], v[2], v[3]};
;             *(f32x4*)(fp + 4) = (f32x4){v[4], v[5], v[6], v[7]};
;           }
.LBB0_2530:
	s_waitcnt vmcnt(1)
	v_mul_lo_u32 v106, v103, s52
	v_mul_lo_u32 v107, v102, s53
	v_mad_u64_u32 v[102:103], s[54:55], v102, s52, 0
	v_add3_u32 v103, v103, v107, v106
	v_lshl_add_u64 v[102:103], v[102:103], 1, v[138:139]
	s_and_b64 vcc, exec, s[2:3]
	global_store_dwordx4 v[102:103], v[114:117], off nt
	s_cbranch_vccnz .LBB0_2532
	v_readlane_b32 s54, v255, 22
	s_lshl_b32 s54, s54, s47
	v_readlane_b32 s55, v255, 23
	v_add_u32_e32 v102, s54, v185
	v_ashrrev_i32_e32 v103, 31, v102
	v_lshlrev_b64 v[102:103], 9, v[102:103]
	v_lshl_add_u64 v[102:103], v[134:135], 0, v[102:103]
	global_store_dwordx4 v[102:103], v[94:97], off nt
	global_store_dwordx4 v[102:103], v[90:93], off offset:16 nt

;   template <int CAT>
;   __device__ __forceinline__ void slot(const f32x4 (&acc)[2][2][4][2], int bj, int r00, int p0, bool sunit, int fq, int c0, bf16_t* bdst, int bstride, float* fdst,
;                                        float scale) const {
;     ...
;           u32x4 w;
; #pragma unroll
;           for (int e = 0; e < 4; ++e) w[e] = cvt_pk_bf16(v[2 * e] * scale, v[2 * e + 1] * scale);
;           size_t brow = (size_t)r;
;           if (fdst && sunit) brow = (size_t)(l * 16 + (sr >> 5)) * 2080 + 2048 + (sr & 31);
;           *(u32x4*)(bdst + brow * bstride + c0) = w;
;           if (fdst) {
;             float* fp = fdst + ((size_t)(sunit ? l * MS + sr : l * MP + r)) * 128 + c0;
;             *(f32x4*)fp = (f32x4){v[0], v[1], v[2], v[3]};
;             *(f32x4*)(fp + 4) = (f32x4){v[4], v[5], v[6], v[7]};
;           }
.LBB0_2536:
	v_mul_lo_u32 v99, v95, s52
	v_mul_lo_u32 v107, v94, s53
	v_mad_u64_u32 v[94:95], s[54:55], v94, s52, 0
	v_add3_u32 v95, v95, v107, v99
	v_lshl_add_u64 v[94:95], v[94:95], 1, v[138:139]
	s_and_b64 vcc, exec, s[2:3]
	global_store_dwordx4 v[94:95], v[90:93], off nt
	s_cbranch_vccnz .LBB0_2538
	v_readlane_b32 s54, v255, 22
	s_lshl_b32 s54, s54, s47
	v_readlane_b32 s55, v255, 23
	v_add_u32_e32 v90, s54, v188
	v_ashrrev_i32_e32 v91, 31, v90
	v_lshlrev_b64 v[90:91], 9, v[90:91]
	v_lshl_add_u64 v[90:91], v[134:135], 0, v[90:91]
	global_store_dwordx4 v[90:91], v[86:89], off nt
	global_store_dwordx4 v[90:91], v[82:85], off offset:16 nt

;   template <int CAT>
;   __device__ __forceinline__ void slot(const f32x4 (&acc)[2][2][4][2], int bj, int r00, int p0, bool sunit, int fq, int c0, bf16_t* bdst, int bstride, float* fdst,
;                                        float scale) const {
;     ...
;           u32x4 w;
; #pragma unroll
;           for (int e = 0; e < 4; ++e) w[e] = cvt_pk_bf16(v[2 * e] * scale, v[2 * e + 1] * scale);
;           size_t brow = (size_t)r;
;           if (fdst && sunit) brow = (size_t)(l * 16 + (sr >> 5)) * 2080 + 2048 + (sr & 31);
;           *(u32x4*)(bdst + brow * bstride + c0) = w;
;           if (fdst) {
;             float* fp = fdst + ((size_t)(sunit ? l * MS + sr : l * MP + r)) * 128 + c0;
;             *(f32x4*)fp = (f32x4){v[0], v[1], v[2], v[3]};
;             *(f32x4*)(fp + 4) = (f32x4){v[4], v[5], v[6], v[7]};
;           }
.LBB0_2547:
	v_mul_lo_u32 v83, v115, s52
	v_mul_lo_u32 v85, v114, s53
	v_mad_u64_u32 v[114:115], s[4:5], v114, s52, 0
	v_add3_u32 v115, v115, v85, v83
	v_lshl_add_u64 v[114:115], v[114:115], 1, v[138:139]
	s_and_b64 vcc, exec, s[2:3]
	global_store_dwordx4 v[114:115], v[98:101], off nt
	s_cbranch_vccnz .LBB0_2549
	v_readlane_b32 s4, v255, 22
	s_lshl_b32 s4, s4, s47
	v_readlane_b32 s5, v255, 23
	v_add_u32_e32 v98, s4, v186
	v_ashrrev_i32_e32 v99, 31, v98
	v_lshlrev_b64 v[98:99], 9, v[98:99]
	v_lshl_add_u64 v[98:99], v[134:135], 0, v[98:99]
	global_store_dwordx4 v[98:99], v[78:81], off nt
	global_store_dwordx4 v[98:99], v[74:77], off offset:16 nt

;   template <int CAT>
;   __device__ __forceinline__ void slot(const f32x4 (&acc)[2][2][4][2], int bj, int r00, int p0, bool sunit, int fq, int c0, bf16_t* bdst, int bstride, float* fdst,
;                                        float scale) const {
;     ...
;           u32x4 w;
; #pragma unroll
;           for (int e = 0; e < 4; ++e) w[e] = cvt_pk_bf16(v[2 * e] * scale, v[2 * e + 1] * scale);
;           size_t brow = (size_t)r;
;           if (fdst && sunit) brow = (size_t)(l * 16 + (sr >> 5)) * 2080 + 2048 + (sr & 31);
;           *(u32x4*)(bdst + brow * bstride + c0) = w;
;           if (fdst) {
;             float* fp = fdst + ((size_t)(sunit ? l * MS + sr : l * MP + r)) * 128 + c0;
;             *(f32x4*)fp = (f32x4){v[0], v[1], v[2], v[3]};
;             *(f32x4*)(fp + 4) = (f32x4){v[4], v[5], v[6], v[7]};
;           }
.LBB0_2553:
	v_mul_lo_u32 v80, v79, s52
	v_mul_lo_u32 v81, v78, s53
	v_mad_u64_u32 v[78:79], s[0:1], v78, s52, 0
	v_add3_u32 v79, v79, v81, v80
	v_lshl_add_u64 v[78:79], v[78:79], 1, v[138:139]
	s_and_b64 vcc, exec, s[2:3]
	global_store_dwordx4 v[78:79], v[74:77], off nt
	s_cbranch_vccnz .LBB0_2555
	v_readlane_b32 s0, v255, 22
	s_lshl_b32 s0, s0, s47
	v_readlane_b32 s1, v255, 23
	v_add_u32_e32 v74, s0, v184
	v_ashrrev_i32_e32 v75, 31, v74
	v_lshlrev_b64 v[74:75], 9, v[74:75]
	v_lshl_add_u64 v[74:75], v[134:135], 0, v[74:75]
	global_store_dwordx4 v[74:75], v[70:73], off nt
	global_store_dwordx4 v[74:75], v[66:69], off offset:16 nt

;   template <int CAT>
;   __device__ __forceinline__ void slot(const f32x4 (&acc)[2][2][4][2], int bj, int r00, int p0, bool sunit, int fq, int c0, bf16_t* bdst, int bstride, float* fdst,
;                                        float scale) const {
;     ...
;         } else if (CAT == 4) {
;           if (fq == 0) *(f32x4*)((float*)(ws + W_WI) + (size_t)r * 4) = (f32x4){v[0] * 0.5f, v[1] * 0.5f, v[2] * 0.5f, v[3] * 0.5f};
;   __device__ __forceinline__ void operator()(const f32x4 (&acc)[2][2][4][2], const Unit& u, int wr, int wc, int fr, int fq) const {
;     ...
;       slot_info(u.pn * 8 + bj * 4 + wc, grp, off);
;       if (grp == G_PAD) continue;
;       const int c0 = off + 8 * fq;
;       const bool dorope = (grp == G_Q || grp == G_K || grp == G_QI) && ((off & 63) == 0);
;       const float scale = grp == G_Q ? 0.125f * 1.44269504089f : (grp == G_QI ? 0.125f : 1.0f);
;       bf16_t* bdst;
;       int bstride;
;       float* fdst = nullptr;
;       switch (grp) {
;         case G_Q: bdst = (bf16_t*)(ws + W_Q); bstride = 512; break;
;         case G_QI: bdst = (bf16_t*)(ws + W_QI); bstride = 256; break;
;         case G_K: bdst = (bf16_t*)(ws + (sunit ? W_KS : W_KP)); bstride = 128; fdst = out + (sunit ? O_SK : O_PK); break;
;         case G_V: bdst = (bf16_t*)(ws + (sunit ? W_VS : W_VP)); bstride = 128; fdst = out + (sunit ? O_SV : O_PV); break;
;         case G_U: bdst = (bf16_t*)(ws + W_U); bstride = 512; break;
;         case G_VG: bdst = (bf16_t*)(ws + W_VG); bstride = 512; break;
;         case G_GA: bdst = (bf16_t*)(ws + W_GA); bstride = 1024; break;
;         case G_GB: bdst = (bf16_t*)(ws + W_GB); bstride = 1024; break;
;         default: bdst = nullptr; bstride = 0; break;
;       }
;       if (dorope) slot<0>(acc, bj, r00, p0, sunit, fq, c0, bdst, bstride, fdst, scale);
;       else if (grp == G_GA || grp == G_GB) slot<2>(acc, bj, r00, p0, sunit, fq, c0, bdst, bstride, fdst, scale);
;       else if (grp == G_KI) slot<3>(acc, bj, r00, p0, sunit, fq, c0, bdst, bstride, fdst, scale);
;       else if (grp == G_WI) slot<4>(acc, bj, r00, p0, sunit, fq, c0, bdst, bstride, fdst, scale);
.LBB0_2621:
	s_cmp_eq_u32 s59, 3
	s_cselect_b64 vcc, -1, 0
	v_mov_b32_e32 v66, 0x3e000000
	s_cmp_lg_u32 s59, 0
	v_cndmask_b32_e32 v66, 1.0, v66, vcc
	s_cselect_b64 vcc, -1, 0
	v_mov_b32_e32 v67, 0x3e38aa3b
	s_waitcnt vmcnt(0)
	v_cndmask_b32_e32 v96, v67, v66, vcc
	v_add_u32_e32 v86, s56, v236
	s_andn2_b64 vcc, exec, s[0:1]
	s_mov_b64 s[0:1], -1
	s_cbranch_vccnz .LBB0_2671
	s_and_b32 s0, s59, 14
	s_cmp_eq_u32 s0, 8
	s_mov_b64 s[0:1], -1
	s_cbranch_scc1 .LBB0_2668
	s_mov_b64 s[56:57], -1
	s_mov_b64 s[0:1], 0
	s_cmp_lt_i32 s59, 5
	s_mov_b64 s[2:3], 0
	s_cbranch_scc1 .LBB0_2663
	s_cmp_eq_u32 s59, 5
	s_mov_b64 s[2:3], -1
	s_cbranch_scc0 .LBB0_2628
	s_and_saveexec_b64 s[2:3], s[8:9]
	s_cbranch_execz .LBB0_2627
	v_pk_mul_f32 v[68:69], v[64:65], 0.5 op_sel_hi:[1,0]
	v_pk_mul_f32 v[66:67], v[62:63], 0.5 op_sel_hi:[1,0]
	v_lshl_add_u64 v[70:71], s[40:41], 0, v[218:219]
	global_store_dwordx4 v[70:71], v[66:69], off nt
	v_lshl_add_u64 v[70:71], s[40:41], 0, v[226:227]
	s_nop 0
	v_pk_mul_f32 v[68:69], v[56:57], 0.5 op_sel_hi:[1,0]
	v_pk_mul_f32 v[66:67], v[54:55], 0.5 op_sel_hi:[1,0]
	global_store_dwordx4 v[70:71], v[66:69], off nt
	v_lshl_add_u64 v[70:71], s[40:41], 0, v[250:251]
	s_nop 0
	v_pk_mul_f32 v[68:69], v[48:49], 0.5 op_sel_hi:[1,0]
	v_pk_mul_f32 v[66:67], v[46:47], 0.5 op_sel_hi:[1,0]
	global_store_dwordx4 v[70:71], v[66:69], off nt
	v_lshl_add_u64 v[70:71], s[40:41], 0, v[136:137]
	s_nop 0
	v_pk_mul_f32 v[68:69], v[40:41], 0.5 op_sel_hi:[1,0]
	v_pk_mul_f32 v[66:67], v[38:39], 0.5 op_sel_hi:[1,0]
	global_store_dwordx4 v[70:71], v[66:69], off nt
	v_lshl_add_u64 v[70:71], s[40:41], 0, v[142:143]
	s_nop 0
	v_pk_mul_f32 v[68:69], v[32:33], 0.5 op_sel_hi:[1,0]
	v_pk_mul_f32 v[66:67], v[30:31], 0.5 op_sel_hi:[1,0]
	global_store_dwordx4 v[70:71], v[66:69], off nt
	v_lshl_add_u64 v[70:71], s[40:41], 0, v[232:233]
	s_nop 0
	v_pk_mul_f32 v[68:69], v[24:25], 0.5 op_sel_hi:[1,0]
	v_pk_mul_f32 v[66:67], v[22:23], 0.5 op_sel_hi:[1,0]
	global_store_dwordx4 v[70:71], v[66:69], off nt
	v_lshl_add_u64 v[70:71], s[40:41], 0, v[230:231]
	s_nop 0
	v_pk_mul_f32 v[68:69], v[14:15], 0.5 op_sel_hi:[1,0]
	v_pk_mul_f32 v[66:67], v[12:13], 0.5 op_sel_hi:[1,0]
	global_store_dwordx4 v[70:71], v[66:69], off nt
	v_lshl_add_u64 v[70:71], s[40:41], 0, v[220:221]
	s_nop 0
	v_pk_mul_f32 v[68:69], v[6:7], 0.5 op_sel_hi:[1,0]
	v_pk_mul_f32 v[66:67], v[4:5], 0.5 op_sel_hi:[1,0]
	global_store_dwordx4 v[70:71], v[66:69], off nt

;   template <int CAT>
;   __device__ __forceinline__ void slot(const f32x4 (&acc)[2][2][4][2], int bj, int r00, int p0, bool sunit, int fq, int c0, bf16_t* bdst, int bstride, float* fdst,
;                                        float scale) const {
;     ...
;           u32x4 w;
; #pragma unroll
;           for (int e = 0; e < 4; ++e) w[e] = cvt_pk_bf16(v[2 * e] * scale, v[2 * e + 1] * scale);
;           size_t brow = (size_t)r;
;           if (fdst && sunit) brow = (size_t)(l * 16 + (sr >> 5)) * 2080 + 2048 + (sr & 31);
;           *(u32x4*)(bdst + brow * bstride + c0) = w;
;           if (fdst) {
;             float* fp = fdst + ((size_t)(sunit ? l * MS + sr : l * MP + r)) * 128 + c0;
;             *(f32x4*)fp = (f32x4){v[0], v[1], v[2], v[3]};
;             *(f32x4*)(fp + 4) = (f32x4){v[4], v[5], v[6], v[7]};
;           }
.LBB0_2632:
	v_ashrrev_i32_e32 v87, 31, v86
	v_mul_lo_u32 v76, v75, s52
	v_mul_lo_u32 v77, v74, s53
	v_mad_u64_u32 v[74:75], s[2:3], v74, s52, 0
	v_lshl_add_u64 v[72:73], v[86:87], 1, s[4:5]
	v_add3_u32 v75, v75, v77, v76
	v_cndmask_b32_e64 v76, 0, 1, s[56:57]
	v_lshl_add_u64 v[70:71], v[86:87], 2, s[54:55]
	v_lshl_add_u64 v[74:75], v[74:75], 1, v[72:73]
	v_cmp_ne_u32_e64 s[2:3], 1, v76
	s_andn2_b64 vcc, exec, s[56:57]
	global_store_dwordx4 v[74:75], v[66:69], off nt
	s_cbranch_vccnz .LBB0_2634
	v_readlane_b32 s56, v255, 22
	s_lshl_b32 s49, s56, s47
	v_add_u32_e32 v66, s49, v247
	v_ashrrev_i32_e32 v67, 31, v66
	v_lshlrev_b64 v[66:67], 9, v[66:67]
	v_lshl_add_u64 v[66:67], v[70:71], 0, v[66:67]
	v_readlane_b32 s57, v255, 23
	global_store_dwordx4 v[66:67], v[62:65], off nt
	global_store_dwordx4 v[66:67], v[58:61], off offset:16 nt

;   template <int CAT>
;   __device__ __forceinline__ void slot(const f32x4 (&acc)[2][2][4][2], int bj, int r00, int p0, bool sunit, int fq, int c0, bf16_t* bdst, int bstride, float* fdst,
;                                        float scale) const {
;     ...
;           u32x4 w;
; #pragma unroll
;           for (int e = 0; e < 4; ++e) w[e] = cvt_pk_bf16(v[2 * e] * scale, v[2 * e + 1] * scale);
;           size_t brow = (size_t)r;
;           if (fdst && sunit) brow = (size_t)(l * 16 + (sr >> 5)) * 2080 + 2048 + (sr & 31);
;           *(u32x4*)(bdst + brow * bstride + c0) = w;
;           if (fdst) {
;             float* fp = fdst + ((size_t)(sunit ? l * MS + sr : l * MP + r)) * 128 + c0;
;             *(f32x4*)fp = (f32x4){v[0], v[1], v[2], v[3]};
;             *(f32x4*)(fp + 4) = (f32x4){v[4], v[5], v[6], v[7]};
;           }
.LBB0_2636:
	v_mul_lo_u32 v76, v75, s52
	v_mul_lo_u32 v77, v74, s53
	v_mad_u64_u32 v[74:75], s[56:57], v74, s52, 0
	v_add3_u32 v75, v75, v77, v76
	v_lshl_add_u64 v[74:75], v[74:75], 1, v[72:73]
	s_and_b64 vcc, exec, s[2:3]
	global_store_dwordx4 v[74:75], v[66:69], off nt
	s_cbranch_vccnz .LBB0_2638
	v_readlane_b32 s56, v255, 22
	s_lshl_b32 s49, s56, s47
	v_add_u32_e32 v66, s49, v187
	v_ashrrev_i32_e32 v67, 31, v66
	v_lshlrev_b64 v[66:67], 9, v[66:67]
	v_lshl_add_u64 v[66:67], v[70:71], 0, v[66:67]
	v_readlane_b32 s57, v255, 23
	global_store_dwordx4 v[66:67], v[54:57], off nt
	global_store_dwordx4 v[66:67], v[50:53], off offset:16 nt

;   template <int CAT>
;   __device__ __forceinline__ void slot(const f32x4 (&acc)[2][2][4][2], int bj, int r00, int p0, bool sunit, int fq, int c0, bf16_t* bdst, int bstride, float* fdst,
;                                        float scale) const {
;     ...
;           u32x4 w;
; #pragma unroll
;           for (int e = 0; e < 4; ++e) w[e] = cvt_pk_bf16(v[2 * e] * scale, v[2 * e + 1] * scale);
;           size_t brow = (size_t)r;
;           if (fdst && sunit) brow = (size_t)(l * 16 + (sr >> 5)) * 2080 + 2048 + (sr & 31);
;           *(u32x4*)(bdst + brow * bstride + c0) = w;
;           if (fdst) {
;             float* fp = fdst + ((size_t)(sunit ? l * MS + sr : l * MP + r)) * 128 + c0;
;             *(f32x4*)fp = (f32x4){v[0], v[1], v[2], v[3]};
;             *(f32x4*)(fp + 4) = (f32x4){v[4], v[5], v[6], v[7]};
;           }
.LBB0_2640:
	v_mul_lo_u32 v76, v75, s52
	v_mul_lo_u32 v77, v74, s53
	v_mad_u64_u32 v[74:75], s[56:57], v74, s52, 0
	v_add3_u32 v75, v75, v77, v76
	v_lshl_add_u64 v[74:75], v[74:75], 1, v[72:73]
	s_and_b64 vcc, exec, s[2:3]
	global_store_dwordx4 v[74:75], v[66:69], off nt
	s_cbranch_vccnz .LBB0_2642
	v_readlane_b32 s56, v255, 22
	s_lshl_b32 s49, s56, s47
	v_add_u32_e32 v66, s49, v197
	v_ashrrev_i32_e32 v67, 31, v66
	v_lshlrev_b64 v[66:67], 9, v[66:67]
	v_lshl_add_u64 v[66:67], v[70:71], 0, v[66:67]
	v_readlane_b32 s57, v255, 23
	global_store_dwordx4 v[66:67], v[46:49], off nt
	global_store_dwordx4 v[66:67], v[42:45], off offset:16 nt

;   template <int CAT>
;   __device__ __forceinline__ void slot(const f32x4 (&acc)[2][2][4][2], int bj, int r00, int p0, bool sunit, int fq, int c0, bf16_t* bdst, int bstride, float* fdst,
;                                        float scale) const {
;     ...
;           u32x4 w;
; #pragma unroll
;           for (int e = 0; e < 4; ++e) w[e] = cvt_pk_bf16(v[2 * e] * scale, v[2 * e + 1] * scale);
;           size_t brow = (size_t)r;
;           if (fdst && sunit) brow = (size_t)(l * 16 + (sr >> 5)) * 2080 + 2048 + (sr & 31);
;           *(u32x4*)(bdst + brow * bstride + c0) = w;
;           if (fdst) {
;             float* fp = fdst + ((size_t)(sunit ? l * MS + sr : l * MP + r)) * 128 + c0;
;             *(f32x4*)fp = (f32x4){v[0], v[1], v[2], v[3]};
;             *(f32x4*)(fp + 4) = (f32x4){v[4], v[5], v[6], v[7]};
;           }
.LBB0_2644:
	v_mul_lo_u32 v76, v75, s52
	v_mul_lo_u32 v77, v74, s53
	v_mad_u64_u32 v[74:75], s[56:57], v74, s52, 0
	v_add3_u32 v75, v75, v77, v76
	v_lshl_add_u64 v[74:75], v[74:75], 1, v[72:73]
	s_and_b64 vcc, exec, s[2:3]
	global_store_dwordx4 v[74:75], v[66:69], off nt
	s_cbranch_vccnz .LBB0_2646
	v_readlane_b32 s56, v255, 22
	s_lshl_b32 s49, s56, s47
	v_add_u32_e32 v66, s49, v245
	v_ashrrev_i32_e32 v67, 31, v66
	v_lshlrev_b64 v[66:67], 9, v[66:67]
	v_lshl_add_u64 v[66:67], v[70:71], 0, v[66:67]
	v_readlane_b32 s57, v255, 23
	global_store_dwordx4 v[66:67], v[38:41], off nt
	global_store_dwordx4 v[66:67], v[34:37], off offset:16 nt

;   template <int CAT>
;   __device__ __forceinline__ void slot(const f32x4 (&acc)[2][2][4][2], int bj, int r00, int p0, bool sunit, int fq, int c0, bf16_t* bdst, int bstride, float* fdst,
;                                        float scale) const {
;     ...
;           u32x4 w;
; #pragma unroll
;           for (int e = 0; e < 4; ++e) w[e] = cvt_pk_bf16(v[2 * e] * scale, v[2 * e + 1] * scale);
;           size_t brow = (size_t)r;
;           if (fdst && sunit) brow = (size_t)(l * 16 + (sr >> 5)) * 2080 + 2048 + (sr & 31);
;           *(u32x4*)(bdst + brow * bstride + c0) = w;
;           if (fdst) {
;             float* fp = fdst + ((size_t)(sunit ? l * MS + sr : l * MP + r)) * 128 + c0;
;             *(f32x4*)fp = (f32x4){v[0], v[1], v[2], v[3]};
;             *(f32x4*)(fp + 4) = (f32x4){v[4], v[5], v[6], v[7]};
;           }
.LBB0_2648:
	v_mul_lo_u32 v76, v75, s52
	v_mul_lo_u32 v77, v74, s53
	v_mad_u64_u32 v[74:75], s[56:57], v74, s52, 0
	v_add3_u32 v75, v75, v77, v76
	v_lshl_add_u64 v[74:75], v[74:75], 1, v[72:73]
	s_and_b64 vcc, exec, s[2:3]
	global_store_dwordx4 v[74:75], v[66:69], off nt
	s_cbranch_vccnz .LBB0_2650
	v_readlane_b32 s56, v255, 22
	s_lshl_b32 s49, s56, s47
	v_add_u32_e32 v66, s49, v185
	v_ashrrev_i32_e32 v67, 31, v66
	v_lshlrev_b64 v[66:67], 9, v[66:67]
	v_lshl_add_u64 v[66:67], v[70:71], 0, v[66:67]
	v_readlane_b32 s57, v255, 23
	global_store_dwordx4 v[66:67], v[30:33], off nt
	global_store_dwordx4 v[66:67], v[26:29], off offset:16 nt

;   template <int CAT>
;   __device__ __forceinline__ void slot(const f32x4 (&acc)[2][2][4][2], int bj, int r00, int p0, bool sunit, int fq, int c0, bf16_t* bdst, int bstride, float* fdst,
;                                        float scale) const {
;     ...
;           u32x4 w;
; #pragma unroll
;           for (int e = 0; e < 4; ++e) w[e] = cvt_pk_bf16(v[2 * e] * scale, v[2 * e + 1] * scale);
;           size_t brow = (size_t)r;
;           if (fdst && sunit) brow = (size_t)(l * 16 + (sr >> 5)) * 2080 + 2048 + (sr & 31);
;           *(u32x4*)(bdst + brow * bstride + c0) = w;
;           if (fdst) {
;             float* fp = fdst + ((size_t)(sunit ? l * MS + sr : l * MP + r)) * 128 + c0;
;             *(f32x4*)fp = (f32x4){v[0], v[1], v[2], v[3]};
;             *(f32x4*)(fp + 4) = (f32x4){v[4], v[5], v[6], v[7]};
;           }
.LBB0_2652:
	v_mul_lo_u32 v76, v75, s52
	v_mul_lo_u32 v77, v74, s53
	v_mad_u64_u32 v[74:75], s[56:57], v74, s52, 0
	v_add3_u32 v75, v75, v77, v76
	v_lshl_add_u64 v[74:75], v[74:75], 1, v[72:73]
	s_and_b64 vcc, exec, s[2:3]
	global_store_dwordx4 v[74:75], v[66:69], off nt
	s_cbranch_vccnz .LBB0_2654
	v_readlane_b32 s56, v255, 22
	s_lshl_b32 s49, s56, s47
	v_add_u32_e32 v66, s49, v188
	v_ashrrev_i32_e32 v67, 31, v66
	v_lshlrev_b64 v[66:67], 9, v[66:67]
	v_lshl_add_u64 v[66:67], v[70:71], 0, v[66:67]
	v_readlane_b32 s57, v255, 23
	global_store_dwordx4 v[66:67], v[22:25], off nt
	global_store_dwordx4 v[66:67], v[18:21], off offset:16 nt

;   template <int CAT>
;   __device__ __forceinline__ void slot(const f32x4 (&acc)[2][2][4][2], int bj, int r00, int p0, bool sunit, int fq, int c0, bf16_t* bdst, int bstride, float* fdst,
;                                        float scale) const {
;     ...
;           u32x4 w;
; #pragma unroll
;           for (int e = 0; e < 4; ++e) w[e] = cvt_pk_bf16(v[2 * e] * scale, v[2 * e + 1] * scale);
;           size_t brow = (size_t)r;
;           if (fdst && sunit) brow = (size_t)(l * 16 + (sr >> 5)) * 2080 + 2048 + (sr & 31);
;           *(u32x4*)(bdst + brow * bstride + c0) = w;
;           if (fdst) {
;             float* fp = fdst + ((size_t)(sunit ? l * MS + sr : l * MP + r)) * 128 + c0;
;             *(f32x4*)fp = (f32x4){v[0], v[1], v[2], v[3]};
;             *(f32x4*)(fp + 4) = (f32x4){v[4], v[5], v[6], v[7]};
;           }
.LBB0_2656:
	v_mul_lo_u32 v76, v75, s52
	v_mul_lo_u32 v77, v74, s53
	v_mad_u64_u32 v[74:75], s[56:57], v74, s52, 0
	v_add3_u32 v75, v75, v77, v76
	v_lshl_add_u64 v[74:75], v[74:75], 1, v[72:73]
	s_and_b64 vcc, exec, s[2:3]
	global_store_dwordx4 v[74:75], v[66:69], off nt
	s_cbranch_vccnz .LBB0_2658
	v_readlane_b32 s56, v255, 22
	s_lshl_b32 s49, s56, s47
	v_add_u32_e32 v66, s49, v186
	v_ashrrev_i32_e32 v67, 31, v66
	v_lshlrev_b64 v[66:67], 9, v[66:67]
	v_lshl_add_u64 v[66:67], v[70:71], 0, v[66:67]
	v_readlane_b32 s57, v255, 23
	global_store_dwordx4 v[66:67], v[12:15], off nt
	global_store_dwordx4 v[66:67], v[8:11], off offset:16 nt

;   template <int CAT>
;   __device__ __forceinline__ void slot(const f32x4 (&acc)[2][2][4][2], int bj, int r00, int p0, bool sunit, int fq, int c0, bf16_t* bdst, int bstride, float* fdst,
;                                        float scale) const {
;     ...
;           u32x4 w;
; #pragma unroll
;           for (int e = 0; e < 4; ++e) w[e] = cvt_pk_bf16(v[2 * e] * scale, v[2 * e + 1] * scale);
;           size_t brow = (size_t)r;
;           if (fdst && sunit) brow = (size_t)(l * 16 + (sr >> 5)) * 2080 + 2048 + (sr & 31);
;           *(u32x4*)(bdst + brow * bstride + c0) = w;
;           if (fdst) {
;             float* fp = fdst + ((size_t)(sunit ? l * MS + sr : l * MP + r)) * 128 + c0;
;             *(f32x4*)fp = (f32x4){v[0], v[1], v[2], v[3]};
;             *(f32x4*)(fp + 4) = (f32x4){v[4], v[5], v[6], v[7]};
;           }
.LBB0_2660:
	v_mul_lo_u32 v76, v75, s52
	v_mul_lo_u32 v77, v74, s53
	v_mad_u64_u32 v[74:75], s[0:1], v74, s52, 0
	v_add3_u32 v75, v75, v77, v76
	v_lshl_add_u64 v[72:73], v[74:75], 1, v[72:73]
	s_and_b64 vcc, exec, s[2:3]
	global_store_dwordx4 v[72:73], v[66:69], off nt
	s_cbranch_vccnz .LBB0_2662
	v_readlane_b32 s0, v255, 22
	s_lshl_b32 s0, s0, s47
	v_readlane_b32 s1, v255, 23
	v_add_u32_e32 v66, s0, v184
	v_ashrrev_i32_e32 v67, 31, v66
	v_lshlrev_b64 v[66:67], 9, v[66:67]
	v_lshl_add_u64 v[66:67], v[70:71], 0, v[66:67]
	global_store_dwordx4 v[66:67], v[4:7], off nt
	global_store_dwordx4 v[66:67], v[0:3], off offset:16 nt

;   template <int CAT>
;   __device__ __forceinline__ void slot(const f32x4 (&acc)[2][2][4][2], int bj, int r00, int p0, bool sunit, int fq, int c0, bf16_t* bdst, int bstride, float* fdst,
;                                        float scale) const {
;     ...
;         if (CAT == 3) {
;           float* d = (float*)(ws + W_KIRAW) + (size_t)r * 64 + c0;
;           *(f32x4*)d = (f32x4){v[0], v[1], v[2], v[3]};
;           *(f32x4*)(d + 4) = (f32x4){v[4], v[5], v[6], v[7]};
.LBB0_2665:
	s_and_b64 vcc, exec, s[0:1]
	s_cbranch_vccz .LBB0_2667
	v_ashrrev_i32_e32 v87, 31, v86
	v_lshl_add_u64 v[66:67], s[42:43], 0, v[216:217]
	v_lshlrev_b64 v[68:69], 2, v[86:87]
	v_lshl_add_u64 v[66:67], v[66:67], 0, v[68:69]
	global_store_dwordx4 v[66:67], v[62:65], off nt
	global_store_dwordx4 v[66:67], v[58:61], off offset:16 nt
	v_lshl_add_u64 v[66:67], s[42:43], 0, v[214:215]
	v_lshl_add_u64 v[66:67], v[66:67], 0, v[68:69]
	global_store_dwordx4 v[66:67], v[54:57], off nt
	global_store_dwordx4 v[66:67], v[50:53], off offset:16 nt
	v_lshl_add_u64 v[66:67], s[42:43], 0, v[212:213]
	v_lshl_add_u64 v[66:67], v[66:67], 0, v[68:69]
	global_store_dwordx4 v[66:67], v[46:49], off nt
	global_store_dwordx4 v[66:67], v[42:45], off offset:16 nt
	v_lshl_add_u64 v[66:67], s[42:43], 0, v[210:211]
	v_lshl_add_u64 v[66:67], v[66:67], 0, v[68:69]
	global_store_dwordx4 v[66:67], v[38:41], off nt
	global_store_dwordx4 v[66:67], v[34:37], off offset:16 nt
	v_lshl_add_u64 v[66:67], s[42:43], 0, v[208:209]
	v_lshl_add_u64 v[66:67], v[66:67], 0, v[68:69]
	global_store_dwordx4 v[66:67], v[30:33], off nt
	global_store_dwordx4 v[66:67], v[26:29], off offset:16 nt
	v_lshl_add_u64 v[66:67], s[42:43], 0, v[206:207]
	v_lshl_add_u64 v[66:67], v[66:67], 0, v[68:69]
	global_store_dwordx4 v[66:67], v[22:25], off nt
	global_store_dwordx4 v[66:67], v[18:21], off offset:16 nt
	v_lshl_add_u64 v[66:67], s[42:43], 0, v[204:205]
	v_lshl_add_u64 v[66:67], v[66:67], 0, v[68:69]
	global_store_dwordx4 v[66:67], v[12:15], off nt
	global_store_dwordx4 v[66:67], v[8:11], off offset:16 nt
	v_lshl_add_u64 v[66:67], s[42:43], 0, v[202:203]
	v_lshl_add_u64 v[66:67], v[66:67], 0, v[68:69]
	global_store_dwordx4 v[66:67], v[4:7], off nt
	global_store_dwordx4 v[66:67], v[0:3], off offset:16 nt

;   template <int CAT>
;   __device__ __forceinline__ void slot(const f32x4 (&acc)[2][2][4][2], int bj, int r00, int p0, bool sunit, int fq, int c0, bf16_t* bdst, int bstride, float* fdst,
;                                        float scale) const {
;     ...
;         if (CAT == 2) {
;           unsigned q[8];
; #pragma unroll
;           for (int e = 0; e < 8; ++e) q[e] = (unsigned)(__frcp_rn(1.f + __expf(-v[e])) * 255.f + 0.5f);
;           u32x2 w8;
;           w8[0] = q[0] | (q[1] << 8) | (q[2] << 16) | (q[3] << 24);
;           w8[1] = q[4] | (q[5] << 8) | (q[6] << 16) | (q[7] << 24);
;           *(u32x2*)((unsigned char*)bdst + (size_t)r * 1024 + c0) = w8;
;           continue;
.LBB0_2668:
	s_and_b64 vcc, exec, s[0:1]
	s_cbranch_vccz .LBB0_2670
	v_mul_f32_e32 v68, 0xbfb8aa3b, v62
	v_mul_f32_e32 v69, 0xbfb8aa3b, v58
	v_exp_f32_e32 v70, v68
	v_exp_f32_e32 v71, v69
	v_mul_f32_e32 v68, 0xbfb8aa3b, v63
	v_mul_f32_e32 v69, 0xbfb8aa3b, v59
	v_exp_f32_e32 v72, v68
	v_pk_add_f32 v[70:71], v[70:71], 1.0 op_sel_hi:[1,0]
	v_exp_f32_e32 v73, v69
	v_rcp_f32_e32 v77, v71
	s_mov_b32 s2, 0x437f0000
	v_mul_f32_e32 v68, 0xbfb8aa3b, v64
	v_mul_f32_e32 v69, 0xbfb8aa3b, v60
	v_fma_f32 v78, -v71, v77, 1.0
	v_fma_f32 v71, v78, v77, v77
	v_rcp_f32_e32 v77, v70
	v_exp_f32_e32 v74, v68
	v_exp_f32_e32 v75, v69
	v_mul_f32_e32 v68, 0xbfb8aa3b, v65
	v_fma_f32 v78, -v70, v77, 1.0
	v_fma_f32 v70, v78, v77, v77
	v_pk_fma_f32 v[70:71], v[70:71], s[2:3], 0.5 op_sel_hi:[1,0,0]
	v_mul_f32_e32 v69, 0xbfb8aa3b, v61
	v_cvt_u32_f32_e32 v76, v71
	v_cvt_u32_f32_e32 v77, v70
	v_pk_add_f32 v[70:71], v[72:73], 1.0 op_sel_hi:[1,0]
	v_exp_f32_e32 v68, v68
	v_rcp_f32_e32 v73, v71
	v_exp_f32_e32 v69, v69
	v_ashrrev_i32_e32 v87, 31, v86
	v_lshl_add_u64 v[66:67], s[4:5], 0, v[86:87]
	v_fma_f32 v78, -v71, v73, 1.0
	v_fma_f32 v71, v78, v73, v73
	v_rcp_f32_e32 v73, v70
	v_pk_add_f32 v[68:69], v[68:69], 1.0 op_sel_hi:[1,0]
	v_fma_f32 v78, -v70, v73, 1.0
	v_fma_f32 v70, v78, v73, v73
	v_pk_fma_f32 v[70:71], v[70:71], s[2:3], 0.5 op_sel_hi:[1,0,0]
	s_nop 0
	v_cvt_u32_f32_e32 v72, v70
	v_cvt_u32_f32_e32 v73, v71
	v_pk_add_f32 v[70:71], v[74:75], 1.0 op_sel_hi:[1,0]
	v_lshlrev_b32_e32 v72, 8, v72
	v_rcp_f32_e32 v75, v71
	v_lshlrev_b32_e32 v73, 8, v73
	v_or_b32_e32 v73, v73, v76
	v_or_b32_e32 v72, v72, v77
	v_fma_f32 v78, -v71, v75, 1.0
	v_fma_f32 v71, v78, v75, v75
	v_rcp_f32_e32 v75, v70
	s_nop 0
	v_fma_f32 v78, -v70, v75, 1.0
	v_fma_f32 v70, v78, v75, v75
	v_rcp_f32_e32 v75, v69
	v_pk_fma_f32 v[70:71], v[70:71], s[2:3], 0.5 op_sel_hi:[1,0,0]
	v_fma_f32 v78, -v69, v75, 1.0
	v_fma_f32 v69, v78, v75, v75
	v_rcp_f32_e32 v75, v68
	v_cvt_u32_f32_sdwa v70, v70 dst_sel:WORD_1 dst_unused:UNUSED_PAD src0_sel:DWORD
	v_cvt_u32_f32_sdwa v71, v71 dst_sel:WORD_1 dst_unused:UNUSED_PAD src0_sel:DWORD
	v_fma_f32 v78, -v68, v75, 1.0
	v_fma_f32 v68, v78, v75, v75
	v_pk_fma_f32 v[68:69], v[68:69], s[2:3], 0.5 op_sel_hi:[1,0,0]
	v_or_b32_e32 v71, v73, v71
	v_cvt_u32_f32_sdwa v68, v68 dst_sel:BYTE_3 dst_unused:UNUSED_PAD src0_sel:DWORD
	v_cvt_u32_f32_sdwa v69, v69 dst_sel:BYTE_3 dst_unused:UNUSED_PAD src0_sel:DWORD
	v_or_b32_e32 v70, v72, v70
	v_or_b32_e32 v68, v70, v68
	v_or_b32_e32 v69, v71, v69
	v_lshl_add_u64 v[70:71], v[66:67], 0, v[200:201]
	global_store_dwordx2 v[70:71], v[68:69], off nt
	v_mul_f32_e32 v68, 0xbfb8aa3b, v54
	v_mul_f32_e32 v69, 0xbfb8aa3b, v50
	v_exp_f32_e32 v70, v68
	v_exp_f32_e32 v71, v69
	v_mul_f32_e32 v68, 0xbfb8aa3b, v55
	v_mul_f32_e32 v69, 0xbfb8aa3b, v51
	v_exp_f32_e32 v72, v68
	v_pk_add_f32 v[70:71], v[70:71], 1.0 op_sel_hi:[1,0]
	v_exp_f32_e32 v73, v69
	v_rcp_f32_e32 v77, v71
	v_mul_f32_e32 v68, 0xbfb8aa3b, v56
	v_mul_f32_e32 v69, 0xbfb8aa3b, v52
	v_exp_f32_e32 v74, v68
	v_fma_f32 v78, -v71, v77, 1.0
	v_fma_f32 v71, v78, v77, v77
	v_rcp_f32_e32 v77, v70
	v_exp_f32_e32 v75, v69
	v_mul_f32_e32 v68, 0xbfb8aa3b, v57
	v_mul_f32_e32 v69, 0xbfb8aa3b, v53
	v_fma_f32 v78, -v70, v77, 1.0
	v_fma_f32 v70, v78, v77, v77
	v_pk_fma_f32 v[70:71], v[70:71], s[2:3], 0.5 op_sel_hi:[1,0,0]
	v_exp_f32_e32 v68, v68
	v_cvt_u32_f32_e32 v76, v71
	v_cvt_u32_f32_e32 v77, v70
	v_pk_add_f32 v[70:71], v[72:73], 1.0 op_sel_hi:[1,0]
	v_exp_f32_e32 v69, v69
	v_rcp_f32_e32 v73, v71
	v_pk_add_f32 v[68:69], v[68:69], 1.0 op_sel_hi:[1,0]
	v_fma_f32 v78, -v71, v73, 1.0
	v_fma_f32 v71, v78, v73, v73
	v_rcp_f32_e32 v73, v70
	s_nop 0
	v_fma_f32 v78, -v70, v73, 1.0
	v_fma_f32 v70, v78, v73, v73
	v_pk_fma_f32 v[70:71], v[70:71], s[2:3], 0.5 op_sel_hi:[1,0,0]
	s_nop 0
	v_cvt_u32_f32_e32 v72, v70
	v_cvt_u32_f32_e32 v73, v71
	v_pk_add_f32 v[70:71], v[74:75], 1.0 op_sel_hi:[1,0]
	v_lshlrev_b32_e32 v72, 8, v72
	v_rcp_f32_e32 v75, v71
	v_lshlrev_b32_e32 v73, 8, v73
	v_or_b32_e32 v73, v73, v76
	v_or_b32_e32 v72, v72, v77
	v_fma_f32 v78, -v71, v75, 1.0
	v_fma_f32 v71, v78, v75, v75
	v_rcp_f32_e32 v75, v70
	s_nop 0
	v_fma_f32 v78, -v70, v75, 1.0
	v_fma_f32 v70, v78, v75, v75
	v_rcp_f32_e32 v75, v69
	v_pk_fma_f32 v[70:71], v[70:71], s[2:3], 0.5 op_sel_hi:[1,0,0]
	v_fma_f32 v78, -v69, v75, 1.0
	v_fma_f32 v69, v78, v75, v75
	v_rcp_f32_e32 v75, v68
	v_cvt_u32_f32_sdwa v70, v70 dst_sel:WORD_1 dst_unused:UNUSED_PAD src0_sel:DWORD
	v_cvt_u32_f32_sdwa v71, v71 dst_sel:WORD_1 dst_unused:UNUSED_PAD src0_sel:DWORD
	v_fma_f32 v78, -v68, v75, 1.0
	v_fma_f32 v68, v78, v75, v75
	v_pk_fma_f32 v[68:69], v[68:69], s[2:3], 0.5 op_sel_hi:[1,0,0]
	v_or_b32_e32 v71, v73, v71
	v_cvt_u32_f32_sdwa v68, v68 dst_sel:BYTE_3 dst_unused:UNUSED_PAD src0_sel:DWORD
	v_cvt_u32_f32_sdwa v69, v69 dst_sel:BYTE_3 dst_unused:UNUSED_PAD src0_sel:DWORD
	v_or_b32_e32 v70, v72, v70
	v_or_b32_e32 v68, v70, v68
	v_or_b32_e32 v69, v71, v69
	v_lshl_add_u64 v[70:71], v[66:67], 0, v[198:199]
	global_store_dwordx2 v[70:71], v[68:69], off nt
	v_mul_f32_e32 v68, 0xbfb8aa3b, v46
	v_mul_f32_e32 v69, 0xbfb8aa3b, v42
	v_exp_f32_e32 v70, v68
	v_exp_f32_e32 v71, v69
	v_mul_f32_e32 v68, 0xbfb8aa3b, v47
	v_mul_f32_e32 v69, 0xbfb8aa3b, v43
	v_exp_f32_e32 v72, v68
	v_pk_add_f32 v[70:71], v[70:71], 1.0 op_sel_hi:[1,0]
	v_exp_f32_e32 v73, v69
	v_rcp_f32_e32 v77, v71
	v_mul_f32_e32 v68, 0xbfb8aa3b, v48
	v_mul_f32_e32 v69, 0xbfb8aa3b, v44
	v_exp_f32_e32 v74, v68
	v_fma_f32 v78, -v71, v77, 1.0
	v_fma_f32 v71, v78, v77, v77
	v_rcp_f32_e32 v77, v70
	v_exp_f32_e32 v75, v69
	v_mul_f32_e32 v68, 0xbfb8aa3b, v49
	v_mul_f32_e32 v69, 0xbfb8aa3b, v45
	v_fma_f32 v78, -v70, v77, 1.0
;   template <int CAT>
;   __device__ __forceinline__ void slot(const f32x4 (&acc)[2][2][4][2], int bj, int r00, int p0, bool sunit, int fq, int c0, bf16_t* bdst, int bstride, float* fdst,
;                                        float scale) const {
;     ...
;         if (CAT == 2) {
;           unsigned q[8];
; #pragma unroll
;           for (int e = 0; e < 8; ++e) q[e] = (unsigned)(__frcp_rn(1.f + __expf(-v[e])) * 255.f + 0.5f);
;           u32x2 w8;
;           w8[0] = q[0] | (q[1] << 8) | (q[2] << 16) | (q[3] << 24);
;           w8[1] = q[4] | (q[5] << 8) | (q[6] << 16) | (q[7] << 24);
;           *(u32x2*)((unsigned char*)bdst + (size_t)r * 1024 + c0) = w8;
;           continue;
;         }
	v_fma_f32 v70, v78, v77, v77
	v_pk_fma_f32 v[70:71], v[70:71], s[2:3], 0.5 op_sel_hi:[1,0,0]
	v_exp_f32_e32 v68, v68
	v_cvt_u32_f32_e32 v76, v71
	v_cvt_u32_f32_e32 v77, v70
	v_pk_add_f32 v[70:71], v[72:73], 1.0 op_sel_hi:[1,0]
	v_exp_f32_e32 v69, v69
	v_rcp_f32_e32 v73, v71
	v_pk_add_f32 v[68:69], v[68:69], 1.0 op_sel_hi:[1,0]
	v_fma_f32 v78, -v71, v73, 1.0
	v_fma_f32 v71, v78, v73, v73
	v_rcp_f32_e32 v73, v70
	s_nop 0
	v_fma_f32 v78, -v70, v73, 1.0
	v_fma_f32 v70, v78, v73, v73
	v_pk_fma_f32 v[70:71], v[70:71], s[2:3], 0.5 op_sel_hi:[1,0,0]
	s_nop 0
	v_cvt_u32_f32_e32 v72, v70
	v_cvt_u32_f32_e32 v73, v71
	v_pk_add_f32 v[70:71], v[74:75], 1.0 op_sel_hi:[1,0]
	v_lshlrev_b32_e32 v72, 8, v72
	v_rcp_f32_e32 v75, v71
	v_lshlrev_b32_e32 v73, 8, v73
	v_or_b32_e32 v73, v73, v76
	v_or_b32_e32 v72, v72, v77
	v_fma_f32 v78, -v71, v75, 1.0
	v_fma_f32 v71, v78, v75, v75
	v_rcp_f32_e32 v75, v70
	s_nop 0
	v_fma_f32 v78, -v70, v75, 1.0
	v_fma_f32 v70, v78, v75, v75
	v_rcp_f32_e32 v75, v69
	v_pk_fma_f32 v[70:71], v[70:71], s[2:3], 0.5 op_sel_hi:[1,0,0]
	v_fma_f32 v78, -v69, v75, 1.0
	v_fma_f32 v69, v78, v75, v75
	v_rcp_f32_e32 v75, v68
	v_cvt_u32_f32_sdwa v70, v70 dst_sel:WORD_1 dst_unused:UNUSED_PAD src0_sel:DWORD
	v_cvt_u32_f32_sdwa v71, v71 dst_sel:WORD_1 dst_unused:UNUSED_PAD src0_sel:DWORD
	v_fma_f32 v78, -v68, v75, 1.0
	v_fma_f32 v68, v78, v75, v75
	v_pk_fma_f32 v[68:69], v[68:69], s[2:3], 0.5 op_sel_hi:[1,0,0]
	v_or_b32_e32 v71, v73, v71
	v_cvt_u32_f32_sdwa v68, v68 dst_sel:BYTE_3 dst_unused:UNUSED_PAD src0_sel:DWORD
	v_cvt_u32_f32_sdwa v69, v69 dst_sel:BYTE_3 dst_unused:UNUSED_PAD src0_sel:DWORD
	v_or_b32_e32 v70, v72, v70
	v_or_b32_e32 v68, v70, v68
	v_or_b32_e32 v69, v71, v69
	v_lshl_add_u64 v[70:71], v[66:67], 0, v[228:229]
	global_store_dwordx2 v[70:71], v[68:69], off nt
	v_mul_f32_e32 v68, 0xbfb8aa3b, v38
	v_mul_f32_e32 v69, 0xbfb8aa3b, v34
	v_exp_f32_e32 v70, v68
	v_exp_f32_e32 v71, v69
	v_mul_f32_e32 v68, 0xbfb8aa3b, v39
	v_mul_f32_e32 v69, 0xbfb8aa3b, v35
	v_exp_f32_e32 v72, v68
	v_pk_add_f32 v[70:71], v[70:71], 1.0 op_sel_hi:[1,0]
	v_exp_f32_e32 v73, v69
	v_rcp_f32_e32 v77, v71
	v_mul_f32_e32 v68, 0xbfb8aa3b, v40
	v_mul_f32_e32 v69, 0xbfb8aa3b, v36
	v_exp_f32_e32 v74, v68
	v_fma_f32 v78, -v71, v77, 1.0
	v_fma_f32 v71, v78, v77, v77
	v_rcp_f32_e32 v77, v70
	v_exp_f32_e32 v75, v69
	v_mul_f32_e32 v68, 0xbfb8aa3b, v41
	v_mul_f32_e32 v69, 0xbfb8aa3b, v37
	v_fma_f32 v78, -v70, v77, 1.0
	v_fma_f32 v70, v78, v77, v77
	v_pk_fma_f32 v[70:71], v[70:71], s[2:3], 0.5 op_sel_hi:[1,0,0]
	v_exp_f32_e32 v68, v68
	v_cvt_u32_f32_e32 v76, v71
	v_cvt_u32_f32_e32 v77, v70
	v_pk_add_f32 v[70:71], v[72:73], 1.0 op_sel_hi:[1,0]
	v_exp_f32_e32 v69, v69
	v_rcp_f32_e32 v73, v71
	v_pk_add_f32 v[68:69], v[68:69], 1.0 op_sel_hi:[1,0]
	v_fma_f32 v78, -v71, v73, 1.0
	v_fma_f32 v71, v78, v73, v73
	v_rcp_f32_e32 v73, v70
	s_nop 0
	v_fma_f32 v78, -v70, v73, 1.0
	v_fma_f32 v70, v78, v73, v73
	v_pk_fma_f32 v[70:71], v[70:71], s[2:3], 0.5 op_sel_hi:[1,0,0]
	s_nop 0
	v_cvt_u32_f32_e32 v72, v70
	v_cvt_u32_f32_e32 v73, v71
	v_pk_add_f32 v[70:71], v[74:75], 1.0 op_sel_hi:[1,0]
	v_lshlrev_b32_e32 v72, 8, v72
	v_rcp_f32_e32 v75, v71
	v_lshlrev_b32_e32 v73, 8, v73
	v_or_b32_e32 v73, v73, v76
	v_or_b32_e32 v72, v72, v77
	v_fma_f32 v78, -v71, v75, 1.0
	v_fma_f32 v71, v78, v75, v75
	v_rcp_f32_e32 v75, v70
	s_nop 0
	v_fma_f32 v78, -v70, v75, 1.0
	v_fma_f32 v70, v78, v75, v75
	v_rcp_f32_e32 v75, v69
	v_pk_fma_f32 v[70:71], v[70:71], s[2:3], 0.5 op_sel_hi:[1,0,0]
	v_fma_f32 v78, -v69, v75, 1.0
	v_fma_f32 v69, v78, v75, v75
	v_rcp_f32_e32 v75, v68
	v_cvt_u32_f32_sdwa v70, v70 dst_sel:WORD_1 dst_unused:UNUSED_PAD src0_sel:DWORD
	v_cvt_u32_f32_sdwa v71, v71 dst_sel:WORD_1 dst_unused:UNUSED_PAD src0_sel:DWORD
	v_fma_f32 v78, -v68, v75, 1.0
	v_fma_f32 v68, v78, v75, v75
	v_pk_fma_f32 v[68:69], v[68:69], s[2:3], 0.5 op_sel_hi:[1,0,0]
	v_or_b32_e32 v71, v73, v71
	v_cvt_u32_f32_sdwa v68, v68 dst_sel:BYTE_3 dst_unused:UNUSED_PAD src0_sel:DWORD
	v_cvt_u32_f32_sdwa v69, v69 dst_sel:BYTE_3 dst_unused:UNUSED_PAD src0_sel:DWORD
	v_or_b32_e32 v70, v72, v70
	v_or_b32_e32 v68, v70, v68
	v_or_b32_e32 v69, v71, v69
	v_lshl_add_u64 v[70:71], v[66:67], 0, v[242:243]
	global_store_dwordx2 v[70:71], v[68:69], off nt
	v_mul_f32_e32 v68, 0xbfb8aa3b, v30
	v_mul_f32_e32 v69, 0xbfb8aa3b, v26
	v_exp_f32_e32 v70, v68
	v_exp_f32_e32 v71, v69
	v_mul_f32_e32 v68, 0xbfb8aa3b, v31
	v_mul_f32_e32 v69, 0xbfb8aa3b, v27
	v_exp_f32_e32 v72, v68
	v_pk_add_f32 v[70:71], v[70:71], 1.0 op_sel_hi:[1,0]
	v_exp_f32_e32 v73, v69
	v_rcp_f32_e32 v77, v71
	v_mul_f32_e32 v68, 0xbfb8aa3b, v32
	v_mul_f32_e32 v69, 0xbfb8aa3b, v28
	v_exp_f32_e32 v74, v68
	v_fma_f32 v78, -v71, v77, 1.0
	v_fma_f32 v71, v78, v77, v77
	v_rcp_f32_e32 v77, v70
	v_exp_f32_e32 v75, v69
	v_mul_f32_e32 v68, 0xbfb8aa3b, v33
	v_mul_f32_e32 v69, 0xbfb8aa3b, v29
	v_fma_f32 v78, -v70, v77, 1.0
	v_fma_f32 v70, v78, v77, v77
	v_pk_fma_f32 v[70:71], v[70:71], s[2:3], 0.5 op_sel_hi:[1,0,0]
	v_exp_f32_e32 v68, v68
	v_cvt_u32_f32_e32 v76, v71
	v_cvt_u32_f32_e32 v77, v70
	v_pk_add_f32 v[70:71], v[72:73], 1.0 op_sel_hi:[1,0]
	v_exp_f32_e32 v69, v69
	v_rcp_f32_e32 v73, v71
	v_pk_add_f32 v[68:69], v[68:69], 1.0 op_sel_hi:[1,0]
	v_fma_f32 v78, -v71, v73, 1.0
	v_fma_f32 v71, v78, v73, v73
	v_rcp_f32_e32 v73, v70
	s_nop 0
	v_fma_f32 v78, -v70, v73, 1.0
	v_fma_f32 v70, v78, v73, v73
	v_pk_fma_f32 v[70:71], v[70:71], s[2:3], 0.5 op_sel_hi:[1,0,0]
	s_nop 0
	v_cvt_u32_f32_e32 v72, v70
	v_cvt_u32_f32_e32 v73, v71
	v_pk_add_f32 v[70:71], v[74:75], 1.0 op_sel_hi:[1,0]
	v_lshlrev_b32_e32 v72, 8, v72
	v_rcp_f32_e32 v75, v71
	v_lshlrev_b32_e32 v73, 8, v73
	v_or_b32_e32 v73, v73, v76
;   template <int CAT>
;   __device__ __forceinline__ void slot(const f32x4 (&acc)[2][2][4][2], int bj, int r00, int p0, bool sunit, int fq, int c0, bf16_t* bdst, int bstride, float* fdst,
;                                        float scale) const {
;     ...
;         if (CAT == 2) {
;           unsigned q[8];
; #pragma unroll
;           for (int e = 0; e < 8; ++e) q[e] = (unsigned)(__frcp_rn(1.f + __expf(-v[e])) * 255.f + 0.5f);
;           u32x2 w8;
;           w8[0] = q[0] | (q[1] << 8) | (q[2] << 16) | (q[3] << 24);
;           w8[1] = q[4] | (q[5] << 8) | (q[6] << 16) | (q[7] << 24);
;           *(u32x2*)((unsigned char*)bdst + (size_t)r * 1024 + c0) = w8;
;           continue;
;         }
	v_or_b32_e32 v72, v72, v77
	v_fma_f32 v78, -v71, v75, 1.0
	v_fma_f32 v71, v78, v75, v75
	v_rcp_f32_e32 v75, v70
	s_nop 0
	v_fma_f32 v78, -v70, v75, 1.0
	v_fma_f32 v70, v78, v75, v75
	v_rcp_f32_e32 v75, v69
	v_pk_fma_f32 v[70:71], v[70:71], s[2:3], 0.5 op_sel_hi:[1,0,0]
	v_fma_f32 v78, -v69, v75, 1.0
	v_fma_f32 v69, v78, v75, v75
	v_rcp_f32_e32 v75, v68
	v_cvt_u32_f32_sdwa v70, v70 dst_sel:WORD_1 dst_unused:UNUSED_PAD src0_sel:DWORD
	v_cvt_u32_f32_sdwa v71, v71 dst_sel:WORD_1 dst_unused:UNUSED_PAD src0_sel:DWORD
	v_fma_f32 v78, -v68, v75, 1.0
	v_fma_f32 v68, v78, v75, v75
	v_pk_fma_f32 v[68:69], v[68:69], s[2:3], 0.5 op_sel_hi:[1,0,0]
	v_or_b32_e32 v71, v73, v71
	v_cvt_u32_f32_sdwa v68, v68 dst_sel:BYTE_3 dst_unused:UNUSED_PAD src0_sel:DWORD
	v_cvt_u32_f32_sdwa v69, v69 dst_sel:BYTE_3 dst_unused:UNUSED_PAD src0_sel:DWORD
	v_or_b32_e32 v70, v72, v70
	v_or_b32_e32 v68, v70, v68
	v_or_b32_e32 v69, v71, v69
	v_lshl_add_u64 v[70:71], v[66:67], 0, v[224:225]
	global_store_dwordx2 v[70:71], v[68:69], off nt
	v_mul_f32_e32 v68, 0xbfb8aa3b, v22
	v_mul_f32_e32 v69, 0xbfb8aa3b, v18
	v_exp_f32_e32 v70, v68
	v_exp_f32_e32 v71, v69
	v_mul_f32_e32 v68, 0xbfb8aa3b, v23
	v_mul_f32_e32 v69, 0xbfb8aa3b, v19
	v_exp_f32_e32 v72, v68
	v_pk_add_f32 v[70:71], v[70:71], 1.0 op_sel_hi:[1,0]
	v_exp_f32_e32 v73, v69
	v_rcp_f32_e32 v77, v71
	v_mul_f32_e32 v68, 0xbfb8aa3b, v24
	v_mul_f32_e32 v69, 0xbfb8aa3b, v20
	v_exp_f32_e32 v74, v68
	v_fma_f32 v78, -v71, v77, 1.0
	v_fma_f32 v71, v78, v77, v77
	v_rcp_f32_e32 v77, v70
	v_exp_f32_e32 v75, v69
	v_mul_f32_e32 v68, 0xbfb8aa3b, v25
	v_mul_f32_e32 v69, 0xbfb8aa3b, v21
	v_fma_f32 v78, -v70, v77, 1.0
	v_fma_f32 v70, v78, v77, v77
	v_pk_fma_f32 v[70:71], v[70:71], s[2:3], 0.5 op_sel_hi:[1,0,0]
	v_exp_f32_e32 v68, v68
	v_cvt_u32_f32_e32 v76, v71
	v_cvt_u32_f32_e32 v77, v70
	v_pk_add_f32 v[70:71], v[72:73], 1.0 op_sel_hi:[1,0]
	v_exp_f32_e32 v69, v69
	v_rcp_f32_e32 v73, v71
	v_pk_add_f32 v[68:69], v[68:69], 1.0 op_sel_hi:[1,0]
	v_fma_f32 v78, -v71, v73, 1.0
	v_fma_f32 v71, v78, v73, v73
	v_rcp_f32_e32 v73, v70
	s_nop 0
	v_fma_f32 v78, -v70, v73, 1.0
	v_fma_f32 v70, v78, v73, v73
	v_pk_fma_f32 v[70:71], v[70:71], s[2:3], 0.5 op_sel_hi:[1,0,0]
	s_nop 0
	v_cvt_u32_f32_e32 v72, v70
	v_cvt_u32_f32_e32 v73, v71
	v_pk_add_f32 v[70:71], v[74:75], 1.0 op_sel_hi:[1,0]
	v_lshlrev_b32_e32 v72, 8, v72
	v_rcp_f32_e32 v75, v71
	v_lshlrev_b32_e32 v73, 8, v73
	v_or_b32_e32 v73, v73, v76
	v_or_b32_e32 v72, v72, v77
	v_fma_f32 v78, -v71, v75, 1.0
	v_fma_f32 v71, v78, v75, v75
	v_rcp_f32_e32 v75, v70
	s_nop 0
	v_fma_f32 v78, -v70, v75, 1.0
	v_fma_f32 v70, v78, v75, v75
	v_rcp_f32_e32 v75, v69
	v_pk_fma_f32 v[70:71], v[70:71], s[2:3], 0.5 op_sel_hi:[1,0,0]
	v_fma_f32 v78, -v69, v75, 1.0
	v_fma_f32 v69, v78, v75, v75
	v_rcp_f32_e32 v75, v68
	v_cvt_u32_f32_sdwa v70, v70 dst_sel:WORD_1 dst_unused:UNUSED_PAD src0_sel:DWORD
	v_cvt_u32_f32_sdwa v71, v71 dst_sel:WORD_1 dst_unused:UNUSED_PAD src0_sel:DWORD
	v_fma_f32 v78, -v68, v75, 1.0
	v_fma_f32 v68, v78, v75, v75
	v_pk_fma_f32 v[68:69], v[68:69], s[2:3], 0.5 op_sel_hi:[1,0,0]
	v_or_b32_e32 v71, v73, v71
	v_cvt_u32_f32_sdwa v68, v68 dst_sel:BYTE_3 dst_unused:UNUSED_PAD src0_sel:DWORD
	v_cvt_u32_f32_sdwa v69, v69 dst_sel:BYTE_3 dst_unused:UNUSED_PAD src0_sel:DWORD
	v_or_b32_e32 v70, v72, v70
	v_or_b32_e32 v68, v70, v68
	v_or_b32_e32 v69, v71, v69
	v_lshl_add_u64 v[70:71], v[66:67], 0, v[222:223]
	global_store_dwordx2 v[70:71], v[68:69], off nt
	v_mul_f32_e32 v68, 0xbfb8aa3b, v12
	v_mul_f32_e32 v69, 0xbfb8aa3b, v8
	v_exp_f32_e32 v70, v68
	v_exp_f32_e32 v71, v69
	v_mul_f32_e32 v68, 0xbfb8aa3b, v13
	v_mul_f32_e32 v69, 0xbfb8aa3b, v9
	v_exp_f32_e32 v72, v68
	v_pk_add_f32 v[70:71], v[70:71], 1.0 op_sel_hi:[1,0]
	v_exp_f32_e32 v73, v69
	v_rcp_f32_e32 v77, v71
	v_mul_f32_e32 v68, 0xbfb8aa3b, v14
	v_mul_f32_e32 v69, 0xbfb8aa3b, v10
	v_exp_f32_e32 v74, v68
	v_fma_f32 v78, -v71, v77, 1.0
	v_fma_f32 v71, v78, v77, v77
	v_rcp_f32_e32 v77, v70
	v_exp_f32_e32 v75, v69
	v_mul_f32_e32 v68, 0xbfb8aa3b, v15
	v_mul_f32_e32 v69, 0xbfb8aa3b, v11
	v_fma_f32 v78, -v70, v77, 1.0
	v_fma_f32 v70, v78, v77, v77
	v_pk_fma_f32 v[70:71], v[70:71], s[2:3], 0.5 op_sel_hi:[1,0,0]
;   template <int CAT>
;   __device__ __forceinline__ void slot(const f32x4 (&acc)[2][2][4][2], int bj, int r00, int p0, bool sunit, int fq, int c0, bf16_t* bdst, int bstride, float* fdst,
;                                        float scale) const {
;     ...
;         if (CAT == 2) {
;           unsigned q[8];
; #pragma unroll
;           for (int e = 0; e < 8; ++e) q[e] = (unsigned)(__frcp_rn(1.f + __expf(-v[e])) * 255.f + 0.5f);
;           u32x2 w8;
;           w8[0] = q[0] | (q[1] << 8) | (q[2] << 16) | (q[3] << 24);
;           w8[1] = q[4] | (q[5] << 8) | (q[6] << 16) | (q[7] << 24);
;           *(u32x2*)((unsigned char*)bdst + (size_t)r * 1024 + c0) = w8;
;           continue;
;         }
	v_exp_f32_e32 v68, v68
	v_cvt_u32_f32_e32 v76, v71
	v_cvt_u32_f32_e32 v77, v70
	v_pk_add_f32 v[70:71], v[72:73], 1.0 op_sel_hi:[1,0]
	v_exp_f32_e32 v69, v69
	v_rcp_f32_e32 v73, v71
	v_pk_add_f32 v[68:69], v[68:69], 1.0 op_sel_hi:[1,0]
	v_fma_f32 v78, -v71, v73, 1.0
	v_fma_f32 v71, v78, v73, v73
	v_rcp_f32_e32 v73, v70
	s_nop 0
	v_fma_f32 v78, -v70, v73, 1.0
	v_fma_f32 v70, v78, v73, v73
	v_pk_fma_f32 v[70:71], v[70:71], s[2:3], 0.5 op_sel_hi:[1,0,0]
	s_nop 0
	v_cvt_u32_f32_e32 v72, v70
	v_cvt_u32_f32_e32 v73, v71
	v_pk_add_f32 v[70:71], v[74:75], 1.0 op_sel_hi:[1,0]
	v_lshlrev_b32_e32 v72, 8, v72
	v_rcp_f32_e32 v75, v71
	v_lshlrev_b32_e32 v73, 8, v73
	v_or_b32_e32 v73, v73, v76
	v_or_b32_e32 v72, v72, v77
	v_fma_f32 v78, -v71, v75, 1.0
	v_fma_f32 v71, v78, v75, v75
	v_rcp_f32_e32 v75, v70
	s_nop 0
	v_fma_f32 v78, -v70, v75, 1.0
	v_fma_f32 v70, v78, v75, v75
	v_rcp_f32_e32 v75, v69
	v_pk_fma_f32 v[70:71], v[70:71], s[2:3], 0.5 op_sel_hi:[1,0,0]
	v_fma_f32 v78, -v69, v75, 1.0
	v_fma_f32 v69, v78, v75, v75
	v_rcp_f32_e32 v75, v68
	v_cvt_u32_f32_sdwa v70, v70 dst_sel:WORD_1 dst_unused:UNUSED_PAD src0_sel:DWORD
	v_cvt_u32_f32_sdwa v71, v71 dst_sel:WORD_1 dst_unused:UNUSED_PAD src0_sel:DWORD
	v_fma_f32 v78, -v68, v75, 1.0
	v_fma_f32 v68, v78, v75, v75
	v_pk_fma_f32 v[68:69], v[68:69], s[2:3], 0.5 op_sel_hi:[1,0,0]
	v_or_b32_e32 v71, v73, v71
	v_cvt_u32_f32_sdwa v68, v68 dst_sel:BYTE_3 dst_unused:UNUSED_PAD src0_sel:DWORD
	v_cvt_u32_f32_sdwa v69, v69 dst_sel:BYTE_3 dst_unused:UNUSED_PAD src0_sel:DWORD
	v_or_b32_e32 v70, v72, v70
	v_or_b32_e32 v68, v70, v68
	v_or_b32_e32 v69, v71, v69
	v_lshl_add_u64 v[70:71], v[66:67], 0, v[148:149]
	global_store_dwordx2 v[70:71], v[68:69], off nt
	v_mul_f32_e32 v68, 0xbfb8aa3b, v4
	v_mul_f32_e32 v69, 0xbfb8aa3b, v0
	v_exp_f32_e32 v70, v68
	v_exp_f32_e32 v71, v69
	v_mul_f32_e32 v68, 0xbfb8aa3b, v5
	v_mul_f32_e32 v69, 0xbfb8aa3b, v1
	v_exp_f32_e32 v72, v68
	v_pk_add_f32 v[70:71], v[70:71], 1.0 op_sel_hi:[1,0]
	v_exp_f32_e32 v73, v69
	v_rcp_f32_e32 v77, v71
	v_mul_f32_e32 v68, 0xbfb8aa3b, v6
	v_mul_f32_e32 v69, 0xbfb8aa3b, v2
	v_exp_f32_e32 v74, v68
	v_fma_f32 v78, -v71, v77, 1.0
	v_fma_f32 v71, v78, v77, v77
	v_rcp_f32_e32 v77, v70
	v_exp_f32_e32 v75, v69
	v_mul_f32_e32 v68, 0xbfb8aa3b, v7
	v_mul_f32_e32 v69, 0xbfb8aa3b, v3
	v_fma_f32 v78, -v70, v77, 1.0
	v_fma_f32 v70, v78, v77, v77
	v_pk_fma_f32 v[70:71], v[70:71], s[2:3], 0.5 op_sel_hi:[1,0,0]
	v_exp_f32_e32 v68, v68
	v_cvt_u32_f32_e32 v76, v71
	v_cvt_u32_f32_e32 v77, v70
	v_pk_add_f32 v[70:71], v[72:73], 1.0 op_sel_hi:[1,0]
	v_exp_f32_e32 v69, v69
	v_rcp_f32_e32 v73, v71
	v_pk_add_f32 v[68:69], v[68:69], 1.0 op_sel_hi:[1,0]
	v_lshl_add_u64 v[66:67], v[66:67], 0, v[146:147]
	v_fma_f32 v78, -v71, v73, 1.0
	v_fma_f32 v71, v78, v73, v73
	v_rcp_f32_e32 v73, v70
	s_nop 0
	v_fma_f32 v78, -v70, v73, 1.0
	v_fma_f32 v70, v78, v73, v73
	v_pk_fma_f32 v[70:71], v[70:71], s[2:3], 0.5 op_sel_hi:[1,0,0]
	s_nop 0
	v_cvt_u32_f32_e32 v72, v70
	v_cvt_u32_f32_e32 v73, v71
	v_pk_add_f32 v[70:71], v[74:75], 1.0 op_sel_hi:[1,0]
	v_lshlrev_b32_e32 v72, 8, v72
	v_rcp_f32_e32 v75, v71
	v_lshlrev_b32_e32 v73, 8, v73
	v_or_b32_e32 v73, v73, v76
	v_or_b32_e32 v72, v72, v77
	v_fma_f32 v78, -v71, v75, 1.0
	v_fma_f32 v71, v78, v75, v75
	v_rcp_f32_e32 v75, v70
	s_nop 0
	v_fma_f32 v78, -v70, v75, 1.0
	v_fma_f32 v70, v78, v75, v75
	v_rcp_f32_e32 v75, v69
	v_pk_fma_f32 v[70:71], v[70:71], s[2:3], 0.5 op_sel_hi:[1,0,0]
	v_fma_f32 v78, -v69, v75, 1.0
	v_fma_f32 v69, v78, v75, v75
	v_rcp_f32_e32 v75, v68
	v_cvt_u32_f32_sdwa v70, v70 dst_sel:WORD_1 dst_unused:UNUSED_PAD src0_sel:DWORD
	v_cvt_u32_f32_sdwa v71, v71 dst_sel:WORD_1 dst_unused:UNUSED_PAD src0_sel:DWORD
	v_fma_f32 v78, -v68, v75, 1.0
	v_fma_f32 v68, v78, v75, v75
	v_pk_fma_f32 v[68:69], v[68:69], s[2:3], 0.5 op_sel_hi:[1,0,0]
	v_or_b32_e32 v71, v73, v71
	v_cvt_u32_f32_sdwa v68, v68 dst_sel:BYTE_3 dst_unused:UNUSED_PAD src0_sel:DWORD
	v_cvt_u32_f32_sdwa v69, v69 dst_sel:BYTE_3 dst_unused:UNUSED_PAD src0_sel:DWORD
	v_or_b32_e32 v70, v72, v70
	v_or_b32_e32 v68, v70, v68
	v_or_b32_e32 v69, v71, v69
	global_store_dwordx2 v[66:67], v[68:69], off nt

;   template <int CAT>
;   __device__ __forceinline__ void slot(const f32x4 (&acc)[2][2][4][2], int bj, int r00, int p0, bool sunit, int fq, int c0, bf16_t* bdst, int bstride, float* fdst,
;                                        float scale) const {
;     ...
;           u32x4 w;
; #pragma unroll
;           for (int e = 0; e < 4; ++e) w[e] = cvt_pk_bf16(v[2 * e] * scale, v[2 * e + 1] * scale);
;           size_t brow = (size_t)r;
;           if (fdst && sunit) brow = (size_t)(l * 16 + (sr >> 5)) * 2080 + 2048 + (sr & 31);
;           *(u32x4*)(bdst + brow * bstride + c0) = w;
;           if (fdst) {
;             float* fp = fdst + ((size_t)(sunit ? l * MS + sr : l * MP + r)) * 128 + c0;
;             *(f32x4*)fp = (f32x4){v[0], v[1], v[2], v[3]};
;             *(f32x4*)(fp + 4) = (f32x4){v[4], v[5], v[6], v[7]};
;           }
.LBB0_2678:
	v_ashrrev_i32_e32 v87, 31, v86
	v_lshl_add_u64 v[74:75], v[86:87], 1, s[4:5]
	v_lshl_add_u64 v[70:71], v[86:87], 2, s[54:55]
	v_mul_lo_u32 v16, v183, s52
	v_mul_lo_u32 v92, v182, s53
	v_mad_u64_u32 v[86:87], s[2:3], v182, s52, 0
	v_add3_u32 v87, v87, v92, v16
	v_cndmask_b32_e64 v16, 0, 1, s[56:57]
	v_lshl_add_u64 v[86:87], v[86:87], 1, v[74:75]
	v_cmp_ne_u32_e64 s[2:3], 1, v16
	s_andn2_b64 vcc, exec, s[56:57]
	global_store_dwordx4 v[86:87], v[82:85], off nt
	s_cbranch_vccnz .LBB0_2680
	v_readlane_b32 s4, v255, 22
	s_lshl_b32 s4, s4, s47
	v_readlane_b32 s5, v255, 23
	v_add_u32_e32 v82, s4, v247
	v_ashrrev_i32_e32 v83, 31, v82
	v_lshlrev_b64 v[82:83], 9, v[82:83]
	v_lshl_add_u64 v[82:83], v[70:71], 0, v[82:83]
	global_store_dwordx4 v[82:83], v[62:65], off nt
	global_store_dwordx4 v[82:83], v[58:61], off offset:16 nt

;   template <int CAT>
;   __device__ __forceinline__ void slot(const f32x4 (&acc)[2][2][4][2], int bj, int r00, int p0, bool sunit, int fq, int c0, bf16_t* bdst, int bstride, float* fdst,
;                                        float scale) const {
;     ...
;           u32x4 w;
; #pragma unroll
;           for (int e = 0; e < 4; ++e) w[e] = cvt_pk_bf16(v[2 * e] * scale, v[2 * e + 1] * scale);
;           size_t brow = (size_t)r;
;           if (fdst && sunit) brow = (size_t)(l * 16 + (sr >> 5)) * 2080 + 2048 + (sr & 31);
;           *(u32x4*)(bdst + brow * bstride + c0) = w;
;           if (fdst) {
;             float* fp = fdst + ((size_t)(sunit ? l * MS + sr : l * MP + r)) * 128 + c0;
;             *(f32x4*)fp = (f32x4){v[0], v[1], v[2], v[3]};
;             *(f32x4*)(fp + 4) = (f32x4){v[4], v[5], v[6], v[7]};
;           }
.LBB0_2684:
	v_mul_lo_u32 v16, v181, s52
	v_mul_lo_u32 v67, v180, s53
	v_mad_u64_u32 v[62:63], s[4:5], v180, s52, 0
	v_add3_u32 v63, v63, v67, v16
	v_lshl_add_u64 v[62:63], v[62:63], 1, v[74:75]
	s_and_b64 vcc, exec, s[2:3]
	global_store_dwordx4 v[62:63], v[58:61], off nt
	s_cbranch_vccnz .LBB0_2686
	v_readlane_b32 s4, v255, 22
	s_lshl_b32 s4, s4, s47
	v_readlane_b32 s5, v255, 23
	v_add_u32_e32 v58, s4, v187
	v_ashrrev_i32_e32 v59, 31, v58
	v_lshlrev_b64 v[58:59], 9, v[58:59]
	v_lshl_add_u64 v[58:59], v[70:71], 0, v[58:59]
	global_store_dwordx4 v[58:59], v[54:57], off nt
	global_store_dwordx4 v[58:59], v[50:53], off offset:16 nt

;   template <int CAT>
;   __device__ __forceinline__ void slot(const f32x4 (&acc)[2][2][4][2], int bj, int r00, int p0, bool sunit, int fq, int c0, bf16_t* bdst, int bstride, float* fdst,
;                                        float scale) const {
;     ...
;           u32x4 w;
; #pragma unroll
;           for (int e = 0; e < 4; ++e) w[e] = cvt_pk_bf16(v[2 * e] * scale, v[2 * e + 1] * scale);
;           size_t brow = (size_t)r;
;           if (fdst && sunit) brow = (size_t)(l * 16 + (sr >> 5)) * 2080 + 2048 + (sr & 31);
;           *(u32x4*)(bdst + brow * bstride + c0) = w;
;           if (fdst) {
;             float* fp = fdst + ((size_t)(sunit ? l * MS + sr : l * MP + r)) * 128 + c0;
;             *(f32x4*)fp = (f32x4){v[0], v[1], v[2], v[3]};
;             *(f32x4*)(fp + 4) = (f32x4){v[4], v[5], v[6], v[7]};
;           }
.LBB0_2695:
	v_mul_lo_u32 v16, v179, s52
	v_mul_lo_u32 v51, v178, s53
	v_mad_u64_u32 v[88:89], s[14:15], v178, s52, 0
	v_add3_u32 v89, v89, v51, v16
	v_lshl_add_u64 v[88:89], v[88:89], 1, v[74:75]
	s_and_b64 vcc, exec, s[2:3]
	global_store_dwordx4 v[88:89], v[66:69], off nt
	s_cbranch_vccnz .LBB0_2697
	v_readlane_b32 s14, v255, 22
	s_lshl_b32 s14, s14, s47
	v_readlane_b32 s15, v255, 23
	v_add_u32_e32 v66, s14, v197
	v_ashrrev_i32_e32 v67, 31, v66
	v_lshlrev_b64 v[66:67], 9, v[66:67]
	v_lshl_add_u64 v[66:67], v[70:71], 0, v[66:67]
	global_store_dwordx4 v[66:67], v[46:49], off nt
	global_store_dwordx4 v[66:67], v[42:45], off offset:16 nt

;   template <int CAT>
;   __device__ __forceinline__ void slot(const f32x4 (&acc)[2][2][4][2], int bj, int r00, int p0, bool sunit, int fq, int c0, bf16_t* bdst, int bstride, float* fdst,
;                                        float scale) const {
;     ...
;           u32x4 w;
; #pragma unroll
;           for (int e = 0; e < 4; ++e) w[e] = cvt_pk_bf16(v[2 * e] * scale, v[2 * e + 1] * scale);
;           size_t brow = (size_t)r;
;           if (fdst && sunit) brow = (size_t)(l * 16 + (sr >> 5)) * 2080 + 2048 + (sr & 31);
;           *(u32x4*)(bdst + brow * bstride + c0) = w;
;           if (fdst) {
;             float* fp = fdst + ((size_t)(sunit ? l * MS + sr : l * MP + r)) * 128 + c0;
;             *(f32x4*)fp = (f32x4){v[0], v[1], v[2], v[3]};
;             *(f32x4*)(fp + 4) = (f32x4){v[4], v[5], v[6], v[7]};
;           }
.LBB0_2701:
	v_mul_lo_u32 v16, v175, s52
	v_mul_lo_u32 v48, v174, s53
	v_mad_u64_u32 v[46:47], s[14:15], v174, s52, 0
	v_add3_u32 v47, v47, v48, v16
	v_lshl_add_u64 v[46:47], v[46:47], 1, v[74:75]
	s_and_b64 vcc, exec, s[2:3]
	global_store_dwordx4 v[46:47], v[42:45], off nt
	s_cbranch_vccnz .LBB0_2703
	v_readlane_b32 s14, v255, 22
	s_lshl_b32 s14, s14, s47
	v_readlane_b32 s15, v255, 23
	v_add_u32_e32 v42, s14, v245
	v_ashrrev_i32_e32 v43, 31, v42
	v_lshlrev_b64 v[42:43], 9, v[42:43]
	v_lshl_add_u64 v[42:43], v[70:71], 0, v[42:43]
	global_store_dwordx4 v[42:43], v[38:41], off nt
	global_store_dwordx4 v[42:43], v[34:37], off offset:16 nt

;   template <int CAT>
;   __device__ __forceinline__ void slot(const f32x4 (&acc)[2][2][4][2], int bj, int r00, int p0, bool sunit, int fq, int c0, bf16_t* bdst, int bstride, float* fdst,
;                                        float scale) const {
;     ...
;           u32x4 w;
; #pragma unroll
;           for (int e = 0; e < 4; ++e) w[e] = cvt_pk_bf16(v[2 * e] * scale, v[2 * e + 1] * scale);
;           size_t brow = (size_t)r;
;           if (fdst && sunit) brow = (size_t)(l * 16 + (sr >> 5)) * 2080 + 2048 + (sr & 31);
;           *(u32x4*)(bdst + brow * bstride + c0) = w;
;           if (fdst) {
;             float* fp = fdst + ((size_t)(sunit ? l * MS + sr : l * MP + r)) * 128 + c0;
;             *(f32x4*)fp = (f32x4){v[0], v[1], v[2], v[3]};
;             *(f32x4*)(fp + 4) = (f32x4){v[4], v[5], v[6], v[7]};
;           }
.LBB0_2709:
	v_mul_lo_u32 v16, v173, s52
	s_waitcnt vmcnt(1)
	v_mul_lo_u32 v42, v172, s53
	v_mad_u64_u32 v[38:39], s[14:15], v172, s52, 0
	v_add3_u32 v39, v39, v42, v16
	v_lshl_add_u64 v[38:39], v[38:39], 1, v[74:75]
	s_and_b64 vcc, exec, s[2:3]
	global_store_dwordx4 v[38:39], v[50:53], off nt
	s_cbranch_vccnz .LBB0_2711
	v_readlane_b32 s14, v255, 22
	s_lshl_b32 s14, s14, s47
	v_readlane_b32 s15, v255, 23
	v_add_u32_e32 v38, s14, v185
	v_ashrrev_i32_e32 v39, 31, v38
	v_lshlrev_b64 v[38:39], 9, v[38:39]
	v_lshl_add_u64 v[38:39], v[70:71], 0, v[38:39]
	global_store_dwordx4 v[38:39], v[30:33], off nt
	global_store_dwordx4 v[38:39], v[26:29], off offset:16 nt

;   template <int CAT>
;   __device__ __forceinline__ void slot(const f32x4 (&acc)[2][2][4][2], int bj, int r00, int p0, bool sunit, int fq, int c0, bf16_t* bdst, int bstride, float* fdst,
;                                        float scale) const {
;     ...
;           u32x4 w;
; #pragma unroll
;           for (int e = 0; e < 4; ++e) w[e] = cvt_pk_bf16(v[2 * e] * scale, v[2 * e + 1] * scale);
;           size_t brow = (size_t)r;
;           if (fdst && sunit) brow = (size_t)(l * 16 + (sr >> 5)) * 2080 + 2048 + (sr & 31);
;           *(u32x4*)(bdst + brow * bstride + c0) = w;
;           if (fdst) {
;             float* fp = fdst + ((size_t)(sunit ? l * MS + sr : l * MP + r)) * 128 + c0;
;             *(f32x4*)fp = (f32x4){v[0], v[1], v[2], v[3]};
;             *(f32x4*)(fp + 4) = (f32x4){v[4], v[5], v[6], v[7]};
;           }
.LBB0_2715:
	v_mul_lo_u32 v16, v171, s52
	v_mul_lo_u32 v35, v170, s53
	v_mad_u64_u32 v[30:31], s[14:15], v170, s52, 0
	v_add3_u32 v31, v31, v35, v16
	v_lshl_add_u64 v[30:31], v[30:31], 1, v[74:75]
	s_and_b64 vcc, exec, s[2:3]
	global_store_dwordx4 v[30:31], v[26:29], off nt
	s_cbranch_vccnz .LBB0_2717
	v_readlane_b32 s14, v255, 22
	s_lshl_b32 s14, s14, s47
	v_readlane_b32 s15, v255, 23
	v_add_u32_e32 v26, s14, v188
	v_ashrrev_i32_e32 v27, 31, v26
	v_lshlrev_b64 v[26:27], 9, v[26:27]
	v_lshl_add_u64 v[26:27], v[70:71], 0, v[26:27]
	global_store_dwordx4 v[26:27], v[22:25], off nt
	global_store_dwordx4 v[26:27], v[18:21], off offset:16 nt

;   template <int CAT>
;   __device__ __forceinline__ void slot(const f32x4 (&acc)[2][2][4][2], int bj, int r00, int p0, bool sunit, int fq, int c0, bf16_t* bdst, int bstride, float* fdst,
;                                        float scale) const {
;     ...
;           u32x4 w;
; #pragma unroll
;           for (int e = 0; e < 4; ++e) w[e] = cvt_pk_bf16(v[2 * e] * scale, v[2 * e + 1] * scale);
;           size_t brow = (size_t)r;
;           if (fdst && sunit) brow = (size_t)(l * 16 + (sr >> 5)) * 2080 + 2048 + (sr & 31);
;           *(u32x4*)(bdst + brow * bstride + c0) = w;
;           if (fdst) {
;             float* fp = fdst + ((size_t)(sunit ? l * MS + sr : l * MP + r)) * 128 + c0;
;             *(f32x4*)fp = (f32x4){v[0], v[1], v[2], v[3]};
;             *(f32x4*)(fp + 4) = (f32x4){v[4], v[5], v[6], v[7]};
;           }
.LBB0_2726:
	v_mul_lo_u32 v16, v169, s52
	v_mul_lo_u32 v19, v168, s53
	v_mad_u64_u32 v[50:51], s[4:5], v168, s52, 0
	v_add3_u32 v51, v51, v19, v16
	v_lshl_add_u64 v[50:51], v[50:51], 1, v[74:75]
	s_and_b64 vcc, exec, s[2:3]
	global_store_dwordx4 v[50:51], v[34:37], off nt
	s_cbranch_vccnz .LBB0_2728
	v_readlane_b32 s4, v255, 22
	s_lshl_b32 s4, s4, s47
	v_readlane_b32 s5, v255, 23
	v_add_u32_e32 v34, s4, v186
	v_ashrrev_i32_e32 v35, 31, v34
	v_lshlrev_b64 v[34:35], 9, v[34:35]
	v_lshl_add_u64 v[34:35], v[70:71], 0, v[34:35]
	global_store_dwordx4 v[34:35], v[12:15], off nt
	global_store_dwordx4 v[34:35], v[8:11], off offset:16 nt

;   template <int CAT>
;   __device__ __forceinline__ void slot(const f32x4 (&acc)[2][2][4][2], int bj, int r00, int p0, bool sunit, int fq, int c0, bf16_t* bdst, int bstride, float* fdst,
;                                        float scale) const {
;     ...
;           u32x4 w;
; #pragma unroll
;           for (int e = 0; e < 4; ++e) w[e] = cvt_pk_bf16(v[2 * e] * scale, v[2 * e + 1] * scale);
;           size_t brow = (size_t)r;
;           if (fdst && sunit) brow = (size_t)(l * 16 + (sr >> 5)) * 2080 + 2048 + (sr & 31);
;           *(u32x4*)(bdst + brow * bstride + c0) = w;
;           if (fdst) {
;             float* fp = fdst + ((size_t)(sunit ? l * MS + sr : l * MP + r)) * 128 + c0;
;             *(f32x4*)fp = (f32x4){v[0], v[1], v[2], v[3]};
;             *(f32x4*)(fp + 4) = (f32x4){v[4], v[5], v[6], v[7]};
;           }
.LBB0_2732:
	v_mul_lo_u32 v14, v167, s52
	v_mul_lo_u32 v15, v166, s53
	v_mad_u64_u32 v[12:13], s[0:1], v166, s52, 0
	v_add3_u32 v13, v13, v15, v14
	v_lshl_add_u64 v[12:13], v[12:13], 1, v[74:75]
	s_and_b64 vcc, exec, s[2:3]
	global_store_dwordx4 v[12:13], v[8:11], off nt
	s_cbranch_vccnz .LBB0_2361
	v_readlane_b32 s0, v255, 22
	s_lshl_b32 s0, s0, s47
	v_readlane_b32 s1, v255, 23
	v_add_u32_e32 v8, s0, v184
	v_ashrrev_i32_e32 v9, 31, v8
	v_lshlrev_b64 v[8:9], 9, v[8:9]
	v_lshl_add_u64 v[8:9], v[70:71], 0, v[8:9]
	global_store_dwordx4 v[8:9], v[4:7], off nt
	global_store_dwordx4 v[8:9], v[0:3], off offset:16 nt
	s_branch .LBB0_2361

; #define PG8_STAGE(bufoff, gbase, voff) do { _Pragma("unroll") for (int _i = 0; _i < 2; ++_i) \
;     __builtin_amdgcn_global_load_lds((const unsigned*)((const char*)(gbase) + (voff)[_i]), (LAS unsigned*)(lds + (bufoff) + ldsw + _i * 8192), 16, 0, 0); } while (0)
; #define PG8_LDA(dst, b, h) do { _Pragma("unroll") for (int m = 0; m < 4; ++m) _Pragma("unroll") for (int k = 0; k < 2; ++k) dst[m][k] = *(const LAS bf16x8*)(lds + PG8_SA(b, h) + aoff + m * 2048 + k * 1024); } while (0)
; #define PG8_LDB(dst, b, h) do { _Pragma("unroll") for (int n = 0; n < 2; ++n) _Pragma("unroll") for (int k = 0; k < 2; ++k) dst[n][k] = *(const LAS bf16x8*)(lds + PG8_SB(b, h) + boff + n * 2048 + k * 1024); } while (0)
; #define PG8_MMA(ai, bj, At, Bt) do { __builtin_amdgcn_s_setprio(1); _Pragma("unroll") for (int m = 0; m < 4; ++m) _Pragma("unroll") for (int n = 0; n < 2; ++n) _Pragma("unroll") for (int k = 0; k < 2; ++k) \
;     acc[ai][bj][m][n] = __builtin_amdgcn_mfma_f32_16x16x32_bf16(Bt[n][k], At[m][k], acc[ai][bj][m][n], 0, 0, 0); __builtin_amdgcn_s_setprio(0); } while (0)
; #define PG8_WAIT_V(n) asm volatile("s_waitcnt vmcnt(" #n ")" ::: "memory")
; #define PG8_WAIT_L(n) asm volatile("s_waitcnt lgkmcnt(" #n ")" ::: "memory")
; #define PG8_BAR __builtin_amdgcn_s_barrier()
; #define PG8_SCHED __builtin_amdgcn_sched_barrier(0)
; template <class Epi>
; __device__ __forceinline__ void gemm_phase(LAS unsigned char* lds, const Gemm g, const StaticOrder& S, const Epi& E) {
;     ...
;       PG8_LDB(B0, 0, 0); PG8_SCHED; PG8_LDA(At, 0, 0); PG8_STAGE(PG8_SA(1, 1), a1 + hstepA, voffA);
;       PG8_WAIT_L(8); PG8_BAR; PG8_WAIT_L(0); PG8_MMA(0, 0, At, B0); PG8_BAR; PG8_SCHED;
;       PG8_LDB(B1, 0, 1); PG8_STAGE(PG8_SB(0, 0), b2, voffB);
;       PG8_BAR; PG8_WAIT_L(0); PG8_MMA(0, 1, At, B1); PG8_BAR;
;       PG8_LDA(At, 0, 1); PG8_STAGE(PG8_SA(0, 0), a2, voffA);
;       PG8_BAR; PG8_WAIT_L(0); PG8_MMA(1, 0, At, B0); PG8_BAR; PG8_SCHED;
;       PG8_STAGE(PG8_SB(0, 1), b2 + hstepB, voffB);
;       PG8_WAIT_V(6); PG8_BAR; PG8_MMA(1, 1, At, B1); PG8_BAR;
.LBB0_3803:
	s_add_u32 s20, s14, 0xfffc0080
	s_addc_u32 s21, s15, -1
	s_add_i32 s46, 0, 0x10000
	v_add_u32_e32 v145, s46, v143
	ds_read_b128 v[146:149], v145
	ds_read_b128 v[150:153], v145 offset:1024
	ds_read_b128 v[154:157], v145 offset:2048
	ds_read_b128 v[158:161], v145 offset:3072
	s_cmp_eq_u32 s45, 12
	s_cselect_b32 s23, s5, s21
	s_cselect_b32 s22, s41, s20
	s_cselect_b32 s21, s3, s44
	s_cselect_b32 s20, s42, s43
	v_lshl_add_u64 v[194:195], s[14:15], 0, v[138:139]
	s_add_i32 m0, s30, 0xc000
	ds_read_b128 v[162:165], v144
	ds_read_b128 v[166:169], v144 offset:1024
	ds_read_b128 v[170:173], v144 offset:2048
	ds_read_b128 v[174:177], v144 offset:3072
	ds_read_b128 v[178:181], v144 offset:4096
	ds_read_b128 v[182:185], v144 offset:5120
	ds_read_b128 v[186:189], v144 offset:6144
	ds_read_b128 v[190:193], v144 offset:7168
	global_load_lds_dwordx4 v[194:195], off
	v_lshl_add_u64 v[194:195], s[14:15], 0, v[140:141]
	s_add_i32 m0, s30, 0xe000
	s_nop 0
	global_load_lds_dwordx4 v[194:195], off
	s_waitcnt lgkmcnt(8)
	s_barrier
	s_waitcnt lgkmcnt(0)
	s_setprio 1
	s_waitcnt lgkmcnt(0)
	v_mfma_f32_16x16x32_bf16 v[126:129], v[146:149], v[162:165], v[126:129]
	v_mfma_f32_16x16x32_bf16 v[122:125], v[154:157], v[162:165], v[122:125]
	v_mfma_f32_16x16x32_bf16 v[110:113], v[146:149], v[170:173], v[110:113]
	v_mfma_f32_16x16x32_bf16 v[106:109], v[154:157], v[170:173], v[106:109]
	v_mfma_f32_16x16x32_bf16 v[94:97], v[146:149], v[178:181], v[94:97]
	v_mfma_f32_16x16x32_bf16 v[90:93], v[154:157], v[178:181], v[90:93]
	v_mfma_f32_16x16x32_bf16 v[78:81], v[146:149], v[186:189], v[78:81]
	v_mfma_f32_16x16x32_bf16 v[74:77], v[154:157], v[186:189], v[74:77]
	v_mfma_f32_16x16x32_bf16 v[126:129], v[150:153], v[166:169], v[126:129]
	v_mfma_f32_16x16x32_bf16 v[122:125], v[158:161], v[166:169], v[122:125]
	v_mfma_f32_16x16x32_bf16 v[110:113], v[150:153], v[174:177], v[110:113]
	v_mfma_f32_16x16x32_bf16 v[106:109], v[158:161], v[174:177], v[106:109]
	v_mfma_f32_16x16x32_bf16 v[94:97], v[150:153], v[182:185], v[94:97]
	v_mfma_f32_16x16x32_bf16 v[90:93], v[158:161], v[182:185], v[90:93]
	v_mfma_f32_16x16x32_bf16 v[78:81], v[150:153], v[190:193], v[78:81]
	v_mfma_f32_16x16x32_bf16 v[74:77], v[158:161], v[190:193], v[74:77]
	s_setprio 0
	s_barrier
	s_add_i32 s48, 0, 0x14000
	s_add_i32 s46, s46, s29
	v_add_u32_e32 v145, s48, v143
	v_lshl_add_u64 v[210:211], s[20:21], 0, v[134:135]
	s_mov_b32 m0, s46
	ds_read_b128 v[194:197], v145
	ds_read_b128 v[198:201], v145 offset:1024
	ds_read_b128 v[202:205], v145 offset:2048
	ds_read_b128 v[206:209], v145 offset:3072
	global_load_lds_dwordx4 v[210:211], off
	v_lshl_add_u64 v[212:213], s[20:21], 0, v[130:131]
	s_add_i32 m0, s46, 0x2000
	s_nop 0
	global_load_lds_dwordx4 v[212:213], off
	s_barrier
	s_waitcnt lgkmcnt(0)
	s_setprio 1
	s_waitcnt lgkmcnt(0)
	v_mfma_f32_16x16x32_bf16 v[118:121], v[194:197], v[162:165], v[118:121]
	v_mfma_f32_16x16x32_bf16 v[114:117], v[202:205], v[162:165], v[114:117]
	v_mfma_f32_16x16x32_bf16 v[102:105], v[194:197], v[170:173], v[102:105]
	v_mfma_f32_16x16x32_bf16 v[98:101], v[202:205], v[170:173], v[98:101]
	v_mfma_f32_16x16x32_bf16 v[86:89], v[194:197], v[178:181], v[86:89]
	v_mfma_f32_16x16x32_bf16 v[82:85], v[202:205], v[178:181], v[82:85]
	v_mfma_f32_16x16x32_bf16 v[70:73], v[194:197], v[186:189], v[70:73]
	v_mfma_f32_16x16x32_bf16 v[66:69], v[202:205], v[186:189], v[66:69]
	v_mfma_f32_16x16x32_bf16 v[118:121], v[198:201], v[166:169], v[118:121]
	v_mfma_f32_16x16x32_bf16 v[114:117], v[206:209], v[166:169], v[114:117]
	v_mfma_f32_16x16x32_bf16 v[102:105], v[198:201], v[174:177], v[102:105]
	v_mfma_f32_16x16x32_bf16 v[98:101], v[206:209], v[174:177], v[98:101]
	v_mfma_f32_16x16x32_bf16 v[86:89], v[198:201], v[182:185], v[86:89]
	v_mfma_f32_16x16x32_bf16 v[82:85], v[206:209], v[182:185], v[82:85]
	v_mfma_f32_16x16x32_bf16 v[70:73], v[198:201], v[190:193], v[70:73]
	v_mfma_f32_16x16x32_bf16 v[66:69], v[206:209], v[190:193], v[66:69]
	s_setprio 0
	s_mov_b32 m0, s30
	v_lshl_add_u64 v[214:215], s[22:23], 0, v[136:137]
	s_barrier
	ds_read_b128 v[162:165], v144 offset:16384
	ds_read_b128 v[166:169], v144 offset:17408
	ds_read_b128 v[170:173], v144 offset:18432
	ds_read_b128 v[174:177], v144 offset:19456
	ds_read_b128 v[178:181], v144 offset:20480
	ds_read_b128 v[182:185], v144 offset:21504
	ds_read_b128 v[186:189], v144 offset:22528
	ds_read_b128 v[190:193], v144 offset:23552
	global_load_lds_dwordx4 v[214:215], off
	v_lshl_add_u64 v[216:217], s[22:23], 0, v[132:133]
	s_mov_b32 m0, s31
	s_nop 0
	global_load_lds_dwordx4 v[216:217], off
	s_barrier
	s_waitcnt lgkmcnt(0)
	s_setprio 1
	s_waitcnt lgkmcnt(0)
	v_mfma_f32_16x16x32_bf16 v[62:65], v[146:149], v[162:165], v[62:65]
	v_mfma_f32_16x16x32_bf16 v[58:61], v[154:157], v[162:165], v[58:61]
	v_mfma_f32_16x16x32_bf16 v[46:49], v[146:149], v[170:173], v[46:49]
	v_mfma_f32_16x16x32_bf16 v[42:45], v[154:157], v[170:173], v[42:45]
	v_mfma_f32_16x16x32_bf16 v[30:33], v[146:149], v[178:181], v[30:33]
	v_mfma_f32_16x16x32_bf16 v[26:29], v[154:157], v[178:181], v[26:29]
	v_mfma_f32_16x16x32_bf16 v[12:15], v[146:149], v[186:189], v[12:15]
	v_mfma_f32_16x16x32_bf16 v[8:11], v[154:157], v[186:189], v[8:11]
	v_mfma_f32_16x16x32_bf16 v[62:65], v[150:153], v[166:169], v[62:65]
	v_mfma_f32_16x16x32_bf16 v[58:61], v[158:161], v[166:169], v[58:61]
	v_mfma_f32_16x16x32_bf16 v[46:49], v[150:153], v[174:177], v[46:49]
	v_mfma_f32_16x16x32_bf16 v[42:45], v[158:161], v[174:177], v[42:45]
	v_mfma_f32_16x16x32_bf16 v[30:33], v[150:153], v[182:185], v[30:33]
	v_mfma_f32_16x16x32_bf16 v[26:29], v[158:161], v[182:185], v[26:29]
	v_mfma_f32_16x16x32_bf16 v[12:15], v[150:153], v[190:193], v[12:15]
	v_mfma_f32_16x16x32_bf16 v[8:11], v[158:161], v[190:193], v[8:11]
	s_setprio 0
	s_barrier
; #define PG8_STAGE(bufoff, gbase, voff) do { _Pragma("unroll") for (int _i = 0; _i < 2; ++_i) \
;     __builtin_amdgcn_global_load_lds((const unsigned*)((const char*)(gbase) + (voff)[_i]), (LAS unsigned*)(lds + (bufoff) + ldsw + _i * 8192), 16, 0, 0); } while (0)
; #define PG8_LDA(dst, b, h) do { _Pragma("unroll") for (int m = 0; m < 4; ++m) _Pragma("unroll") for (int k = 0; k < 2; ++k) dst[m][k] = *(const LAS bf16x8*)(lds + PG8_SA(b, h) + aoff + m * 2048 + k * 1024); } while (0)
; #define PG8_LDB(dst, b, h) do { _Pragma("unroll") for (int n = 0; n < 2; ++n) _Pragma("unroll") for (int k = 0; k < 2; ++k) dst[n][k] = *(const LAS bf16x8*)(lds + PG8_SB(b, h) + boff + n * 2048 + k * 1024); } while (0)
; #define PG8_MMA(ai, bj, At, Bt) do { __builtin_amdgcn_s_setprio(1); _Pragma("unroll") for (int m = 0; m < 4; ++m) _Pragma("unroll") for (int n = 0; n < 2; ++n) _Pragma("unroll") for (int k = 0; k < 2; ++k) \
;     acc[ai][bj][m][n] = __builtin_amdgcn_mfma_f32_16x16x32_bf16(Bt[n][k], At[m][k], acc[ai][bj][m][n], 0, 0, 0); __builtin_amdgcn_s_setprio(0); } while (0)
; #define PG8_WAIT_V(n) asm volatile("s_waitcnt vmcnt(" #n ")" ::: "memory")
; #define PG8_WAIT_L(n) asm volatile("s_waitcnt lgkmcnt(" #n ")" ::: "memory")
; #define PG8_BAR __builtin_amdgcn_s_barrier()
; #define PG8_SCHED __builtin_amdgcn_sched_barrier(0)
; template <class Epi>
; __device__ __forceinline__ void gemm_phase(LAS unsigned char* lds, const Gemm g, const StaticOrder& S, const Epi& E) {
;     ...
;       PG8_WAIT_V(6); PG8_BAR; PG8_MMA(1, 1, At, B1); PG8_BAR;
;       PG8_LDB(B0, 1, 0); PG8_SCHED; PG8_LDA(At, 1, 0); PG8_STAGE(PG8_SA(0, 1), a2 + hstepA, voffA);
;       PG8_WAIT_L(8); PG8_BAR; PG8_WAIT_L(0); PG8_MMA(0, 0, At, B0); PG8_BAR; PG8_SCHED;
;       PG8_LDB(B1, 1, 1); PG8_STAGE(PG8_SB(1, 0), b3, voffB);
;       PG8_BAR; PG8_WAIT_L(0); PG8_MMA(0, 1, At, B1); PG8_BAR;
;       PG8_LDA(At, 1, 1); PG8_STAGE(PG8_SA(1, 0), a3, voffA);
;       PG8_BAR; PG8_WAIT_L(0); PG8_MMA(1, 0, At, B0); PG8_BAR; PG8_SCHED;
	s_add_u32 s46, s20, 0x40000
	s_addc_u32 s47, s21, 0
	s_add_i32 s48, s48, s29
	v_lshl_add_u64 v[146:147], s[46:47], 0, v[134:135]
	s_mov_b32 m0, s48
	s_nop 0
	global_load_lds_dwordx4 v[146:147], off
	v_lshl_add_u64 v[146:147], s[46:47], 0, v[130:131]
	s_add_i32 m0, s48, 0x2000
	s_nop 0
	global_load_lds_dwordx4 v[146:147], off
	s_waitcnt vmcnt(6)
	s_barrier
	s_setprio 1
	v_mfma_f32_16x16x32_bf16 v[54:57], v[194:197], v[162:165], v[54:57]
	v_mfma_f32_16x16x32_bf16 v[50:53], v[202:205], v[162:165], v[50:53]
	v_mfma_f32_16x16x32_bf16 v[38:41], v[194:197], v[170:173], v[38:41]
	v_mfma_f32_16x16x32_bf16 v[34:37], v[202:205], v[170:173], v[34:37]
	v_mfma_f32_16x16x32_bf16 v[22:25], v[194:197], v[178:181], v[22:25]
	v_mfma_f32_16x16x32_bf16 v[18:21], v[202:205], v[178:181], v[18:21]
	v_mfma_f32_16x16x32_bf16 v[4:7], v[194:197], v[186:189], v[4:7]
	v_mfma_f32_16x16x32_bf16 v[0:3], v[202:205], v[186:189], v[0:3]
	v_mfma_f32_16x16x32_bf16 v[54:57], v[198:201], v[166:169], v[54:57]
	v_mfma_f32_16x16x32_bf16 v[50:53], v[206:209], v[166:169], v[50:53]
	v_mfma_f32_16x16x32_bf16 v[38:41], v[198:201], v[174:177], v[38:41]
	v_mfma_f32_16x16x32_bf16 v[34:37], v[206:209], v[174:177], v[34:37]
	v_mfma_f32_16x16x32_bf16 v[22:25], v[198:201], v[182:185], v[22:25]
	v_mfma_f32_16x16x32_bf16 v[18:21], v[206:209], v[182:185], v[18:21]
	v_mfma_f32_16x16x32_bf16 v[4:7], v[198:201], v[190:193], v[4:7]
	v_mfma_f32_16x16x32_bf16 v[0:3], v[206:209], v[190:193], v[0:3]
	s_setprio 0
	s_add_i32 s46, 0, 0x18000
	v_add_u32_e32 v145, s46, v143
	s_barrier
	ds_read_b128 v[146:149], v145
	ds_read_b128 v[150:153], v145 offset:1024
	ds_read_b128 v[154:157], v145 offset:2048
	ds_read_b128 v[158:161], v145 offset:3072
	s_add_u32 s22, s22, 0x40000
	s_addc_u32 s23, s23, 0
	s_mov_b32 m0, s34
	v_lshl_add_u64 v[194:195], s[22:23], 0, v[136:137]
	ds_read_b128 v[162:165], v144 offset:32768
	ds_read_b128 v[166:169], v144 offset:33792
	ds_read_b128 v[170:173], v144 offset:34816
	ds_read_b128 v[174:177], v144 offset:35840
	ds_read_b128 v[178:181], v144 offset:36864
	ds_read_b128 v[182:185], v144 offset:37888
	ds_read_b128 v[186:189], v144 offset:38912
	ds_read_b128 v[190:193], v144 offset:39936
	global_load_lds_dwordx4 v[194:195], off
	v_lshl_add_u64 v[194:195], s[22:23], 0, v[132:133]
	s_mov_b32 m0, s35
	s_nop 0
	global_load_lds_dwordx4 v[194:195], off
	s_waitcnt lgkmcnt(8)
	s_barrier
	s_waitcnt lgkmcnt(0)
	s_setprio 1
	s_waitcnt lgkmcnt(0)
	v_mfma_f32_16x16x32_bf16 v[126:129], v[146:149], v[162:165], v[126:129]
	v_mfma_f32_16x16x32_bf16 v[122:125], v[154:157], v[162:165], v[122:125]
	v_mfma_f32_16x16x32_bf16 v[110:113], v[146:149], v[170:173], v[110:113]
	v_mfma_f32_16x16x32_bf16 v[106:109], v[154:157], v[170:173], v[106:109]
	v_mfma_f32_16x16x32_bf16 v[94:97], v[146:149], v[178:181], v[94:97]
	v_mfma_f32_16x16x32_bf16 v[90:93], v[154:157], v[178:181], v[90:93]
	v_mfma_f32_16x16x32_bf16 v[78:81], v[146:149], v[186:189], v[78:81]
	v_mfma_f32_16x16x32_bf16 v[74:77], v[154:157], v[186:189], v[74:77]
	v_mfma_f32_16x16x32_bf16 v[126:129], v[150:153], v[166:169], v[126:129]
	v_mfma_f32_16x16x32_bf16 v[122:125], v[158:161], v[166:169], v[122:125]
	v_mfma_f32_16x16x32_bf16 v[110:113], v[150:153], v[174:177], v[110:113]
	v_mfma_f32_16x16x32_bf16 v[106:109], v[158:161], v[174:177], v[106:109]
	v_mfma_f32_16x16x32_bf16 v[94:97], v[150:153], v[182:185], v[94:97]
	v_mfma_f32_16x16x32_bf16 v[90:93], v[158:161], v[182:185], v[90:93]
	v_mfma_f32_16x16x32_bf16 v[78:81], v[150:153], v[190:193], v[78:81]
	v_mfma_f32_16x16x32_bf16 v[74:77], v[158:161], v[190:193], v[74:77]
	s_setprio 0
	s_barrier
	s_add_i32 s22, 0, 0x1c000
	s_add_i32 s23, s46, s29
	v_add_u32_e32 v145, s22, v143
	v_lshl_add_u64 v[210:211], v[210:211], 0, s[16:17]
	s_mov_b32 m0, s23
	ds_read_b128 v[194:197], v145
	ds_read_b128 v[198:201], v145 offset:1024
	ds_read_b128 v[202:205], v145 offset:2048
	ds_read_b128 v[206:209], v145 offset:3072
	global_load_lds_dwordx4 v[210:211], off
	v_lshl_add_u64 v[210:211], v[212:213], 0, s[16:17]
	s_add_i32 m0, s23, 0x2000
	s_nop 0
	global_load_lds_dwordx4 v[210:211], off
	s_barrier
	s_waitcnt lgkmcnt(0)
	s_setprio 1
	s_waitcnt lgkmcnt(0)
	v_mfma_f32_16x16x32_bf16 v[118:121], v[194:197], v[162:165], v[118:121]
	v_mfma_f32_16x16x32_bf16 v[114:117], v[202:205], v[162:165], v[114:117]
	v_mfma_f32_16x16x32_bf16 v[102:105], v[194:197], v[170:173], v[102:105]
	v_mfma_f32_16x16x32_bf16 v[98:101], v[202:205], v[170:173], v[98:101]
	v_mfma_f32_16x16x32_bf16 v[86:89], v[194:197], v[178:181], v[86:89]
	v_mfma_f32_16x16x32_bf16 v[82:85], v[202:205], v[178:181], v[82:85]
	v_mfma_f32_16x16x32_bf16 v[70:73], v[194:197], v[186:189], v[70:73]
	v_mfma_f32_16x16x32_bf16 v[66:69], v[202:205], v[186:189], v[66:69]
	v_mfma_f32_16x16x32_bf16 v[118:121], v[198:201], v[166:169], v[118:121]
	v_mfma_f32_16x16x32_bf16 v[114:117], v[206:209], v[166:169], v[114:117]
	v_mfma_f32_16x16x32_bf16 v[102:105], v[198:201], v[174:177], v[102:105]
	v_mfma_f32_16x16x32_bf16 v[98:101], v[206:209], v[174:177], v[98:101]
	v_mfma_f32_16x16x32_bf16 v[86:89], v[198:201], v[182:185], v[86:89]
	v_mfma_f32_16x16x32_bf16 v[82:85], v[206:209], v[182:185], v[82:85]
	v_mfma_f32_16x16x32_bf16 v[70:73], v[198:201], v[190:193], v[70:73]
	v_mfma_f32_16x16x32_bf16 v[66:69], v[206:209], v[190:193], v[66:69]
	s_setprio 0
	s_mov_b32 m0, s36
	v_lshl_add_u64 v[210:211], v[214:215], 0, s[16:17]
	s_barrier
	ds_read_b128 v[162:165], v144 offset:49152
	ds_read_b128 v[166:169], v144 offset:50176
	ds_read_b128 v[170:173], v144 offset:51200
	ds_read_b128 v[174:177], v144 offset:52224
	ds_read_b128 v[178:181], v144 offset:53248
	ds_read_b128 v[182:185], v144 offset:54272
	ds_read_b128 v[186:189], v144 offset:55296
	ds_read_b128 v[190:193], v144 offset:56320
	global_load_lds_dwordx4 v[210:211], off
	v_lshl_add_u64 v[210:211], v[216:217], 0, s[16:17]
	s_mov_b32 m0, s37
	s_nop 0
	global_load_lds_dwordx4 v[210:211], off
	s_barrier
; #define PG8_STAGE(bufoff, gbase, voff) do { _Pragma("unroll") for (int _i = 0; _i < 2; ++_i) \
;     __builtin_amdgcn_global_load_lds((const unsigned*)((const char*)(gbase) + (voff)[_i]), (LAS unsigned*)(lds + (bufoff) + ldsw + _i * 8192), 16, 0, 0); } while (0)
; #define PG8_MMA(ai, bj, At, Bt) do { __builtin_amdgcn_s_setprio(1); _Pragma("unroll") for (int m = 0; m < 4; ++m) _Pragma("unroll") for (int n = 0; n < 2; ++n) _Pragma("unroll") for (int k = 0; k < 2; ++k) \
;     acc[ai][bj][m][n] = __builtin_amdgcn_mfma_f32_16x16x32_bf16(Bt[n][k], At[m][k], acc[ai][bj][m][n], 0, 0, 0); __builtin_amdgcn_s_setprio(0); } while (0)
; #define PG8_WAIT_V(n) asm volatile("s_waitcnt vmcnt(" #n ")" ::: "memory")
; #define PG8_WAIT_L(n) asm volatile("s_waitcnt lgkmcnt(" #n ")" ::: "memory")
; #define PG8_BAR __builtin_amdgcn_s_barrier()
; #define PG8_SCHED __builtin_amdgcn_sched_barrier(0)
; template <class Epi>
; __device__ __forceinline__ void gemm_phase(LAS unsigned char* lds, const Gemm g, const StaticOrder& S, const Epi& E) {
;     ...
;       PG8_BAR; PG8_WAIT_L(0); PG8_MMA(1, 0, At, B0); PG8_BAR; PG8_SCHED;
;       PG8_STAGE(PG8_SB(1, 1), b3 + hstepB, voffB);
;       PG8_WAIT_V(6); PG8_BAR; PG8_MMA(1, 1, At, B1); PG8_BAR;
;   __device__ __forceinline__ void operator()(const f32x4 (&acc)[2][2][4][2], const Unit& u, int wr, int wc, int fr, int fq) const {
; #pragma unroll
;     for (int ai = 0; ai < 2; ++ai)
; #pragma unroll
;       for (int m = 0; m < 4; ++m) {
;         const int r = u.pm * 256 + ai * 128 + wr * 64 + m * 16 + fr;
; #pragma unroll
;         for (int bj = 0; bj < 2; ++bj) {
;           float v[8];
; #pragma unroll
;           for (int e = 0; e < 4; ++e) {
;             const float a = fmaxf(acc[ai][bj][m][0][e], 0.f), b = fmaxf(acc[ai][bj][m][1][e], 0.f);
;             v[e] = a * a; v[4 + e] = b * b;
;           }
;           u32x4 w;
; #pragma unroll
;           for (int e = 0; e < 4; ++e) w[e] = cvt_pk_bf16(v[2 * e], v[2 * e + 1]);
;           *(u32x4*)(H + (size_t)r * LDH + u.pn * 256 + bj * 128 + wc * 32 + 8 * fq) = w;
;         }
	s_waitcnt lgkmcnt(0)
	s_setprio 1
	s_waitcnt lgkmcnt(0)
	v_mfma_f32_16x16x32_bf16 v[62:65], v[146:149], v[162:165], v[62:65]
	v_mfma_f32_16x16x32_bf16 v[58:61], v[154:157], v[162:165], v[58:61]
	v_mfma_f32_16x16x32_bf16 v[46:49], v[146:149], v[170:173], v[46:49]
	v_mfma_f32_16x16x32_bf16 v[42:45], v[154:157], v[170:173], v[42:45]
	v_mfma_f32_16x16x32_bf16 v[30:33], v[146:149], v[178:181], v[30:33]
	v_mfma_f32_16x16x32_bf16 v[26:29], v[154:157], v[178:181], v[26:29]
	v_mfma_f32_16x16x32_bf16 v[12:15], v[146:149], v[186:189], v[12:15]
	v_mfma_f32_16x16x32_bf16 v[8:11], v[154:157], v[186:189], v[8:11]
	v_mfma_f32_16x16x32_bf16 v[62:65], v[150:153], v[166:169], v[62:65]
	v_mfma_f32_16x16x32_bf16 v[58:61], v[158:161], v[166:169], v[58:61]
	v_mfma_f32_16x16x32_bf16 v[46:49], v[150:153], v[174:177], v[46:49]
	v_mfma_f32_16x16x32_bf16 v[42:45], v[158:161], v[174:177], v[42:45]
	v_mfma_f32_16x16x32_bf16 v[30:33], v[150:153], v[182:185], v[30:33]
	v_mfma_f32_16x16x32_bf16 v[26:29], v[158:161], v[182:185], v[26:29]
	v_mfma_f32_16x16x32_bf16 v[12:15], v[150:153], v[190:193], v[12:15]
	v_mfma_f32_16x16x32_bf16 v[8:11], v[158:161], v[190:193], v[8:11]
	s_setprio 0
	s_barrier
	s_add_u32 s20, s20, 0x40080
	s_addc_u32 s21, s21, 0
	s_add_i32 s22, s22, s29
	v_lshl_add_u64 v[146:147], s[20:21], 0, v[134:135]
	s_mov_b32 m0, s22
	s_nop 0
	global_load_lds_dwordx4 v[146:147], off
	v_lshl_add_u64 v[146:147], s[20:21], 0, v[130:131]
	s_add_i32 m0, s22, 0x2000
	s_nop 0
	global_load_lds_dwordx4 v[146:147], off
	s_waitcnt vmcnt(6)
	s_barrier
	s_setprio 1
	v_mfma_f32_16x16x32_bf16 v[54:57], v[194:197], v[162:165], v[54:57]
	v_mfma_f32_16x16x32_bf16 v[50:53], v[202:205], v[162:165], v[50:53]
	v_mfma_f32_16x16x32_bf16 v[38:41], v[194:197], v[170:173], v[38:41]
	v_mfma_f32_16x16x32_bf16 v[34:37], v[202:205], v[170:173], v[34:37]
	v_mfma_f32_16x16x32_bf16 v[22:25], v[194:197], v[178:181], v[22:25]
	v_mfma_f32_16x16x32_bf16 v[18:21], v[202:205], v[178:181], v[18:21]
	v_mfma_f32_16x16x32_bf16 v[4:7], v[194:197], v[186:189], v[4:7]
	v_mfma_f32_16x16x32_bf16 v[0:3], v[202:205], v[186:189], v[0:3]
	v_mfma_f32_16x16x32_bf16 v[54:57], v[198:201], v[166:169], v[54:57]
	v_mfma_f32_16x16x32_bf16 v[50:53], v[206:209], v[166:169], v[50:53]
	v_mfma_f32_16x16x32_bf16 v[38:41], v[198:201], v[174:177], v[38:41]
	v_mfma_f32_16x16x32_bf16 v[34:37], v[206:209], v[174:177], v[34:37]
	v_mfma_f32_16x16x32_bf16 v[22:25], v[198:201], v[182:185], v[22:25]
	v_mfma_f32_16x16x32_bf16 v[18:21], v[206:209], v[182:185], v[18:21]
	v_mfma_f32_16x16x32_bf16 v[4:7], v[198:201], v[190:193], v[4:7]
	v_mfma_f32_16x16x32_bf16 v[0:3], v[206:209], v[190:193], v[0:3]
	s_setprio 0
	s_add_i32 s45, s45, 2
	s_add_u32 s14, s14, 0x100
	s_addc_u32 s15, s15, 0
	s_add_u32 s43, s43, 0x100
	s_addc_u32 s44, s44, 0
	s_cmp_gt_u32 s45, 13
	s_barrier
	s_cbranch_scc0 .LBB0_3803
	v_max_f32_e32 v124, 0, v124
	v_max_f32_e32 v126, 0, v126
	v_max_f32_e32 v122, 0, v122
	v_max_f32_e32 v123, 0, v123
	v_mul_f32_e32 v146, v124, v124
	s_lshl_b32 s14, s39, 8
	v_mul_f32_e32 v126, v126, v126
	v_mul_f32_e32 v122, v122, v122
	v_max_f32_e32 v127, 0, v127
	v_mul_f32_e32 v123, v123, v123
	v_max_f32_e32 v128, 0, v128
	v_max_f32_e32 v124, 0, v129
	v_max_f32_e32 v125, 0, v125
	v_lshl_add_u32 v145, s40, 8, v142
	s_ashr_i32 s15, s14, 31
	v_mul_f32_e32 v127, v127, v127
	v_mul_f32_e32 v128, v128, v128
	v_mul_f32_e32 v129, v124, v124
	v_mul_f32_e32 v147, v125, v125
	v_cvt_pk_bf16_f32 v124, v126, v127
	v_cvt_pk_bf16_f32 v125, v128, v129
	v_cvt_pk_bf16_f32 v126, v122, v123
	v_mov_b64_e32 v[122:123], s[0:1]
	s_movk_i32 s3, 0x2080
	v_mad_i64_i32 v[128:129], s[20:21], v145, s3, v[122:123]
	s_lshl_b64 s[14:15], s[14:15], 1
	v_readlane_b32 s22, v255, 20
	v_lshl_add_u64 v[128:129], v[128:129], 0, s[14:15]
	v_readlane_b32 s23, v255, 21
	s_nop 0
	s_nop 0
	v_lshl_add_u64 v[128:129], v[128:129], 0, s[22:23]
	v_lshl_add_u64 v[128:129], v[128:129], 0, v[16:17]
	v_max_f32_e32 v114, 0, v114
	v_max_f32_e32 v115, 0, v115
	v_cvt_pk_bf16_f32 v127, v146, v147
	global_store_dwordx4 v[128:129], v[124:127], off nt
	v_max_f32_e32 v116, 0, v116
	s_nop 0
	v_mul_f32_e32 v124, v114, v114
	v_max_f32_e32 v114, v119, v119
	v_mul_f32_e32 v119, v115, v115
	v_max_f32_e32 v114, 0, v114
	v_max_f32_e32 v115, 0, v120
	v_mul_f32_e32 v120, v116, v116
	v_max_f32_e32 v118, 0, v118
	v_mul_f32_e32 v114, v114, v114
	v_mul_f32_e32 v115, v115, v115
	v_max_f32_e32 v116, 0, v121
	v_max_f32_e32 v117, 0, v117
	v_mul_f32_e32 v118, v118, v118
	v_mul_f32_e32 v116, v116, v116
	v_mul_f32_e32 v117, v117, v117
	v_cvt_pk_bf16_f32 v114, v118, v114
	v_cvt_pk_bf16_f32 v115, v115, v116
	v_max_f32_e32 v106, 0, v106
	v_max_f32_e32 v107, 0, v107
	v_max_f32_e32 v108, 0, v108
	v_cvt_pk_bf16_f32 v116, v124, v119
	v_cvt_pk_bf16_f32 v117, v120, v117
	global_store_dwordx4 v[128:129], v[114:117], off offset:256 nt
	s_nop 0
	v_max_f32_e32 v110, 0, v110
	v_mul_f32_e32 v115, v106, v106
	v_max_f32_e32 v106, v111, v111
	v_mul_f32_e32 v111, v107, v107
	v_max_f32_e32 v107, v112, v112
	v_mul_f32_e32 v112, v108, v108
	v_max_f32_e32 v106, 0, v106
	v_max_f32_e32 v107, 0, v107
	v_max_f32_e32 v108, 0, v113
	v_or_b32_e32 v114, 16, v145
	v_mul_f32_e32 v110, v110, v110
	v_mul_f32_e32 v106, v106, v106
	v_mul_f32_e32 v107, v107, v107
	v_mul_f32_e32 v108, v108, v108
	v_cvt_pk_bf16_f32 v106, v110, v106
	v_cvt_pk_bf16_f32 v107, v107, v108
	v_cvt_pk_bf16_f32 v108, v115, v111
	v_mad_i64_i32 v[110:111], s[20:21], v114, s3, v[122:123]
	s_nop 0
	v_lshl_add_u64 v[110:111], v[110:111], 0, s[14:15]
	v_max_f32_e32 v109, 0, v109
	v_lshl_add_u64 v[110:111], v[110:111], 0, s[22:23]
	s_nop 0
	v_mul_f32_e32 v109, v109, v109
	v_lshl_add_u64 v[110:111], v[110:111], 0, v[16:17]
;   __device__ __forceinline__ void operator()(const f32x4 (&acc)[2][2][4][2], const Unit& u, int wr, int wc, int fr, int fq) const {
; #pragma unroll
;     for (int ai = 0; ai < 2; ++ai)
; #pragma unroll
;       for (int m = 0; m < 4; ++m) {
;         const int r = u.pm * 256 + ai * 128 + wr * 64 + m * 16 + fr;
; #pragma unroll
;         for (int bj = 0; bj < 2; ++bj) {
;           float v[8];
; #pragma unroll
;           for (int e = 0; e < 4; ++e) {
;             const float a = fmaxf(acc[ai][bj][m][0][e], 0.f), b = fmaxf(acc[ai][bj][m][1][e], 0.f);
;             v[e] = a * a; v[4 + e] = b * b;
;           }
;           u32x4 w;
; #pragma unroll
;           for (int e = 0; e < 4; ++e) w[e] = cvt_pk_bf16(v[2 * e], v[2 * e + 1]);
;           *(u32x4*)(H + (size_t)r * LDH + u.pn * 256 + bj * 128 + wc * 32 + 8 * fq) = w;
;         }
	v_max_f32_e32 v98, 0, v98
	v_max_f32_e32 v99, 0, v99
	v_cvt_pk_bf16_f32 v109, v112, v109
	global_store_dwordx4 v[110:111], v[106:109], off nt
	v_max_f32_e32 v100, 0, v100
	s_nop 0
	v_mul_f32_e32 v106, v98, v98
	v_max_f32_e32 v98, v103, v103
	v_mul_f32_e32 v103, v99, v99
	v_max_f32_e32 v98, 0, v98
	v_max_f32_e32 v99, 0, v104
	v_mul_f32_e32 v104, v100, v100
	v_max_f32_e32 v102, 0, v102
	v_mul_f32_e32 v98, v98, v98
	v_mul_f32_e32 v99, v99, v99
	v_max_f32_e32 v100, 0, v105
	v_max_f32_e32 v101, 0, v101
	v_mul_f32_e32 v102, v102, v102
	v_mul_f32_e32 v100, v100, v100
	v_mul_f32_e32 v101, v101, v101
	v_cvt_pk_bf16_f32 v98, v102, v98
	v_cvt_pk_bf16_f32 v99, v99, v100
	v_max_f32_e32 v90, 0, v90
	v_max_f32_e32 v91, 0, v91
	v_max_f32_e32 v92, 0, v92
	v_cvt_pk_bf16_f32 v100, v106, v103
	v_cvt_pk_bf16_f32 v101, v104, v101
	global_store_dwordx4 v[110:111], v[98:101], off offset:256 nt
	s_nop 0
	v_max_f32_e32 v94, 0, v94
	v_mul_f32_e32 v99, v90, v90
	v_max_f32_e32 v90, v95, v95
	v_mul_f32_e32 v95, v91, v91
	v_max_f32_e32 v91, v96, v96
	v_mul_f32_e32 v96, v92, v92
	v_max_f32_e32 v90, 0, v90
	v_max_f32_e32 v91, 0, v91
	v_max_f32_e32 v92, 0, v97
	v_or_b32_e32 v98, 32, v145
	v_mul_f32_e32 v94, v94, v94
	v_mul_f32_e32 v90, v90, v90
	v_mul_f32_e32 v91, v91, v91
	v_mul_f32_e32 v92, v92, v92
	v_cvt_pk_bf16_f32 v90, v94, v90
	v_cvt_pk_bf16_f32 v91, v91, v92
	v_cvt_pk_bf16_f32 v92, v99, v95
	v_mad_i64_i32 v[94:95], s[20:21], v98, s3, v[122:123]
	s_nop 0
	v_lshl_add_u64 v[94:95], v[94:95], 0, s[14:15]
	v_max_f32_e32 v93, 0, v93
	v_lshl_add_u64 v[94:95], v[94:95], 0, s[22:23]
	s_nop 0
	v_mul_f32_e32 v93, v93, v93
	v_lshl_add_u64 v[94:95], v[94:95], 0, v[16:17]
	v_max_f32_e32 v82, 0, v82
	v_max_f32_e32 v83, 0, v83
	v_cvt_pk_bf16_f32 v93, v96, v93
	global_store_dwordx4 v[94:95], v[90:93], off nt
	v_max_f32_e32 v84, 0, v84
	s_nop 0
	v_mul_f32_e32 v90, v82, v82
	v_max_f32_e32 v82, v87, v87
	v_mul_f32_e32 v87, v83, v83
	v_max_f32_e32 v82, 0, v82
	v_max_f32_e32 v83, 0, v88
	v_mul_f32_e32 v88, v84, v84
	v_max_f32_e32 v86, 0, v86
	v_mul_f32_e32 v82, v82, v82
	v_mul_f32_e32 v83, v83, v83
	v_max_f32_e32 v84, 0, v89
	v_max_f32_e32 v85, 0, v85
	v_mul_f32_e32 v86, v86, v86
	v_mul_f32_e32 v84, v84, v84
	v_mul_f32_e32 v85, v85, v85
	v_cvt_pk_bf16_f32 v82, v86, v82
	v_cvt_pk_bf16_f32 v83, v83, v84
	v_max_f32_e32 v74, 0, v74
	v_max_f32_e32 v75, 0, v75
	v_max_f32_e32 v76, 0, v76
	v_cvt_pk_bf16_f32 v84, v90, v87
	v_cvt_pk_bf16_f32 v85, v88, v85
	global_store_dwordx4 v[94:95], v[82:85], off offset:256 nt
	s_nop 0
	v_max_f32_e32 v78, 0, v78
	v_mul_f32_e32 v83, v74, v74
	v_max_f32_e32 v74, v79, v79
	v_mul_f32_e32 v79, v75, v75
	v_max_f32_e32 v75, v80, v80
	v_mul_f32_e32 v80, v76, v76
	v_max_f32_e32 v74, 0, v74
	v_max_f32_e32 v75, 0, v75
	v_max_f32_e32 v76, 0, v81
	v_or_b32_e32 v82, 48, v145
	v_mul_f32_e32 v78, v78, v78
	v_mul_f32_e32 v74, v74, v74
	v_mul_f32_e32 v75, v75, v75
	v_mul_f32_e32 v76, v76, v76
	v_cvt_pk_bf16_f32 v74, v78, v74
	v_cvt_pk_bf16_f32 v75, v75, v76
	v_cvt_pk_bf16_f32 v76, v83, v79
	v_mad_i64_i32 v[78:79], s[20:21], v82, s3, v[122:123]
	s_nop 0
	v_lshl_add_u64 v[78:79], v[78:79], 0, s[14:15]
	v_max_f32_e32 v77, 0, v77
	v_lshl_add_u64 v[78:79], v[78:79], 0, s[22:23]
	s_nop 0
	v_mul_f32_e32 v77, v77, v77
	v_lshl_add_u64 v[78:79], v[78:79], 0, v[16:17]
	v_max_f32_e32 v66, 0, v66
	v_max_f32_e32 v67, 0, v67
	v_cvt_pk_bf16_f32 v77, v80, v77
	global_store_dwordx4 v[78:79], v[74:77], off nt
	v_max_f32_e32 v68, 0, v68
	s_nop 0
	v_mul_f32_e32 v74, v66, v66
	v_max_f32_e32 v66, v71, v71
	v_mul_f32_e32 v71, v67, v67
	v_max_f32_e32 v66, 0, v66
	v_max_f32_e32 v67, 0, v72
	v_mul_f32_e32 v72, v68, v68
	v_max_f32_e32 v70, 0, v70
	v_mul_f32_e32 v66, v66, v66
	v_mul_f32_e32 v67, v67, v67
	v_max_f32_e32 v68, 0, v73
	v_max_f32_e32 v69, 0, v69
	v_mul_f32_e32 v70, v70, v70
	v_mul_f32_e32 v68, v68, v68
	v_mul_f32_e32 v69, v69, v69
	v_cvt_pk_bf16_f32 v66, v70, v66
	v_cvt_pk_bf16_f32 v67, v67, v68
	v_max_f32_e32 v58, 0, v58
	v_max_f32_e32 v59, 0, v59
	v_max_f32_e32 v60, 0, v60
	v_cvt_pk_bf16_f32 v68, v74, v71
	v_cvt_pk_bf16_f32 v69, v72, v69
	global_store_dwordx4 v[78:79], v[66:69], off offset:256 nt
	s_nop 0
	v_max_f32_e32 v62, 0, v62
	v_mul_f32_e32 v67, v58, v58
	v_max_f32_e32 v58, v63, v63
	v_mul_f32_e32 v63, v59, v59
	v_max_f32_e32 v59, v64, v64
	v_mul_f32_e32 v64, v60, v60
	v_max_f32_e32 v58, 0, v58
	v_max_f32_e32 v59, 0, v59
	v_max_f32_e32 v60, 0, v65
	v_add_u32_e32 v66, 0x80, v145
	v_mul_f32_e32 v62, v62, v62
	v_mul_f32_e32 v58, v58, v58
	v_mul_f32_e32 v59, v59, v59
	v_mul_f32_e32 v60, v60, v60
	v_cvt_pk_bf16_f32 v58, v62, v58
	v_cvt_pk_bf16_f32 v59, v59, v60
	v_cvt_pk_bf16_f32 v60, v67, v63
	v_mad_i64_i32 v[62:63], s[20:21], v66, s3, v[122:123]
	s_nop 0
	v_lshl_add_u64 v[62:63], v[62:63], 0, s[14:15]
	v_max_f32_e32 v61, 0, v61
	v_lshl_add_u64 v[62:63], v[62:63], 0, s[22:23]
	s_nop 0
	v_mul_f32_e32 v61, v61, v61
	v_lshl_add_u64 v[62:63], v[62:63], 0, v[16:17]
	v_max_f32_e32 v50, 0, v50
	v_max_f32_e32 v51, 0, v51
	v_cvt_pk_bf16_f32 v61, v64, v61
	global_store_dwordx4 v[62:63], v[58:61], off nt
	v_max_f32_e32 v52, 0, v52
	s_nop 0
	v_mul_f32_e32 v58, v50, v50
	v_max_f32_e32 v50, v55, v55
	v_mul_f32_e32 v55, v51, v51
	v_max_f32_e32 v50, 0, v50
	v_max_f32_e32 v51, 0, v56
	v_mul_f32_e32 v56, v52, v52
	v_max_f32_e32 v54, 0, v54
	v_mul_f32_e32 v50, v50, v50
	v_mul_f32_e32 v51, v51, v51
; template <class Epi>
; __device__ __forceinline__ void gemm_phase(LAS unsigned char* lds, const Gemm g, const StaticOrder& S, const Epi& E) {
;     ...
;     E(acc, cur, wr, wc, fr, fq);
;     if (!has_next) break;
; #pragma unroll
;     for (int a = 0; a < 2; ++a)
; #pragma unroll
;       for (int b = 0; b < 2; ++b)
; #pragma unroll
;         for (int m = 0; m < 4; ++m)
; #pragma unroll
;           for (int n = 0; n < 2; ++n) acc[a][b][m][n] = (f32x4){0.f, 0.f, 0.f, 0.f};
;     cur = nxt; cA = nA; cB = nB; ++ui;
;   __device__ __forceinline__ void operator()(const f32x4 (&acc)[2][2][4][2], const Unit& u, int wr, int wc, int fr, int fq) const {
; #pragma unroll
;     for (int ai = 0; ai < 2; ++ai)
; #pragma unroll
;       for (int m = 0; m < 4; ++m) {
;         const int r = u.pm * 256 + ai * 128 + wr * 64 + m * 16 + fr;
; #pragma unroll
;         for (int bj = 0; bj < 2; ++bj) {
;           float v[8];
; #pragma unroll
;           for (int e = 0; e < 4; ++e) {
;             const float a = fmaxf(acc[ai][bj][m][0][e], 0.f), b = fmaxf(acc[ai][bj][m][1][e], 0.f);
;             v[e] = a * a; v[4 + e] = b * b;
;           }
;           u32x4 w;
; #pragma unroll
;           for (int e = 0; e < 4; ++e) w[e] = cvt_pk_bf16(v[2 * e], v[2 * e + 1]);
;           *(u32x4*)(H + (size_t)r * LDH + u.pn * 256 + bj * 128 + wc * 32 + 8 * fq) = w;
;         }
	v_max_f32_e32 v52, 0, v57
	v_max_f32_e32 v53, 0, v53
	v_mul_f32_e32 v54, v54, v54
	v_mul_f32_e32 v52, v52, v52
	v_mul_f32_e32 v53, v53, v53
	v_cvt_pk_bf16_f32 v50, v54, v50
	v_cvt_pk_bf16_f32 v51, v51, v52
	v_max_f32_e32 v42, 0, v42
	v_max_f32_e32 v43, 0, v43
	v_max_f32_e32 v44, 0, v44
	v_cvt_pk_bf16_f32 v52, v58, v55
	v_cvt_pk_bf16_f32 v53, v56, v53
	global_store_dwordx4 v[62:63], v[50:53], off offset:256 nt
	s_nop 0
	v_max_f32_e32 v46, 0, v46
	v_mul_f32_e32 v51, v42, v42
	v_max_f32_e32 v42, v47, v47
	v_mul_f32_e32 v47, v43, v43
	v_max_f32_e32 v43, v48, v48
	v_mul_f32_e32 v48, v44, v44
	v_max_f32_e32 v42, 0, v42
	v_max_f32_e32 v43, 0, v43
	v_max_f32_e32 v44, 0, v49
	v_add_u32_e32 v50, 0x90, v145
	v_mul_f32_e32 v46, v46, v46
	v_mul_f32_e32 v42, v42, v42
	v_mul_f32_e32 v43, v43, v43
	v_mul_f32_e32 v44, v44, v44
	v_cvt_pk_bf16_f32 v42, v46, v42
	v_cvt_pk_bf16_f32 v43, v43, v44
	v_cvt_pk_bf16_f32 v44, v51, v47
	v_mad_i64_i32 v[46:47], s[20:21], v50, s3, v[122:123]
	s_nop 0
	v_lshl_add_u64 v[46:47], v[46:47], 0, s[14:15]
	v_max_f32_e32 v45, 0, v45
	v_lshl_add_u64 v[46:47], v[46:47], 0, s[22:23]
	s_nop 0
	v_mul_f32_e32 v45, v45, v45
	v_lshl_add_u64 v[46:47], v[46:47], 0, v[16:17]
	v_max_f32_e32 v34, 0, v34
	v_max_f32_e32 v35, 0, v35
	v_cvt_pk_bf16_f32 v45, v48, v45
	global_store_dwordx4 v[46:47], v[42:45], off nt
	v_max_f32_e32 v36, 0, v36
	s_nop 0
	v_mul_f32_e32 v42, v34, v34
	v_max_f32_e32 v34, v39, v39
	v_mul_f32_e32 v39, v35, v35
	v_max_f32_e32 v34, 0, v34
	v_max_f32_e32 v35, 0, v40
	v_mul_f32_e32 v40, v36, v36
	v_max_f32_e32 v38, 0, v38
	v_mul_f32_e32 v34, v34, v34
	v_mul_f32_e32 v35, v35, v35
	v_max_f32_e32 v36, 0, v41
	v_max_f32_e32 v37, 0, v37
	v_mul_f32_e32 v38, v38, v38
	v_mul_f32_e32 v36, v36, v36
	v_mul_f32_e32 v37, v37, v37
	v_cvt_pk_bf16_f32 v34, v38, v34
	v_cvt_pk_bf16_f32 v35, v35, v36
	v_max_f32_e32 v26, 0, v26
	v_max_f32_e32 v27, 0, v27
	v_max_f32_e32 v28, 0, v28
	v_cvt_pk_bf16_f32 v36, v42, v39
	v_cvt_pk_bf16_f32 v37, v40, v37
	global_store_dwordx4 v[46:47], v[34:37], off offset:256 nt
	s_nop 0
	v_max_f32_e32 v30, 0, v30
	v_mul_f32_e32 v35, v26, v26
	v_max_f32_e32 v26, v31, v31
	v_mul_f32_e32 v31, v27, v27
	v_max_f32_e32 v27, v32, v32
	v_mul_f32_e32 v32, v28, v28
	v_max_f32_e32 v26, 0, v26
	v_max_f32_e32 v27, 0, v27
	v_max_f32_e32 v28, 0, v33
	v_add_u32_e32 v34, 0xa0, v145
	v_mul_f32_e32 v30, v30, v30
	v_mul_f32_e32 v26, v26, v26
	v_mul_f32_e32 v27, v27, v27
	v_mul_f32_e32 v28, v28, v28
	v_cvt_pk_bf16_f32 v26, v30, v26
	v_cvt_pk_bf16_f32 v27, v27, v28
	v_cvt_pk_bf16_f32 v28, v35, v31
	v_mad_i64_i32 v[30:31], s[20:21], v34, s3, v[122:123]
	s_nop 0
	v_lshl_add_u64 v[30:31], v[30:31], 0, s[14:15]
	v_max_f32_e32 v29, 0, v29
	v_lshl_add_u64 v[30:31], v[30:31], 0, s[22:23]
	s_nop 0
	v_mul_f32_e32 v29, v29, v29
	v_lshl_add_u64 v[30:31], v[30:31], 0, v[16:17]
	v_max_f32_e32 v18, 0, v18
	v_max_f32_e32 v19, 0, v19
	v_cvt_pk_bf16_f32 v29, v32, v29
	global_store_dwordx4 v[30:31], v[26:29], off nt
	v_max_f32_e32 v20, 0, v20
	s_nop 0
	v_mul_f32_e32 v26, v18, v18
	v_max_f32_e32 v18, v23, v23
	v_mul_f32_e32 v23, v19, v19
	v_max_f32_e32 v18, 0, v18
	v_max_f32_e32 v19, 0, v24
	v_mul_f32_e32 v24, v20, v20
	v_max_f32_e32 v22, 0, v22
	v_mul_f32_e32 v18, v18, v18
	v_mul_f32_e32 v19, v19, v19
	v_max_f32_e32 v20, 0, v25
	v_max_f32_e32 v21, 0, v21
	v_mul_f32_e32 v22, v22, v22
	v_mul_f32_e32 v20, v20, v20
	v_mul_f32_e32 v21, v21, v21
	v_cvt_pk_bf16_f32 v18, v22, v18
	v_cvt_pk_bf16_f32 v19, v19, v20
	v_max_f32_e32 v8, 0, v8
	v_max_f32_e32 v9, 0, v9
	v_max_f32_e32 v10, 0, v10
	v_cvt_pk_bf16_f32 v20, v26, v23
	v_cvt_pk_bf16_f32 v21, v24, v21
	global_store_dwordx4 v[30:31], v[18:21], off offset:256 nt
	s_nop 0
	v_max_f32_e32 v12, 0, v12
	v_mul_f32_e32 v19, v8, v8
	v_max_f32_e32 v8, v13, v13
	v_mul_f32_e32 v13, v9, v9
	v_max_f32_e32 v9, v14, v14
	v_mul_f32_e32 v14, v10, v10
	v_max_f32_e32 v8, 0, v8
	v_max_f32_e32 v9, 0, v9
	v_max_f32_e32 v10, 0, v15
	v_add_u32_e32 v18, 0xb0, v145
	v_mul_f32_e32 v12, v12, v12
	v_mul_f32_e32 v8, v8, v8
	v_mul_f32_e32 v9, v9, v9
	v_mul_f32_e32 v10, v10, v10
	v_cvt_pk_bf16_f32 v8, v12, v8
	v_cvt_pk_bf16_f32 v9, v9, v10
	v_cvt_pk_bf16_f32 v10, v19, v13
	v_mad_i64_i32 v[12:13], s[20:21], v18, s3, v[122:123]
	s_nop 0
	v_lshl_add_u64 v[12:13], v[12:13], 0, s[14:15]
	v_max_f32_e32 v11, 0, v11
	v_lshl_add_u64 v[12:13], v[12:13], 0, s[22:23]
	s_nop 0
	v_mul_f32_e32 v11, v11, v11
	v_lshl_add_u64 v[12:13], v[12:13], 0, v[16:17]
	v_max_f32_e32 v0, 0, v0
	v_max_f32_e32 v1, 0, v1
	v_max_f32_e32 v2, 0, v2
	v_cvt_pk_bf16_f32 v11, v14, v11
	global_store_dwordx4 v[12:13], v[8:11], off nt
	s_nop 0
	s_nop 0
	v_mul_f32_e32 v8, v0, v0
	v_max_f32_e32 v0, v5, v5
	v_mul_f32_e32 v5, v1, v1
	v_max_f32_e32 v1, v6, v6
	v_mul_f32_e32 v6, v2, v2
	v_max_f32_e32 v0, 0, v0
	v_max_f32_e32 v1, 0, v1
	v_max_f32_e32 v2, 0, v7
	v_max_f32_e32 v3, 0, v3
	v_max_f32_e32 v4, 0, v4
	v_mul_f32_e32 v0, v0, v0
	v_mul_f32_e32 v1, v1, v1
	v_mul_f32_e32 v2, v2, v2
	v_mul_f32_e32 v3, v3, v3
	s_and_b64 vcc, exec, s[6:7]
	s_mov_b32 s39, s2
	s_mov_b32 s40, s4
	s_mov_b64 s[20:21], s[12:13]
	s_mov_b64 s[14:15], s[10:11]
	v_mul_f32_e32 v4, v4, v4
	v_cvt_pk_bf16_f32 v0, v4, v0
	v_cvt_pk_bf16_f32 v1, v1, v2
	v_cvt_pk_bf16_f32 v2, v8, v5
	v_cvt_pk_bf16_f32 v3, v6, v3
	global_store_dwordx4 v[12:13], v[0:3], off offset:256 nt
	s_cbranch_vccz .LBB0_3794
	s_branch .LBB0_3806
